# bf16 weight stores of the conversion passes also marked nt
# baseline (speedup 1.0000x reference)
; #define LAS __attribute__((address_space(3)))
; #define LDS_WAIT() asm volatile("s_waitcnt lgkmcnt(0)" ::: "memory")
; __device__ __forceinline__ unsigned cvt_pk_bf16(float lo, float hi) { unsigned r; asm volatile("v_cvt_pk_bf16_f32 %0, %1, %2" : "=v"(r) : "v"(lo), "v"(hi)); return r; }
;     ...
; #pragma unroll
;     for (int i = 0; i < 8; ++i)
; #pragma unroll
;         for (int e = 0; e < 4; ++e) *(LAS unsigned*)(scr + (4 * r16 + e) * 128 + ((i ^ (r16 & 7)) * 16) + q * 4) = cvt_pk_bf16(v[2 * i][e], v[2 * i + 1][e]);
;     LDS_WAIT(); asm volatile("" ::: "memory");
;     const int c = lane & 7;
; #pragma unroll
;     for (int j = 0; j < 8; ++j) { const int row = (lane >> 3) + 8 * j; const u32x4 o = *(const LAS u32x4*)(scr + row * 128 + ((c ^ ((row >> 2) & 7)) * 16));
;         const int lc = col_off + n0 + row; int dr;
;         if (MODE == 0) dr = lc;
;         else if (MODE == 1) dr = (lc & ~255) + 128 * ((lc >> 5) & 1) + 32 * ((lc >> 6) & 3) + (lc & 31);
;         else if (MODE == 2) dr = 256 * (lc >> 7) + (lc & 127);
;         else dr = 256 * (lc >> 7) + 128 + (lc & 127);
;         *(u32x4*)(WT + (size_t)dr * (ldt ? ldt : K) + k0 + 8 * c) = o; }
;     LDS_WAIT(); asm volatile("" ::: "memory");
.LBB0_9:
	s_waitcnt vmcnt(14)
	v_cvt_pk_bf16_f32 v58, v58, v62
	v_add_u32_e32 v62, v73, v75
	ds_write_b32 v62, v58
	v_cvt_pk_bf16_f32 v58, v59, v63
	ds_write_b32 v62, v58 offset:128
	v_cvt_pk_bf16_f32 v58, v60, v64
	ds_write_b32 v62, v58 offset:256
	v_cvt_pk_bf16_f32 v58, v61, v65
	ds_write_b32 v62, v58 offset:384
	s_waitcnt vmcnt(12)
	v_cvt_pk_bf16_f32 v50, v50, v54
	v_add_u32_e32 v54, v76, v75
	ds_write_b32 v54, v50
	v_cvt_pk_bf16_f32 v50, v51, v55
	ds_write_b32 v54, v50 offset:128
	v_cvt_pk_bf16_f32 v50, v52, v56
	ds_write_b32 v54, v50 offset:256
	v_cvt_pk_bf16_f32 v50, v53, v57
	ds_write_b32 v54, v50 offset:384
	s_waitcnt vmcnt(10)
	v_cvt_pk_bf16_f32 v42, v42, v46
	v_add_u32_e32 v46, v77, v75
	ds_write_b32 v46, v42
	v_cvt_pk_bf16_f32 v42, v43, v47
	ds_write_b32 v46, v42 offset:128
	v_cvt_pk_bf16_f32 v42, v44, v48
	ds_write_b32 v46, v42 offset:256
	v_cvt_pk_bf16_f32 v42, v45, v49
	ds_write_b32 v46, v42 offset:384
	s_waitcnt vmcnt(8)
	v_cvt_pk_bf16_f32 v26, v26, v38
	v_add_u32_e32 v38, v78, v75
	ds_write_b32 v38, v26
	v_cvt_pk_bf16_f32 v26, v27, v39
	ds_write_b32 v38, v26 offset:128
	v_cvt_pk_bf16_f32 v26, v28, v40
	ds_write_b32 v38, v26 offset:256
	v_cvt_pk_bf16_f32 v26, v29, v41
	ds_write_b32 v38, v26 offset:384
	s_waitcnt vmcnt(6)
	v_cvt_pk_bf16_f32 v18, v18, v34
	v_add_u32_e32 v26, v79, v75
	ds_write_b32 v26, v18
	v_cvt_pk_bf16_f32 v18, v19, v35
	ds_write_b32 v26, v18 offset:128
	v_cvt_pk_bf16_f32 v18, v20, v36
	ds_write_b32 v26, v18 offset:256
	v_cvt_pk_bf16_f32 v18, v21, v37
	ds_write_b32 v26, v18 offset:384
	s_waitcnt vmcnt(4)
	v_cvt_pk_bf16_f32 v14, v14, v30
	v_add_u32_e32 v18, v80, v75
	ds_write_b32 v18, v14
	v_cvt_pk_bf16_f32 v14, v15, v31
	ds_write_b32 v18, v14 offset:128
	v_cvt_pk_bf16_f32 v14, v16, v32
	ds_write_b32 v18, v14 offset:256
	v_cvt_pk_bf16_f32 v14, v17, v33
	ds_write_b32 v18, v14 offset:384
	s_waitcnt vmcnt(2)
	v_cvt_pk_bf16_f32 v6, v6, v22
	v_add_u32_e32 v14, v81, v75
	ds_write_b32 v14, v6
	v_cvt_pk_bf16_f32 v6, v7, v23
	ds_write_b32 v14, v6 offset:128
	v_cvt_pk_bf16_f32 v6, v8, v24
	ds_write_b32 v14, v6 offset:256
	v_cvt_pk_bf16_f32 v6, v9, v25
	ds_write_b32 v14, v6 offset:384
	s_waitcnt vmcnt(0)
	v_cvt_pk_bf16_f32 v2, v2, v10
	v_add_u32_e32 v6, v82, v75
	ds_write_b32 v6, v2
	v_cvt_pk_bf16_f32 v2, v3, v11
	ds_write_b32 v6, v2 offset:128
	v_cvt_pk_bf16_f32 v2, v4, v12
	s_lshl_b64 s[10:11], s[12:13], 1
	ds_write_b32 v6, v2 offset:256
	v_cvt_pk_bf16_f32 v2, v5, v13
	ds_write_b32 v6, v2 offset:384
	s_add_u32 s10, s47, s10
	s_waitcnt lgkmcnt(0)
	s_addc_u32 s11, s48, s11
	s_lshr_b32 s1, s0, 1
	v_lshlrev_b32_e32 v2, 1, v72
	v_mov_b32_e32 v3, v71
	v_add_u32_e32 v8, v84, v85
	s_and_b32 s1, s1, 0x60
	s_and_b32 s2, s0, 0xffffff00
	v_lshl_add_u64 v[14:15], s[10:11], 0, v[2:3]
	ds_read_b128 v[2:5], v8
	s_or_b32 s2, s1, s2
	v_or_b32_e32 v16, s2, v83
	v_ashrrev_i32_e32 v17, 31, v16
	v_lshlrev_b64 v[6:7], 13, v[16:17]
	v_lshl_add_u64 v[10:11], v[14:15], 0, v[6:7]
	s_waitcnt lgkmcnt(0)
	global_store_dwordx4 v[10:11], v[2:5], off nt
	ds_read_b128 v[6:9], v8 offset:4096
	v_or_b32_e32 v10, s2, v86
	v_add_u32_e32 v2, v87, v88
	ds_read_b128 v[2:5], v2
	v_ashrrev_i32_e32 v11, 31, v10
	v_lshlrev_b64 v[10:11], 13, v[10:11]
	v_lshl_add_u64 v[18:19], v[14:15], 0, v[10:11]
	v_add_u32_e32 v10, v90, v91
	ds_read_b128 v[10:13], v10
	s_waitcnt lgkmcnt(1)
	global_store_dwordx4 v[18:19], v[2:5], off nt
	s_nop 1
	v_or_b32_e32 v2, s2, v89
	v_ashrrev_i32_e32 v3, 31, v2
	v_lshlrev_b64 v[2:3], 13, v[2:3]
	v_lshl_add_u64 v[2:3], v[14:15], 0, v[2:3]
	s_waitcnt lgkmcnt(0)
	global_store_dwordx4 v[2:3], v[10:13], off nt
	v_add_u32_e32 v2, v93, v94
	ds_read_b128 v[2:5], v2
	v_or_b32_e32 v10, s2, v92
	v_ashrrev_i32_e32 v11, 31, v10
	v_lshlrev_b64 v[10:11], 13, v[10:11]
	v_lshl_add_u64 v[18:19], v[14:15], 0, v[10:11]
	v_add_u32_e32 v10, v98, v99
	ds_read_b128 v[10:13], v10
	s_waitcnt lgkmcnt(1)
	global_store_dwordx4 v[18:19], v[2:5], off nt
	s_nop 1
	v_or_b32_e32 v2, 0x80, v16
	v_ashrrev_i32_e32 v3, 31, v2
	v_lshlrev_b64 v[2:3], 13, v[2:3]
	v_lshl_add_u64 v[2:3], v[14:15], 0, v[2:3]
	global_store_dwordx4 v[2:3], v[6:9], off nt
	v_bitop3_b32 v2, s0, v111, v97 bitop3:0xc8
	v_or_b32_e32 v2, s1, v2
	v_or_b32_e32 v2, 0x80, v2
	v_ashrrev_i32_e32 v3, 31, v2
	v_lshlrev_b64 v[2:3], 13, v[2:3]
	v_lshl_add_u64 v[2:3], v[14:15], 0, v[2:3]
	s_waitcnt lgkmcnt(0)
	global_store_dwordx4 v[2:3], v[10:13], off nt
	v_add_u32_e32 v2, v101, v102
	v_bitop3_b32 v6, s0, v112, v100 bitop3:0xc8
	ds_read_b128 v[2:5], v2
	v_or_b32_e32 v6, s1, v6
	v_or_b32_e32 v6, 0x80, v6
	v_ashrrev_i32_e32 v7, 31, v6
	v_lshlrev_b64 v[6:7], 13, v[6:7]
	v_lshl_add_u64 v[10:11], v[14:15], 0, v[6:7]
	v_add_u32_e32 v6, v104, v105
	ds_read_b128 v[6:9], v6
	s_waitcnt lgkmcnt(1)
	global_store_dwordx4 v[10:11], v[2:5], off nt
	s_nop 1
	v_bitop3_b32 v2, s0, v113, v103 bitop3:0xc8
	v_or_b32_e32 v2, s1, v2
	v_or_b32_e32 v2, 0x80, v2
	v_ashrrev_i32_e32 v3, 31, v2
	v_lshlrev_b64 v[2:3], 13, v[2:3]
	v_lshl_add_u64 v[2:3], v[14:15], 0, v[2:3]
	s_waitcnt lgkmcnt(0)
	global_store_dwordx4 v[2:3], v[6:9], off nt
	s_waitcnt lgkmcnt(0)

; #define LAS __attribute__((address_space(3)))
; #define LDS_WAIT() asm volatile("s_waitcnt lgkmcnt(0)" ::: "memory")
; __device__ __forceinline__ unsigned cvt_pk_bf16(float lo, float hi) { unsigned r; asm volatile("v_cvt_pk_bf16_f32 %0, %1, %2" : "=v"(r) : "v"(lo), "v"(hi)); return r; }
;     ...
; #pragma unroll
;     for (int i = 0; i < 8; ++i)
; #pragma unroll
;         for (int e = 0; e < 4; ++e) *(LAS unsigned*)(scr + (4 * r16 + e) * 128 + ((i ^ (r16 & 7)) * 16) + q * 4) = cvt_pk_bf16(v[2 * i][e], v[2 * i + 1][e]);
;     LDS_WAIT(); asm volatile("" ::: "memory");
;     const int c = lane & 7;
; #pragma unroll
;     for (int j = 0; j < 8; ++j) { const int row = (lane >> 3) + 8 * j; const u32x4 o = *(const LAS u32x4*)(scr + row * 128 + ((c ^ ((row >> 2) & 7)) * 16));
;         const int lc = col_off + n0 + row; int dr;
;         if (MODE == 0) dr = lc;
;         else if (MODE == 1) dr = (lc & ~255) + 128 * ((lc >> 5) & 1) + 32 * ((lc >> 6) & 3) + (lc & 31);
;         else if (MODE == 2) dr = 256 * (lc >> 7) + (lc & 127);
;         else dr = 256 * (lc >> 7) + 128 + (lc & 127);
;         *(u32x4*)(WT + (size_t)dr * (ldt ? ldt : K) + k0 + 8 * c) = o; }
;     LDS_WAIT(); asm volatile("" ::: "memory");
; __device__ __forceinline__ void weights_pass(const Args& a, LAS unsigned char* scr, int gw, int NGW, int lane, int pass) {
;     ...
;         if (r < I_QM) { transpose_item<1>(a.in[I_WVM] + (size_t)l * DM * MW, DM, MW, (bf16_t*)(ws + WS_WKV) + (size_t)l * 1024 * DM, a.in[I_GMEM] + l * DM, nullptr, 512, scr, r, lane); continue; } r -= I_QM;
.LBB0_19:
	s_waitcnt vmcnt(14)
	v_cvt_pk_bf16_f32 v58, v58, v62
	v_add_u32_e32 v62, v73, v75
	ds_write_b32 v62, v58
	v_cvt_pk_bf16_f32 v58, v59, v63
	ds_write_b32 v62, v58 offset:128
	v_cvt_pk_bf16_f32 v58, v60, v64
	ds_write_b32 v62, v58 offset:256
	v_cvt_pk_bf16_f32 v58, v61, v65
	ds_write_b32 v62, v58 offset:384
	s_waitcnt vmcnt(12)
	v_cvt_pk_bf16_f32 v50, v50, v54
	v_add_u32_e32 v54, v76, v75
	ds_write_b32 v54, v50
	v_cvt_pk_bf16_f32 v50, v51, v55
	ds_write_b32 v54, v50 offset:128
	v_cvt_pk_bf16_f32 v50, v52, v56
	ds_write_b32 v54, v50 offset:256
	v_cvt_pk_bf16_f32 v50, v53, v57
	ds_write_b32 v54, v50 offset:384
	s_waitcnt vmcnt(10)
	v_cvt_pk_bf16_f32 v42, v42, v46
	v_add_u32_e32 v46, v77, v75
	ds_write_b32 v46, v42
	v_cvt_pk_bf16_f32 v42, v43, v47
	ds_write_b32 v46, v42 offset:128
	v_cvt_pk_bf16_f32 v42, v44, v48
	ds_write_b32 v46, v42 offset:256
	v_cvt_pk_bf16_f32 v42, v45, v49
	ds_write_b32 v46, v42 offset:384
	s_waitcnt vmcnt(8)
	v_cvt_pk_bf16_f32 v34, v34, v38
	v_add_u32_e32 v38, v78, v75
	ds_write_b32 v38, v34
	v_cvt_pk_bf16_f32 v34, v35, v39
	ds_write_b32 v38, v34 offset:128
	v_cvt_pk_bf16_f32 v34, v36, v40
	ds_write_b32 v38, v34 offset:256
	v_cvt_pk_bf16_f32 v34, v37, v41
	ds_write_b32 v38, v34 offset:384
	s_waitcnt vmcnt(6)
	v_cvt_pk_bf16_f32 v26, v26, v30
	v_add_u32_e32 v30, v79, v75
	ds_write_b32 v30, v26
	v_cvt_pk_bf16_f32 v26, v27, v31
	ds_write_b32 v30, v26 offset:128
	v_cvt_pk_bf16_f32 v26, v28, v32
	ds_write_b32 v30, v26 offset:256
	v_cvt_pk_bf16_f32 v26, v29, v33
	ds_write_b32 v30, v26 offset:384
	s_waitcnt vmcnt(4)
	v_cvt_pk_bf16_f32 v18, v18, v22
	v_add_u32_e32 v22, v80, v75
	ds_write_b32 v22, v18
	v_cvt_pk_bf16_f32 v18, v19, v23
	ds_write_b32 v22, v18 offset:128
	v_cvt_pk_bf16_f32 v18, v20, v24
	ds_write_b32 v22, v18 offset:256
	v_cvt_pk_bf16_f32 v18, v21, v25
	ds_write_b32 v22, v18 offset:384
	s_waitcnt vmcnt(2)
	v_cvt_pk_bf16_f32 v10, v10, v14
	v_add_u32_e32 v14, v81, v75
	ds_write_b32 v14, v10
	v_cvt_pk_bf16_f32 v10, v11, v15
	ds_write_b32 v14, v10 offset:128
	v_cvt_pk_bf16_f32 v10, v12, v16
	ds_write_b32 v14, v10 offset:256
	v_cvt_pk_bf16_f32 v10, v13, v17
	ds_write_b32 v14, v10 offset:384
	s_waitcnt vmcnt(0)
	v_cvt_pk_bf16_f32 v2, v2, v6
	v_add_u32_e32 v6, v82, v75
	ds_write_b32 v6, v2
	v_cvt_pk_bf16_f32 v2, v3, v7
	ds_write_b32 v6, v2 offset:128
	v_cvt_pk_bf16_f32 v2, v4, v8
	ds_write_b32 v6, v2 offset:256
	v_cvt_pk_bf16_f32 v2, v5, v9
	ds_write_b32 v6, v2 offset:384
	s_or_b32 s8, s54, 0x200
	s_lshl_b32 s14, s55, 1
	s_waitcnt lgkmcnt(0)
	s_add_u32 s14, s52, s14
	s_addc_u32 s15, s53, 0
	v_lshlrev_b32_e32 v2, 1, v72
	v_mov_b32_e32 v3, v71
	v_add_u32_e32 v8, v84, v85
	v_lshl_add_u64 v[14:15], s[14:15], 0, v[2:3]
	ds_read_b128 v[2:5], v8
	s_and_b32 s14, s37, 0x60
	s_and_b32 s15, s8, 0x300
	s_or_b32 s15, s15, s14
	v_or_b32_e32 v6, s15, v83
	v_or_b32_e32 v10, s15, v86
	v_lshlrev_b32_e32 v6, 13, v6
	v_mov_b32_e32 v7, v71
	v_lshlrev_b32_e32 v10, 13, v10
	v_mov_b32_e32 v11, v71
	v_lshl_add_u64 v[16:17], v[14:15], 0, v[6:7]
	v_lshl_add_u64 v[18:19], v[14:15], 0, v[10:11]
	v_add_u32_e32 v10, v90, v91
	ds_read_b128 v[10:13], v10
	s_waitcnt lgkmcnt(1)
	global_store_dwordx4 v[16:17], v[2:5], off nt
	ds_read_b128 v[6:9], v8 offset:4096
	s_nop 0
	v_add_u32_e32 v2, v87, v88
	ds_read_b128 v[2:5], v2
	s_waitcnt lgkmcnt(0)
	global_store_dwordx4 v[18:19], v[2:5], off nt
	s_nop 1
	v_or_b32_e32 v2, s15, v89
	v_lshlrev_b32_e32 v2, 13, v2
	v_mov_b32_e32 v3, v71
	v_lshl_add_u64 v[2:3], v[14:15], 0, v[2:3]
	global_store_dwordx4 v[2:3], v[10:13], off nt
	v_add_u32_e32 v2, v93, v94
	ds_read_b128 v[2:5], v2
	v_or_b32_e32 v10, s15, v92
	v_lshlrev_b32_e32 v10, 13, v10
	v_mov_b32_e32 v11, v71
	v_lshl_add_u64 v[18:19], v[14:15], 0, v[10:11]
	v_add_u32_e32 v10, v98, v99
	ds_read_b128 v[10:13], v10
	s_waitcnt lgkmcnt(1)
	global_store_dwordx4 v[18:19], v[2:5], off nt
	s_nop 1
	v_add_co_u32_e32 v2, vcc, s44, v16
	s_nop 1
	v_addc_co_u32_e32 v3, vcc, 0, v17, vcc
	global_store_dwordx4 v[2:3], v[6:9], off nt
	v_bitop3_b32 v2, s8, v108, v97 bitop3:0xc8
	v_or_b32_e32 v2, s14, v2
	v_lshlrev_b32_e32 v2, 13, v2
	v_mov_b32_e32 v3, v71
	v_lshl_add_u64 v[2:3], v[14:15], 0, v[2:3]
	v_add_co_u32_e32 v2, vcc, s44, v2
	v_bitop3_b32 v6, s8, v109, v100 bitop3:0xc8
	s_nop 0
	v_addc_co_u32_e32 v3, vcc, 0, v3, vcc
	s_waitcnt lgkmcnt(0)
	global_store_dwordx4 v[2:3], v[10:13], off nt
	v_add_u32_e32 v2, v101, v102
	ds_read_b128 v[2:5], v2
	v_or_b32_e32 v6, s14, v6
	v_lshlrev_b32_e32 v6, 13, v6
	v_mov_b32_e32 v7, v71
	v_lshl_add_u64 v[6:7], v[14:15], 0, v[6:7]
	v_add_co_u32_e32 v10, vcc, s44, v6
	v_add_u32_e32 v6, v104, v105
	s_nop 0
	v_addc_co_u32_e32 v11, vcc, 0, v7, vcc
	ds_read_b128 v[6:9], v6
	s_waitcnt lgkmcnt(1)
	global_store_dwordx4 v[10:11], v[2:5], off nt
	s_nop 1
	v_bitop3_b32 v2, s8, v110, v103 bitop3:0xc8
	v_or_b32_e32 v2, s14, v2
	v_lshlrev_b32_e32 v2, 13, v2
	v_mov_b32_e32 v3, v71
	v_lshl_add_u64 v[2:3], v[14:15], 0, v[2:3]
	v_add_co_u32_e32 v2, vcc, 0x100000, v2
	s_mov_b64 s[14:15], 0
	s_nop 0
	v_addc_co_u32_e32 v3, vcc, 0, v3, vcc
	s_waitcnt lgkmcnt(0)
	global_store_dwordx4 v[2:3], v[6:9], off nt
	s_waitcnt lgkmcnt(0)

; #define LAS __attribute__((address_space(3)))
; #define LDS_WAIT() asm volatile("s_waitcnt lgkmcnt(0)" ::: "memory")
; __device__ __forceinline__ unsigned cvt_pk_bf16(float lo, float hi) { unsigned r; asm volatile("v_cvt_pk_bf16_f32 %0, %1, %2" : "=v"(r) : "v"(lo), "v"(hi)); return r; }
;     ...
; #pragma unroll
;     for (int i = 0; i < 8; ++i)
; #pragma unroll
;         for (int e = 0; e < 4; ++e) *(LAS unsigned*)(scr + (4 * r16 + e) * 128 + ((i ^ (r16 & 7)) * 16) + q * 4) = cvt_pk_bf16(v[2 * i][e], v[2 * i + 1][e]);
;     LDS_WAIT(); asm volatile("" ::: "memory");
;     const int c = lane & 7;
; #pragma unroll
;     for (int j = 0; j < 8; ++j) { const int row = (lane >> 3) + 8 * j; const u32x4 o = *(const LAS u32x4*)(scr + row * 128 + ((c ^ ((row >> 2) & 7)) * 16));
;         const int lc = col_off + n0 + row; int dr;
;         if (MODE == 0) dr = lc;
;         else if (MODE == 1) dr = (lc & ~255) + 128 * ((lc >> 5) & 1) + 32 * ((lc >> 6) & 3) + (lc & 31);
;         else if (MODE == 2) dr = 256 * (lc >> 7) + (lc & 127);
;         else dr = 256 * (lc >> 7) + 128 + (lc & 127);
;         *(u32x4*)(WT + (size_t)dr * (ldt ? ldt : K) + k0 + 8 * c) = o; }
;     LDS_WAIT(); asm volatile("" ::: "memory");
; __device__ __forceinline__ void weights_pass(const Args& a, LAS unsigned char* scr, int gw, int NGW, int lane, int pass) {
;     ...
;         if (r < I_QM) { transpose_item<1>(a.in[I_WKM] + (size_t)l * DM * MW, DM, MW, (bf16_t*)(ws + WS_WKV) + (size_t)l * 1024 * DM, a.in[I_GMEM] + l * DM, nullptr, 0, scr, r, lane); continue; } r -= I_QM;
.LBB0_23:
	s_waitcnt vmcnt(14)
	v_cvt_pk_bf16_f32 v58, v58, v62
	v_add_u32_e32 v62, v73, v75
	ds_write_b32 v62, v58
	v_cvt_pk_bf16_f32 v58, v59, v63
	ds_write_b32 v62, v58 offset:128
	v_cvt_pk_bf16_f32 v58, v60, v64
	ds_write_b32 v62, v58 offset:256
	v_cvt_pk_bf16_f32 v58, v61, v65
	ds_write_b32 v62, v58 offset:384
	s_waitcnt vmcnt(12)
	v_cvt_pk_bf16_f32 v50, v50, v54
	v_add_u32_e32 v54, v76, v75
	ds_write_b32 v54, v50
	v_cvt_pk_bf16_f32 v50, v51, v55
	ds_write_b32 v54, v50 offset:128
	v_cvt_pk_bf16_f32 v50, v52, v56
	ds_write_b32 v54, v50 offset:256
	v_cvt_pk_bf16_f32 v50, v53, v57
	ds_write_b32 v54, v50 offset:384
	s_waitcnt vmcnt(10)
	v_cvt_pk_bf16_f32 v42, v42, v46
	v_add_u32_e32 v46, v77, v75
	ds_write_b32 v46, v42
	v_cvt_pk_bf16_f32 v42, v43, v47
	ds_write_b32 v46, v42 offset:128
	v_cvt_pk_bf16_f32 v42, v44, v48
	ds_write_b32 v46, v42 offset:256
	v_cvt_pk_bf16_f32 v42, v45, v49
	ds_write_b32 v46, v42 offset:384
	s_waitcnt vmcnt(8)
	v_cvt_pk_bf16_f32 v34, v34, v38
	v_add_u32_e32 v38, v78, v75
	ds_write_b32 v38, v34
	v_cvt_pk_bf16_f32 v34, v35, v39
	ds_write_b32 v38, v34 offset:128
	v_cvt_pk_bf16_f32 v34, v36, v40
	ds_write_b32 v38, v34 offset:256
	v_cvt_pk_bf16_f32 v34, v37, v41
	ds_write_b32 v38, v34 offset:384
	s_waitcnt vmcnt(6)
	v_cvt_pk_bf16_f32 v26, v26, v30
	v_add_u32_e32 v30, v79, v75
	ds_write_b32 v30, v26
	v_cvt_pk_bf16_f32 v26, v27, v31
	ds_write_b32 v30, v26 offset:128
	v_cvt_pk_bf16_f32 v26, v28, v32
	ds_write_b32 v30, v26 offset:256
	v_cvt_pk_bf16_f32 v26, v29, v33
	ds_write_b32 v30, v26 offset:384
	s_waitcnt vmcnt(4)
	v_cvt_pk_bf16_f32 v18, v18, v22
	v_add_u32_e32 v22, v80, v75
	ds_write_b32 v22, v18
	v_cvt_pk_bf16_f32 v18, v19, v23
	ds_write_b32 v22, v18 offset:128
	v_cvt_pk_bf16_f32 v18, v20, v24
	ds_write_b32 v22, v18 offset:256
	v_cvt_pk_bf16_f32 v18, v21, v25
	ds_write_b32 v22, v18 offset:384
	s_waitcnt vmcnt(2)
	v_cvt_pk_bf16_f32 v10, v10, v14
	v_add_u32_e32 v14, v81, v75
	ds_write_b32 v14, v10
	v_cvt_pk_bf16_f32 v10, v11, v15
	ds_write_b32 v14, v10 offset:128
	v_cvt_pk_bf16_f32 v10, v12, v16
	ds_write_b32 v14, v10 offset:256
	v_cvt_pk_bf16_f32 v10, v13, v17
	ds_write_b32 v14, v10 offset:384
	s_waitcnt vmcnt(0)
	v_cvt_pk_bf16_f32 v2, v2, v6
	v_add_u32_e32 v6, v82, v75
	ds_write_b32 v6, v2
	v_cvt_pk_bf16_f32 v2, v3, v7
	ds_write_b32 v6, v2 offset:128
	v_cvt_pk_bf16_f32 v2, v4, v8
	ds_write_b32 v6, v2 offset:256
	v_cvt_pk_bf16_f32 v2, v5, v9
	ds_write_b32 v6, v2 offset:384
	s_lshl_b32 s0, s14, 1
	s_waitcnt lgkmcnt(0)
	s_add_u32 s0, s52, s0
	s_addc_u32 s1, s53, 0
	v_lshlrev_b32_e32 v2, 1, v72
	v_mov_b32_e32 v3, v71
	v_add_u32_e32 v8, v84, v85
	v_lshl_add_u64 v[14:15], s[0:1], 0, v[2:3]
	ds_read_b128 v[2:5], v8
	s_and_b32 s0, s37, 0x60
	s_and_b32 s1, s2, 0x100
	s_or_b32 s1, s1, s0
	v_or_b32_e32 v6, s1, v83
	v_or_b32_e32 v10, s1, v86
	v_lshlrev_b32_e32 v6, 13, v6
	v_mov_b32_e32 v7, v71
	v_lshlrev_b32_e32 v10, 13, v10
	v_mov_b32_e32 v11, v71
	v_lshl_add_u64 v[16:17], v[14:15], 0, v[6:7]
	v_lshl_add_u64 v[18:19], v[14:15], 0, v[10:11]
	v_add_u32_e32 v10, v90, v91
	ds_read_b128 v[10:13], v10
	s_waitcnt lgkmcnt(1)
	global_store_dwordx4 v[16:17], v[2:5], off nt
	ds_read_b128 v[6:9], v8 offset:4096
	s_nop 0
	v_add_u32_e32 v2, v87, v88
	ds_read_b128 v[2:5], v2
	s_waitcnt lgkmcnt(0)
	global_store_dwordx4 v[18:19], v[2:5], off nt
	s_nop 1
	v_or_b32_e32 v2, s1, v89
	v_lshlrev_b32_e32 v2, 13, v2
	v_mov_b32_e32 v3, v71
	v_lshl_add_u64 v[2:3], v[14:15], 0, v[2:3]
	global_store_dwordx4 v[2:3], v[10:13], off nt
	v_add_u32_e32 v2, v93, v94
	ds_read_b128 v[2:5], v2
	v_or_b32_e32 v10, s1, v92
	v_lshlrev_b32_e32 v10, 13, v10
	v_mov_b32_e32 v11, v71
	v_lshl_add_u64 v[18:19], v[14:15], 0, v[10:11]
	v_add_u32_e32 v10, v98, v99
	ds_read_b128 v[10:13], v10
	s_waitcnt lgkmcnt(1)
	global_store_dwordx4 v[18:19], v[2:5], off nt
	s_nop 1
	v_add_co_u32_e32 v2, vcc, s44, v16
	v_add_u32_e32 v16, s2, v83
	s_nop 0
	v_addc_co_u32_e32 v3, vcc, 0, v17, vcc
	global_store_dwordx4 v[2:3], v[6:9], off nt
	v_add_u32_e32 v2, 40, v16
	v_and_b32_e32 v2, 0x10f, v2
	v_or_b32_e32 v2, s0, v2
	v_lshlrev_b32_e32 v2, 13, v2
	v_mov_b32_e32 v3, v71
	v_lshl_add_u64 v[2:3], v[14:15], 0, v[2:3]
	v_add_co_u32_e32 v2, vcc, s44, v2
	v_add_u32_e32 v6, 48, v16
	s_nop 0
	v_addc_co_u32_e32 v3, vcc, 0, v3, vcc
	s_waitcnt lgkmcnt(0)
	global_store_dwordx4 v[2:3], v[10:13], off nt
	v_add_u32_e32 v2, v101, v102
	v_and_b32_e32 v6, 0x117, v6
	ds_read_b128 v[2:5], v2
	v_or_b32_e32 v6, s0, v6
	v_lshlrev_b32_e32 v6, 13, v6
	v_mov_b32_e32 v7, v71
	v_lshl_add_u64 v[6:7], v[14:15], 0, v[6:7]
	v_add_co_u32_e32 v10, vcc, s44, v6
	v_add_u32_e32 v6, v104, v105
	s_nop 0
	v_addc_co_u32_e32 v11, vcc, 0, v7, vcc
	ds_read_b128 v[6:9], v6
	s_waitcnt lgkmcnt(1)
	global_store_dwordx4 v[10:11], v[2:5], off nt
	s_nop 1
	v_add_u32_e32 v2, 56, v16
	v_and_b32_e32 v2, 0x11f, v2
	v_or_b32_e32 v2, s0, v2
	v_lshlrev_b32_e32 v2, 13, v2
	v_mov_b32_e32 v3, v71
	v_lshl_add_u64 v[2:3], v[14:15], 0, v[2:3]
	v_add_co_u32_e32 v2, vcc, 0x100000, v2
	s_mov_b64 s[0:1], 0
	s_nop 0
	v_addc_co_u32_e32 v3, vcc, 0, v3, vcc
	s_waitcnt lgkmcnt(0)
	global_store_dwordx4 v[2:3], v[6:9], off nt
	s_waitcnt lgkmcnt(0)

; #define LAS __attribute__((address_space(3)))
; #define LDS_WAIT() asm volatile("s_waitcnt lgkmcnt(0)" ::: "memory")
; __device__ __forceinline__ unsigned cvt_pk_bf16(float lo, float hi) { unsigned r; asm volatile("v_cvt_pk_bf16_f32 %0, %1, %2" : "=v"(r) : "v"(lo), "v"(hi)); return r; }
;     ...
; #pragma unroll
;     for (int i = 0; i < 8; ++i)
; #pragma unroll
;         for (int e = 0; e < 4; ++e) *(LAS unsigned*)(scr + (4 * r16 + e) * 128 + ((i ^ (r16 & 7)) * 16) + q * 4) = cvt_pk_bf16(v[2 * i][e], v[2 * i + 1][e]);
;     LDS_WAIT(); asm volatile("" ::: "memory");
;     const int c = lane & 7;
; #pragma unroll
;     for (int j = 0; j < 8; ++j) { const int row = (lane >> 3) + 8 * j; const u32x4 o = *(const LAS u32x4*)(scr + row * 128 + ((c ^ ((row >> 2) & 7)) * 16));
;         const int lc = col_off + n0 + row; int dr;
;         if (MODE == 0) dr = lc;
;         else if (MODE == 1) dr = (lc & ~255) + 128 * ((lc >> 5) & 1) + 32 * ((lc >> 6) & 3) + (lc & 31);
;         else if (MODE == 2) dr = 256 * (lc >> 7) + (lc & 127);
;         else dr = 256 * (lc >> 7) + 128 + (lc & 127);
;         *(u32x4*)(WT + (size_t)dr * (ldt ? ldt : K) + k0 + 8 * c) = o; }
;     LDS_WAIT(); asm volatile("" ::: "memory");
; __device__ __forceinline__ void weights_pass(const Args& a, LAS unsigned char* scr, int gw, int NGW, int lane, int pass) {
;     ...
;         if (r < I_QM) { transpose_item<0>(a.in[I_WQM] + (size_t)l * DM * MW, DM, MW, (bf16_t*)(wl + WL_Q), a.in[I_GCROSS] + l * DM, nullptr, 0, scr, r, lane); continue; } r -= I_QM;
.LBB0_27:
	s_waitcnt vmcnt(14)
	v_cvt_pk_bf16_f32 v58, v58, v62
	v_add_u32_e32 v62, v73, v75
	ds_write_b32 v62, v58
	v_cvt_pk_bf16_f32 v58, v59, v63
	ds_write_b32 v62, v58 offset:128
	v_cvt_pk_bf16_f32 v58, v60, v64
	ds_write_b32 v62, v58 offset:256
	v_cvt_pk_bf16_f32 v58, v61, v65
	ds_write_b32 v62, v58 offset:384
	s_waitcnt vmcnt(12)
	v_cvt_pk_bf16_f32 v50, v50, v54
	v_add_u32_e32 v54, v76, v75
	ds_write_b32 v54, v50
	v_cvt_pk_bf16_f32 v50, v51, v55
	ds_write_b32 v54, v50 offset:128
	v_cvt_pk_bf16_f32 v50, v52, v56
	ds_write_b32 v54, v50 offset:256
	v_cvt_pk_bf16_f32 v50, v53, v57
	ds_write_b32 v54, v50 offset:384
	s_waitcnt vmcnt(10)
	v_cvt_pk_bf16_f32 v42, v42, v46
	v_add_u32_e32 v46, v77, v75
	ds_write_b32 v46, v42
	v_cvt_pk_bf16_f32 v42, v43, v47
	ds_write_b32 v46, v42 offset:128
	v_cvt_pk_bf16_f32 v42, v44, v48
	ds_write_b32 v46, v42 offset:256
	v_cvt_pk_bf16_f32 v42, v45, v49
	ds_write_b32 v46, v42 offset:384
	s_waitcnt vmcnt(8)
	v_cvt_pk_bf16_f32 v34, v34, v38
	v_add_u32_e32 v38, v78, v75
	ds_write_b32 v38, v34
	v_cvt_pk_bf16_f32 v34, v35, v39
	ds_write_b32 v38, v34 offset:128
	v_cvt_pk_bf16_f32 v34, v36, v40
	ds_write_b32 v38, v34 offset:256
	v_cvt_pk_bf16_f32 v34, v37, v41
	ds_write_b32 v38, v34 offset:384
	s_waitcnt vmcnt(6)
	v_cvt_pk_bf16_f32 v26, v26, v30
	v_add_u32_e32 v30, v79, v75
	ds_write_b32 v30, v26
	v_cvt_pk_bf16_f32 v26, v27, v31
	ds_write_b32 v30, v26 offset:128
	v_cvt_pk_bf16_f32 v26, v28, v32
	ds_write_b32 v30, v26 offset:256
	v_cvt_pk_bf16_f32 v26, v29, v33
	ds_write_b32 v30, v26 offset:384
	s_waitcnt vmcnt(4)
	v_cvt_pk_bf16_f32 v18, v18, v22
	v_add_u32_e32 v22, v80, v75
	ds_write_b32 v22, v18
	v_cvt_pk_bf16_f32 v18, v19, v23
	ds_write_b32 v22, v18 offset:128
	v_cvt_pk_bf16_f32 v18, v20, v24
	ds_write_b32 v22, v18 offset:256
	v_cvt_pk_bf16_f32 v18, v21, v25
	ds_write_b32 v22, v18 offset:384
	s_waitcnt vmcnt(2)
	v_cvt_pk_bf16_f32 v10, v10, v14
	v_add_u32_e32 v14, v81, v75
	ds_write_b32 v14, v10
	v_cvt_pk_bf16_f32 v10, v11, v15
	ds_write_b32 v14, v10 offset:128
	v_cvt_pk_bf16_f32 v10, v12, v16
	ds_write_b32 v14, v10 offset:256
	v_cvt_pk_bf16_f32 v10, v13, v17
	ds_write_b32 v14, v10 offset:384
	s_waitcnt vmcnt(0)
	v_cvt_pk_bf16_f32 v2, v2, v6
	v_add_u32_e32 v6, v82, v75
	ds_write_b32 v6, v2
	v_cvt_pk_bf16_f32 v2, v3, v7
	s_and_b32 s0, 0xffff, s12
	ds_write_b32 v6, v2 offset:128
	v_cvt_pk_bf16_f32 v2, v4, v8
	s_lshl_b32 s1, s2, 1
	ds_write_b32 v6, v2 offset:256
	v_cvt_pk_bf16_f32 v2, v5, v9
	s_add_u32 s12, s47, s1
	ds_write_b32 v6, v2 offset:384
	s_addc_u32 s13, s48, 0
	v_lshlrev_b32_e32 v2, 1, v72
	v_mov_b32_e32 v3, v71
	s_waitcnt lgkmcnt(0)
	v_lshl_add_u64 v[2:3], s[12:13], 0, v[2:3]
	s_mov_b64 s[12:13], 0x4600000
	v_lshl_add_u64 v[10:11], v[2:3], 0, s[12:13]
	v_add_u32_e32 v2, v84, v85
	ds_read_b128 v[2:5], v2
	v_or_b32_e32 v6, s0, v83
	v_lshlrev_b32_e32 v6, 13, v6
	v_mov_b32_e32 v7, v71
	v_lshl_add_u64 v[12:13], v[10:11], 0, v[6:7]
	v_add_u32_e32 v6, v87, v88
	ds_read_b128 v[6:9], v6
	s_waitcnt lgkmcnt(1)
	global_store_dwordx4 v[12:13], v[2:5], off nt
	s_nop 1
	v_or_b32_e32 v2, s0, v86
	v_lshlrev_b32_e32 v2, 13, v2
	v_mov_b32_e32 v3, v71
	v_lshl_add_u64 v[2:3], v[10:11], 0, v[2:3]
	s_waitcnt lgkmcnt(0)
	global_store_dwordx4 v[2:3], v[6:9], off nt
	v_add_u32_e32 v2, v90, v91
	ds_read_b128 v[2:5], v2
	v_or_b32_e32 v6, s0, v89
	v_lshlrev_b32_e32 v6, 13, v6
	v_mov_b32_e32 v7, v71
	v_lshl_add_u64 v[12:13], v[10:11], 0, v[6:7]
	v_add_u32_e32 v6, v93, v94
	ds_read_b128 v[6:9], v6
	s_waitcnt lgkmcnt(1)
	global_store_dwordx4 v[12:13], v[2:5], off nt
	s_nop 1
	v_or_b32_e32 v2, s0, v92
	v_lshlrev_b32_e32 v2, 13, v2
	v_mov_b32_e32 v3, v71
	v_lshl_add_u64 v[2:3], v[10:11], 0, v[2:3]
	s_waitcnt lgkmcnt(0)
	global_store_dwordx4 v[2:3], v[6:9], off nt
	v_add_u32_e32 v2, v96, v85
	ds_read_b128 v[2:5], v2
	v_or_b32_e32 v6, s0, v95
	v_lshlrev_b32_e32 v6, 13, v6
	v_mov_b32_e32 v7, v71
	v_lshl_add_u64 v[12:13], v[10:11], 0, v[6:7]
	v_add_u32_e32 v6, v98, v99
	ds_read_b128 v[6:9], v6
	s_waitcnt lgkmcnt(1)
	global_store_dwordx4 v[12:13], v[2:5], off nt
	s_nop 1
	v_or_b32_e32 v2, s0, v97
	v_lshlrev_b32_e32 v2, 13, v2
	v_mov_b32_e32 v3, v71
	v_lshl_add_u64 v[2:3], v[10:11], 0, v[2:3]
	s_waitcnt lgkmcnt(0)
	global_store_dwordx4 v[2:3], v[6:9], off nt
	v_add_u32_e32 v2, v101, v102
	ds_read_b128 v[2:5], v2
	v_or_b32_e32 v6, s0, v100
	v_lshlrev_b32_e32 v6, 13, v6
	v_mov_b32_e32 v7, v71
	v_lshl_add_u64 v[12:13], v[10:11], 0, v[6:7]
	v_add_u32_e32 v6, v104, v105
	ds_read_b128 v[6:9], v6
	s_waitcnt lgkmcnt(1)
	global_store_dwordx4 v[12:13], v[2:5], off nt
	s_nop 1
	v_or_b32_e32 v2, s0, v103
	v_lshlrev_b32_e32 v2, 13, v2
	v_mov_b32_e32 v3, v71
	v_lshl_add_u64 v[2:3], v[10:11], 0, v[2:3]
	s_waitcnt lgkmcnt(0)
	global_store_dwordx4 v[2:3], v[6:9], off nt
	s_waitcnt lgkmcnt(0)

; #define LAS __attribute__((address_space(3)))
; __device__ __forceinline__ unsigned cvt_pk_bf16(float lo, float hi) { unsigned r; asm volatile("v_cvt_pk_bf16_f32 %0, %1, %2" : "=v"(r) : "v"(lo), "v"(hi)); return r; }
;     const int nblk = N / 64, kb = item / nblk, nb = item % nblk, k0 = 64 * kb, n0 = 64 * nb;
;     const int r16 = lane & 15, q = lane >> 4;
;     const float* src = W + (size_t)(k0 + 2 * q) * N + n0 + 4 * r16;
;     f32x4 v[16];
; #pragma unroll
;     for (int j = 0; j < 16; ++j) v[j] = *(const f32x4*)(src + (size_t)(8 * (j >> 1) + (j & 1)) * N);
;     if (nscale) { const f32x4 ns = *(const f32x4*)(nscale + n0 + 4 * r16);
; #pragma unroll
;         for (int j = 0; j < 16; ++j) v[j] = v[j] * ns; }
;     if (kscale) {
; #pragma unroll
;         for (int i = 0; i < 8; ++i) { const f32x2 g = *(const f32x2*)(kscale + k0 + 8 * i + 2 * q); v[2 * i] = v[2 * i] * g[0]; v[2 * i + 1] = v[2 * i + 1] * g[1]; } }
; #pragma unroll
;     for (int i = 0; i < 8; ++i)
; #pragma unroll
;         for (int e = 0; e < 4; ++e) *(LAS unsigned*)(scr + (4 * r16 + e) * 128 + ((i ^ (r16 & 7)) * 16) + q * 4) = cvt_pk_bf16(v[2 * i][e], v[2 * i + 1][e]);
; __device__ __forceinline__ void weights_pass(const Args& a, LAS unsigned char* scr, int gw, int NGW, int lane, int pass) {
;     ...
;         if (r < I_OUT / 2) { transpose_item<0>(a.in[I_WOUT] + (size_t)l * DM * DM + (size_t)2048 * DM, 2048, DM, (bf16_t*)(ws + WS_WLOW) + (size_t)l * DM * 2048, nullptr, nullptr, 0, scr, r, lane); continue; } r -= I_OUT / 2;
.LBB0_29:
	s_andn2_b64 vcc, exec, s[0:1]
	s_cbranch_vccnz .LBB0_31
	v_readlane_b32 s52, v250, 10
	s_lshl_b64 s[0:1], s[10:11], 26
	v_readlane_b32 s66, v250, 24
	v_readlane_b32 s67, v250, 25
	s_add_u32 s14, s66, s0
	s_addc_u32 s15, s67, s1
	s_lshl_b64 s[12:13], s[10:11], 24
	s_add_u32 s1, s27, s12
	s_addc_u32 s2, s30, s13
	s_and_b32 s12, s51, 0xffc0
	s_lshl_b32 s0, s49, 6
	v_lshlrev_b32_e32 v2, 2, v67
	s_and_b32 s0, s0, 0xfc0
	v_lshl_or_b32 v2, s12, 14, v2
	v_mov_b32_e32 v3, v71
	v_lshl_add_u64 v[2:3], s[14:15], 0, v[2:3]
	s_lshl_b32 s8, s0, 2
	v_lshl_add_u64 v[2:3], v[2:3], 0, s[8:9]
	v_lshl_add_u64 v[58:59], v[2:3], 0, v[70:71]
	s_brev_b32 s8, 64
	v_add_co_u32_e32 v2, vcc, s8, v58
	s_mov_b32 s8, 0x2004000
	s_nop 0
	v_addc_co_u32_e32 v3, vcc, 0, v59, vcc
	v_add_co_u32_e32 v6, vcc, s8, v58
	s_mov_b32 s8, 0x2020000
	s_nop 0
	v_addc_co_u32_e32 v7, vcc, 0, v59, vcc
	global_load_dwordx4 v[2:5], v[2:3], off nt
	s_nop 0
	global_load_dwordx4 v[6:9], v[6:7], off nt
	v_add_co_u32_e32 v10, vcc, s8, v58
	s_mov_b32 s8, 0x2024000
	s_nop 0
	v_addc_co_u32_e32 v11, vcc, 0, v59, vcc
	v_add_co_u32_e32 v14, vcc, s8, v58
	s_mov_b32 s8, 0x2040000
	s_nop 0
	v_addc_co_u32_e32 v15, vcc, 0, v59, vcc
	global_load_dwordx4 v[10:13], v[10:11], off nt
	s_nop 0
	global_load_dwordx4 v[14:17], v[14:15], off nt
	v_add_co_u32_e32 v18, vcc, s8, v58
	s_mov_b32 s8, 0x2044000
	s_nop 0
	v_addc_co_u32_e32 v19, vcc, 0, v59, vcc
	v_add_co_u32_e32 v22, vcc, s8, v58
	s_mov_b32 s8, 0x2060000
	s_nop 0
	v_addc_co_u32_e32 v23, vcc, 0, v59, vcc
	global_load_dwordx4 v[18:21], v[18:19], off nt
	s_nop 0
	global_load_dwordx4 v[22:25], v[22:23], off nt
	v_add_co_u32_e32 v26, vcc, s8, v58
	s_mov_b32 s8, 0x2064000
	s_nop 0
	v_addc_co_u32_e32 v27, vcc, 0, v59, vcc
	v_add_co_u32_e32 v30, vcc, s8, v58
	s_mov_b32 s8, 0x2080000
	s_nop 0
	v_addc_co_u32_e32 v31, vcc, 0, v59, vcc
	global_load_dwordx4 v[26:29], v[26:27], off nt
	s_nop 0
	global_load_dwordx4 v[30:33], v[30:31], off nt
	v_add_co_u32_e32 v34, vcc, s8, v58
	s_mov_b32 s8, 0x2084000
	s_nop 0
	v_addc_co_u32_e32 v35, vcc, 0, v59, vcc
	v_add_co_u32_e32 v38, vcc, s8, v58
	s_mov_b32 s8, 0x20a0000
	s_nop 0
	v_addc_co_u32_e32 v39, vcc, 0, v59, vcc
	global_load_dwordx4 v[34:37], v[34:35], off nt
	s_nop 0
	global_load_dwordx4 v[38:41], v[38:39], off nt
	v_add_co_u32_e32 v42, vcc, s8, v58
	s_mov_b32 s8, 0x20a4000
	s_nop 0
	v_addc_co_u32_e32 v43, vcc, 0, v59, vcc
	v_add_co_u32_e32 v46, vcc, s8, v58
	s_mov_b32 s8, 0x20c0000
	s_nop 0
	v_addc_co_u32_e32 v47, vcc, 0, v59, vcc
	global_load_dwordx4 v[42:45], v[42:43], off nt
	s_nop 0
	global_load_dwordx4 v[46:49], v[46:47], off nt
	v_add_co_u32_e32 v50, vcc, s8, v58
	s_mov_b32 s8, 0x20c4000
	s_nop 0
	v_addc_co_u32_e32 v51, vcc, 0, v59, vcc
	v_add_co_u32_e32 v54, vcc, s8, v58
	s_mov_b32 s8, 0x20e0000
	s_nop 0
	v_addc_co_u32_e32 v55, vcc, 0, v59, vcc
	global_load_dwordx4 v[50:53], v[50:51], off nt
	s_nop 0
	global_load_dwordx4 v[54:57], v[54:55], off nt
	v_add_co_u32_e32 v60, vcc, s8, v58
	s_mov_b32 s8, 0x20e4000
	s_nop 0
	v_addc_co_u32_e32 v61, vcc, 0, v59, vcc
	v_add_co_u32_e32 v62, vcc, s8, v58
	s_lshl_b32 s8, s12, 1
	s_nop 0
	v_addc_co_u32_e32 v63, vcc, 0, v59, vcc
	global_load_dwordx4 v[58:61], v[60:61], off nt
	s_nop 0
	global_load_dwordx4 v[62:65], v[62:63], off nt
	s_waitcnt vmcnt(14)
	v_cvt_pk_bf16_f32 v2, v2, v6
	v_add_u32_e32 v6, v73, v75
	ds_write_b32 v6, v2
	v_cvt_pk_bf16_f32 v2, v3, v7
	ds_write_b32 v6, v2 offset:128
	v_cvt_pk_bf16_f32 v2, v4, v8
	ds_write_b32 v6, v2 offset:256
	v_cvt_pk_bf16_f32 v2, v5, v9
	ds_write_b32 v6, v2 offset:384
	s_waitcnt vmcnt(12)
	v_cvt_pk_bf16_f32 v2, v10, v14
	v_add_u32_e32 v3, v76, v75
	ds_write_b32 v3, v2
	v_cvt_pk_bf16_f32 v2, v11, v15
	ds_write_b32 v3, v2 offset:128
	v_cvt_pk_bf16_f32 v2, v12, v16
	ds_write_b32 v3, v2 offset:256
	v_cvt_pk_bf16_f32 v2, v13, v17
	ds_write_b32 v3, v2 offset:384
	s_waitcnt vmcnt(10)
	v_cvt_pk_bf16_f32 v2, v18, v22
	v_add_u32_e32 v3, v77, v75
	ds_write_b32 v3, v2
	v_cvt_pk_bf16_f32 v2, v19, v23
	ds_write_b32 v3, v2 offset:128
	v_cvt_pk_bf16_f32 v2, v20, v24
	ds_write_b32 v3, v2 offset:256
	v_cvt_pk_bf16_f32 v2, v21, v25
	ds_write_b32 v3, v2 offset:384
	s_waitcnt vmcnt(8)
; #define LAS __attribute__((address_space(3)))
; #define LDS_WAIT() asm volatile("s_waitcnt lgkmcnt(0)" ::: "memory")
; __device__ __forceinline__ unsigned cvt_pk_bf16(float lo, float hi) { unsigned r; asm volatile("v_cvt_pk_bf16_f32 %0, %1, %2" : "=v"(r) : "v"(lo), "v"(hi)); return r; }
;     ...
;         for (int e = 0; e < 4; ++e) *(LAS unsigned*)(scr + (4 * r16 + e) * 128 + ((i ^ (r16 & 7)) * 16) + q * 4) = cvt_pk_bf16(v[2 * i][e], v[2 * i + 1][e]);
;     LDS_WAIT(); asm volatile("" ::: "memory");
;     const int c = lane & 7;
; #pragma unroll
;     for (int j = 0; j < 8; ++j) { const int row = (lane >> 3) + 8 * j; const u32x4 o = *(const LAS u32x4*)(scr + row * 128 + ((c ^ ((row >> 2) & 7)) * 16));
;         const int lc = col_off + n0 + row; int dr;
;         if (MODE == 0) dr = lc;
;         else if (MODE == 1) dr = (lc & ~255) + 128 * ((lc >> 5) & 1) + 32 * ((lc >> 6) & 3) + (lc & 31);
;         else if (MODE == 2) dr = 256 * (lc >> 7) + (lc & 127);
;         else dr = 256 * (lc >> 7) + 128 + (lc & 127);
;         *(u32x4*)(WT + (size_t)dr * (ldt ? ldt : K) + k0 + 8 * c) = o; }
;     LDS_WAIT(); asm volatile("" ::: "memory");
	v_cvt_pk_bf16_f32 v2, v26, v30
	v_add_u32_e32 v3, v78, v75
	ds_write_b32 v3, v2
	v_cvt_pk_bf16_f32 v2, v27, v31
	ds_write_b32 v3, v2 offset:128
	v_cvt_pk_bf16_f32 v2, v28, v32
	ds_write_b32 v3, v2 offset:256
	v_cvt_pk_bf16_f32 v2, v29, v33
	ds_write_b32 v3, v2 offset:384
	s_waitcnt vmcnt(6)
	v_cvt_pk_bf16_f32 v2, v34, v38
	v_add_u32_e32 v3, v79, v75
	ds_write_b32 v3, v2
	v_cvt_pk_bf16_f32 v2, v35, v39
	ds_write_b32 v3, v2 offset:128
	v_cvt_pk_bf16_f32 v2, v36, v40
	ds_write_b32 v3, v2 offset:256
	v_cvt_pk_bf16_f32 v2, v37, v41
	ds_write_b32 v3, v2 offset:384
	s_waitcnt vmcnt(4)
	v_cvt_pk_bf16_f32 v2, v42, v46
	v_add_u32_e32 v3, v80, v75
	ds_write_b32 v3, v2
	v_cvt_pk_bf16_f32 v2, v43, v47
	ds_write_b32 v3, v2 offset:128
	v_cvt_pk_bf16_f32 v2, v44, v48
	ds_write_b32 v3, v2 offset:256
	v_cvt_pk_bf16_f32 v2, v45, v49
	ds_write_b32 v3, v2 offset:384
	s_waitcnt vmcnt(2)
	v_cvt_pk_bf16_f32 v2, v50, v54
	v_add_u32_e32 v3, v81, v75
	ds_write_b32 v3, v2
	v_cvt_pk_bf16_f32 v2, v51, v55
	ds_write_b32 v3, v2 offset:128
	v_cvt_pk_bf16_f32 v2, v52, v56
	ds_write_b32 v3, v2 offset:256
	v_cvt_pk_bf16_f32 v2, v53, v57
	ds_write_b32 v3, v2 offset:384
	s_waitcnt vmcnt(0)
	v_cvt_pk_bf16_f32 v2, v58, v62
	v_add_u32_e32 v3, v82, v75
	ds_write_b32 v3, v2
	v_cvt_pk_bf16_f32 v2, v59, v63
	ds_write_b32 v3, v2 offset:128
	v_cvt_pk_bf16_f32 v2, v60, v64
	ds_write_b32 v3, v2 offset:256
	v_cvt_pk_bf16_f32 v2, v61, v65
	ds_write_b32 v3, v2 offset:384
	s_add_u32 s12, s1, s8
	s_waitcnt lgkmcnt(0)
	s_addc_u32 s13, s2, 0
	v_lshlrev_b32_e32 v2, 1, v72
	v_mov_b32_e32 v3, v71
	v_lshl_add_u64 v[10:11], s[12:13], 0, v[2:3]
	v_add_u32_e32 v2, v84, v85
	ds_read_b128 v[2:5], v2
	v_or_b32_e32 v6, s0, v83
	v_lshlrev_b32_e32 v6, 12, v6
	v_mov_b32_e32 v7, v71
	v_lshl_add_u64 v[12:13], v[10:11], 0, v[6:7]
	v_add_u32_e32 v6, v87, v88
	ds_read_b128 v[6:9], v6
	s_waitcnt lgkmcnt(1)
	global_store_dwordx4 v[12:13], v[2:5], off nt
	v_readlane_b32 s53, v250, 11
	v_readlane_b32 s54, v250, 12
	v_or_b32_e32 v2, s0, v86
	v_lshlrev_b32_e32 v2, 12, v2
	v_mov_b32_e32 v3, v71
	v_lshl_add_u64 v[2:3], v[10:11], 0, v[2:3]
	s_waitcnt lgkmcnt(0)
	global_store_dwordx4 v[2:3], v[6:9], off nt
	v_add_u32_e32 v2, v90, v91
	ds_read_b128 v[2:5], v2
	v_or_b32_e32 v6, s0, v89
	v_lshlrev_b32_e32 v6, 12, v6
	v_mov_b32_e32 v7, v71
	v_lshl_add_u64 v[12:13], v[10:11], 0, v[6:7]
	v_add_u32_e32 v6, v93, v94
	ds_read_b128 v[6:9], v6
	s_waitcnt lgkmcnt(1)
	global_store_dwordx4 v[12:13], v[2:5], off nt
	v_readlane_b32 s55, v250, 13
	v_readlane_b32 s56, v250, 14
	v_or_b32_e32 v2, s0, v92
	v_lshlrev_b32_e32 v2, 12, v2
	v_mov_b32_e32 v3, v71
	v_lshl_add_u64 v[2:3], v[10:11], 0, v[2:3]
	s_waitcnt lgkmcnt(0)
	global_store_dwordx4 v[2:3], v[6:9], off nt
	v_add_u32_e32 v2, v96, v85
	ds_read_b128 v[2:5], v2
	v_or_b32_e32 v6, s0, v95
	v_lshlrev_b32_e32 v6, 12, v6
	v_mov_b32_e32 v7, v71
	v_lshl_add_u64 v[12:13], v[10:11], 0, v[6:7]
	v_add_u32_e32 v6, v98, v99
	ds_read_b128 v[6:9], v6
	s_waitcnt lgkmcnt(1)
	global_store_dwordx4 v[12:13], v[2:5], off nt
	v_readlane_b32 s57, v250, 15
	v_readlane_b32 s58, v250, 16
	v_or_b32_e32 v2, s0, v97
	v_lshlrev_b32_e32 v2, 12, v2
	v_mov_b32_e32 v3, v71
	v_lshl_add_u64 v[2:3], v[10:11], 0, v[2:3]
	s_waitcnt lgkmcnt(0)
	global_store_dwordx4 v[2:3], v[6:9], off nt
	v_add_u32_e32 v2, v101, v102
	ds_read_b128 v[2:5], v2
	v_or_b32_e32 v6, s0, v100
	v_lshlrev_b32_e32 v6, 12, v6
	v_mov_b32_e32 v7, v71
	v_lshl_add_u64 v[12:13], v[10:11], 0, v[6:7]
	v_add_u32_e32 v6, v104, v105
	ds_read_b128 v[6:9], v6
	s_waitcnt lgkmcnt(1)
	global_store_dwordx4 v[12:13], v[2:5], off nt
	v_readlane_b32 s59, v250, 17
	v_readlane_b32 s60, v250, 18
	v_or_b32_e32 v2, s0, v103
	v_lshlrev_b32_e32 v2, 12, v2
	v_mov_b32_e32 v3, v71
	v_lshl_add_u64 v[2:3], v[10:11], 0, v[2:3]
	s_waitcnt lgkmcnt(0)
	global_store_dwordx4 v[2:3], v[6:9], off nt
	s_waitcnt lgkmcnt(0)
	v_readlane_b32 s61, v250, 19
	v_readlane_b32 s62, v250, 20
	v_readlane_b32 s63, v250, 21
	v_readlane_b32 s64, v250, 22
	v_readlane_b32 s65, v250, 23

; #define LAS __attribute__((address_space(3)))
; __device__ __forceinline__ unsigned cvt_pk_bf16(float lo, float hi) { unsigned r; asm volatile("v_cvt_pk_bf16_f32 %0, %1, %2" : "=v"(r) : "v"(lo), "v"(hi)); return r; }
;     const int nblk = N / 64, kb = item / nblk, nb = item % nblk, k0 = 64 * kb, n0 = 64 * nb;
;     const int r16 = lane & 15, q = lane >> 4;
;     const float* src = W + (size_t)(k0 + 2 * q) * N + n0 + 4 * r16;
;     f32x4 v[16];
; #pragma unroll
;     for (int j = 0; j < 16; ++j) v[j] = *(const f32x4*)(src + (size_t)(8 * (j >> 1) + (j & 1)) * N);
;     if (nscale) { const f32x4 ns = *(const f32x4*)(nscale + n0 + 4 * r16);
; #pragma unroll
;         for (int j = 0; j < 16; ++j) v[j] = v[j] * ns; }
;     if (kscale) {
; #pragma unroll
;         for (int i = 0; i < 8; ++i) { const f32x2 g = *(const f32x2*)(kscale + k0 + 8 * i + 2 * q); v[2 * i] = v[2 * i] * g[0]; v[2 * i + 1] = v[2 * i + 1] * g[1]; } }
; #pragma unroll
;     for (int i = 0; i < 8; ++i)
; #pragma unroll
;         for (int e = 0; e < 4; ++e) *(LAS unsigned*)(scr + (4 * r16 + e) * 128 + ((i ^ (r16 & 7)) * 16) + q * 4) = cvt_pk_bf16(v[2 * i][e], v[2 * i + 1][e]);
; __device__ __forceinline__ void weights_pass(const Args& a, LAS unsigned char* scr, int gw, int NGW, int lane, int pass) {
;     ...
;         if (r < I_OUT / 2) { transpose_item<0>(a.in[I_WOUT] + (size_t)l * DM * DM, 2048, DM, (bf16_t*)(wl + WL_OUT), nullptr, nullptr, 0, scr, r, lane, DM); continue; } r -= I_OUT / 2;
.LBB0_32:
	s_andn2_b64 vcc, exec, s[0:1]
	s_cbranch_vccnz .LBB0_34
	v_readlane_b32 s52, v250, 10
	s_lshl_b64 s[0:1], s[10:11], 26
	v_readlane_b32 s66, v250, 24
	v_readlane_b32 s67, v250, 25
	s_add_u32 s12, s66, s0
	s_addc_u32 s13, s67, s1
	s_add_i32 s0, s49, 0xee00
	s_and_b32 s1, s0, 0xffc0
	s_lshl_b32 s0, s49, 6
	v_lshlrev_b32_e32 v2, 2, v67
	s_and_b32 s0, s0, 0xfc0
	v_lshl_or_b32 v2, s1, 14, v2
	v_mov_b32_e32 v3, v71
	v_lshl_add_u64 v[2:3], s[12:13], 0, v[2:3]
	s_lshl_b32 s8, s0, 2
	v_lshl_add_u64 v[2:3], v[2:3], 0, s[8:9]
	v_lshl_add_u64 v[58:59], v[2:3], 0, v[70:71]
	v_add_co_u32_e32 v6, vcc, s39, v58
	s_mov_b32 s2, 0x20000
	s_nop 0
	v_addc_co_u32_e32 v7, vcc, 0, v59, vcc
	global_load_dwordx4 v[2:5], v[58:59], off nt
	s_nop 0
	global_load_dwordx4 v[6:9], v[6:7], off nt
	v_add_co_u32_e32 v10, vcc, s2, v58
	s_mov_b32 s2, 0x40000
	s_nop 0
	v_addc_co_u32_e32 v11, vcc, 0, v59, vcc
	v_add_co_u32_e32 v14, vcc, s45, v58
	s_lshl_b32 s1, s1, 1
	s_nop 0
	v_addc_co_u32_e32 v15, vcc, 0, v59, vcc
	global_load_dwordx4 v[10:13], v[10:11], off nt
	s_nop 0
	global_load_dwordx4 v[14:17], v[14:15], off nt
	v_add_co_u32_e32 v18, vcc, s2, v58
	s_mov_b32 s2, 0x44000
	s_nop 0
	v_addc_co_u32_e32 v19, vcc, 0, v59, vcc
	v_add_co_u32_e32 v22, vcc, s2, v58
	s_mov_b32 s2, 0x60000
	s_nop 0
	v_addc_co_u32_e32 v23, vcc, 0, v59, vcc
	global_load_dwordx4 v[18:21], v[18:19], off nt
	s_nop 0
	global_load_dwordx4 v[22:25], v[22:23], off nt
	v_add_co_u32_e32 v26, vcc, s2, v58
	s_mov_b32 s2, 0x64000
	s_nop 0
	v_addc_co_u32_e32 v27, vcc, 0, v59, vcc
	v_add_co_u32_e32 v30, vcc, s2, v58
	s_mov_b32 s2, 0x80000
	s_nop 0
	v_addc_co_u32_e32 v31, vcc, 0, v59, vcc
	global_load_dwordx4 v[26:29], v[26:27], off nt
	s_nop 0
	global_load_dwordx4 v[30:33], v[30:31], off nt
	v_add_co_u32_e32 v34, vcc, s2, v58
	s_mov_b32 s2, 0x84000
	s_nop 0
	v_addc_co_u32_e32 v35, vcc, 0, v59, vcc
	v_add_co_u32_e32 v38, vcc, s2, v58
	s_mov_b32 s2, 0xa0000
	s_nop 0
	v_addc_co_u32_e32 v39, vcc, 0, v59, vcc
	global_load_dwordx4 v[34:37], v[34:35], off nt
	s_nop 0
	global_load_dwordx4 v[38:41], v[38:39], off nt
	v_add_co_u32_e32 v42, vcc, s2, v58
	s_mov_b32 s2, 0xa4000
	s_nop 0
	v_addc_co_u32_e32 v43, vcc, 0, v59, vcc
	v_add_co_u32_e32 v46, vcc, s2, v58
	s_mov_b32 s2, 0xc0000
	s_nop 0
	v_addc_co_u32_e32 v47, vcc, 0, v59, vcc
	global_load_dwordx4 v[42:45], v[42:43], off nt
	s_nop 0
	global_load_dwordx4 v[46:49], v[46:47], off nt
	v_add_co_u32_e32 v50, vcc, s2, v58
	s_mov_b32 s2, 0xc4000
	s_nop 0
	v_addc_co_u32_e32 v51, vcc, 0, v59, vcc
	v_add_co_u32_e32 v54, vcc, s2, v58
	s_mov_b32 s2, 0xe0000
	s_nop 0
	v_addc_co_u32_e32 v55, vcc, 0, v59, vcc
	global_load_dwordx4 v[50:53], v[50:51], off nt
	s_nop 0
	global_load_dwordx4 v[54:57], v[54:55], off nt
	v_add_co_u32_e32 v60, vcc, s2, v58
	s_mov_b32 s2, 0xe4000
	s_nop 0
	v_addc_co_u32_e32 v61, vcc, 0, v59, vcc
	v_add_co_u32_e32 v62, vcc, s2, v58
	s_add_u32 s12, s47, s1
	s_nop 0
	v_addc_co_u32_e32 v63, vcc, 0, v59, vcc
	global_load_dwordx4 v[58:61], v[60:61], off nt
	s_nop 0
	global_load_dwordx4 v[62:65], v[62:63], off nt
	s_waitcnt vmcnt(14)
	v_cvt_pk_bf16_f32 v2, v2, v6
	v_add_u32_e32 v6, v73, v75
	ds_write_b32 v6, v2
	v_cvt_pk_bf16_f32 v2, v3, v7
	ds_write_b32 v6, v2 offset:128
	v_cvt_pk_bf16_f32 v2, v4, v8
	ds_write_b32 v6, v2 offset:256
	v_cvt_pk_bf16_f32 v2, v5, v9
	ds_write_b32 v6, v2 offset:384
	s_waitcnt vmcnt(12)
	v_cvt_pk_bf16_f32 v2, v10, v14
	v_add_u32_e32 v3, v76, v75
	ds_write_b32 v3, v2
	v_cvt_pk_bf16_f32 v2, v11, v15
	ds_write_b32 v3, v2 offset:128
	v_cvt_pk_bf16_f32 v2, v12, v16
	ds_write_b32 v3, v2 offset:256
	v_cvt_pk_bf16_f32 v2, v13, v17
	ds_write_b32 v3, v2 offset:384
	s_waitcnt vmcnt(10)
	v_cvt_pk_bf16_f32 v2, v18, v22
	v_add_u32_e32 v3, v77, v75
	ds_write_b32 v3, v2
	v_cvt_pk_bf16_f32 v2, v19, v23
	ds_write_b32 v3, v2 offset:128
	v_cvt_pk_bf16_f32 v2, v20, v24
	ds_write_b32 v3, v2 offset:256
	v_cvt_pk_bf16_f32 v2, v21, v25
	ds_write_b32 v3, v2 offset:384
	s_waitcnt vmcnt(8)
; #define LAS __attribute__((address_space(3)))
; #define LDS_WAIT() asm volatile("s_waitcnt lgkmcnt(0)" ::: "memory")
; __device__ __forceinline__ unsigned cvt_pk_bf16(float lo, float hi) { unsigned r; asm volatile("v_cvt_pk_bf16_f32 %0, %1, %2" : "=v"(r) : "v"(lo), "v"(hi)); return r; }
;     ...
;         for (int e = 0; e < 4; ++e) *(LAS unsigned*)(scr + (4 * r16 + e) * 128 + ((i ^ (r16 & 7)) * 16) + q * 4) = cvt_pk_bf16(v[2 * i][e], v[2 * i + 1][e]);
;     LDS_WAIT(); asm volatile("" ::: "memory");
;     const int c = lane & 7;
; #pragma unroll
;     for (int j = 0; j < 8; ++j) { const int row = (lane >> 3) + 8 * j; const u32x4 o = *(const LAS u32x4*)(scr + row * 128 + ((c ^ ((row >> 2) & 7)) * 16));
;         const int lc = col_off + n0 + row; int dr;
;         if (MODE == 0) dr = lc;
;         else if (MODE == 1) dr = (lc & ~255) + 128 * ((lc >> 5) & 1) + 32 * ((lc >> 6) & 3) + (lc & 31);
;         else if (MODE == 2) dr = 256 * (lc >> 7) + (lc & 127);
;         else dr = 256 * (lc >> 7) + 128 + (lc & 127);
;         *(u32x4*)(WT + (size_t)dr * (ldt ? ldt : K) + k0 + 8 * c) = o; }
;     LDS_WAIT(); asm volatile("" ::: "memory");
	v_cvt_pk_bf16_f32 v2, v26, v30
	v_add_u32_e32 v3, v78, v75
	ds_write_b32 v3, v2
	v_cvt_pk_bf16_f32 v2, v27, v31
	ds_write_b32 v3, v2 offset:128
	v_cvt_pk_bf16_f32 v2, v28, v32
	ds_write_b32 v3, v2 offset:256
	v_cvt_pk_bf16_f32 v2, v29, v33
	ds_write_b32 v3, v2 offset:384
	s_waitcnt vmcnt(6)
	v_cvt_pk_bf16_f32 v2, v34, v38
	v_add_u32_e32 v3, v79, v75
	ds_write_b32 v3, v2
	v_cvt_pk_bf16_f32 v2, v35, v39
	ds_write_b32 v3, v2 offset:128
	v_cvt_pk_bf16_f32 v2, v36, v40
	ds_write_b32 v3, v2 offset:256
	v_cvt_pk_bf16_f32 v2, v37, v41
	ds_write_b32 v3, v2 offset:384
	s_waitcnt vmcnt(4)
	v_cvt_pk_bf16_f32 v2, v42, v46
	v_add_u32_e32 v3, v80, v75
	ds_write_b32 v3, v2
	v_cvt_pk_bf16_f32 v2, v43, v47
	ds_write_b32 v3, v2 offset:128
	v_cvt_pk_bf16_f32 v2, v44, v48
	ds_write_b32 v3, v2 offset:256
	v_cvt_pk_bf16_f32 v2, v45, v49
	ds_write_b32 v3, v2 offset:384
	s_waitcnt vmcnt(2)
	v_cvt_pk_bf16_f32 v2, v50, v54
	v_add_u32_e32 v3, v81, v75
	ds_write_b32 v3, v2
	v_cvt_pk_bf16_f32 v2, v51, v55
	ds_write_b32 v3, v2 offset:128
	v_cvt_pk_bf16_f32 v2, v52, v56
	ds_write_b32 v3, v2 offset:256
	v_cvt_pk_bf16_f32 v2, v53, v57
	ds_write_b32 v3, v2 offset:384
	s_waitcnt vmcnt(0)
	v_cvt_pk_bf16_f32 v2, v58, v62
	v_add_u32_e32 v3, v82, v75
	ds_write_b32 v3, v2
	v_cvt_pk_bf16_f32 v2, v59, v63
	ds_write_b32 v3, v2 offset:128
	v_cvt_pk_bf16_f32 v2, v60, v64
	ds_write_b32 v3, v2 offset:256
	v_cvt_pk_bf16_f32 v2, v61, v65
	ds_write_b32 v3, v2 offset:384
	s_addc_u32 s13, s48, 0
	v_lshlrev_b32_e32 v2, 1, v72
	v_mov_b32_e32 v3, v71
	s_waitcnt lgkmcnt(0)
	v_lshl_add_u64 v[2:3], s[12:13], 0, v[2:3]
	s_mov_b64 s[12:13], 0x2600000
	v_lshl_add_u64 v[10:11], v[2:3], 0, s[12:13]
	v_add_u32_e32 v2, v84, v85
	ds_read_b128 v[2:5], v2
	v_or_b32_e32 v6, s0, v83
	v_lshlrev_b32_e32 v6, 13, v6
	v_mov_b32_e32 v7, v71
	v_lshl_add_u64 v[12:13], v[10:11], 0, v[6:7]
	v_add_u32_e32 v6, v87, v88
	ds_read_b128 v[6:9], v6
	s_waitcnt lgkmcnt(1)
	global_store_dwordx4 v[12:13], v[2:5], off nt
	v_readlane_b32 s53, v250, 11
	v_readlane_b32 s54, v250, 12
	v_or_b32_e32 v2, s0, v86
	v_lshlrev_b32_e32 v2, 13, v2
	v_mov_b32_e32 v3, v71
	v_lshl_add_u64 v[2:3], v[10:11], 0, v[2:3]
	s_waitcnt lgkmcnt(0)
	global_store_dwordx4 v[2:3], v[6:9], off nt
	v_add_u32_e32 v2, v90, v91
	ds_read_b128 v[2:5], v2
	v_or_b32_e32 v6, s0, v89
	v_lshlrev_b32_e32 v6, 13, v6
	v_mov_b32_e32 v7, v71
	v_lshl_add_u64 v[12:13], v[10:11], 0, v[6:7]
	v_add_u32_e32 v6, v93, v94
	ds_read_b128 v[6:9], v6
	s_waitcnt lgkmcnt(1)
	global_store_dwordx4 v[12:13], v[2:5], off nt
	v_readlane_b32 s55, v250, 13
	v_readlane_b32 s56, v250, 14
	v_or_b32_e32 v2, s0, v92
	v_lshlrev_b32_e32 v2, 13, v2
	v_mov_b32_e32 v3, v71
	v_lshl_add_u64 v[2:3], v[10:11], 0, v[2:3]
	s_waitcnt lgkmcnt(0)
	global_store_dwordx4 v[2:3], v[6:9], off nt
	v_add_u32_e32 v2, v96, v85
	ds_read_b128 v[2:5], v2
	v_or_b32_e32 v6, s0, v95
	v_lshlrev_b32_e32 v6, 13, v6
	v_mov_b32_e32 v7, v71
	v_lshl_add_u64 v[12:13], v[10:11], 0, v[6:7]
	v_add_u32_e32 v6, v98, v99
	ds_read_b128 v[6:9], v6
	s_waitcnt lgkmcnt(1)
	global_store_dwordx4 v[12:13], v[2:5], off nt
	v_readlane_b32 s57, v250, 15
	v_readlane_b32 s58, v250, 16
	v_or_b32_e32 v2, s0, v97
	v_lshlrev_b32_e32 v2, 13, v2
	v_mov_b32_e32 v3, v71
	v_lshl_add_u64 v[2:3], v[10:11], 0, v[2:3]
	s_waitcnt lgkmcnt(0)
	global_store_dwordx4 v[2:3], v[6:9], off nt
	v_add_u32_e32 v2, v101, v102
	ds_read_b128 v[2:5], v2
	v_or_b32_e32 v6, s0, v100
	v_lshlrev_b32_e32 v6, 13, v6
	v_mov_b32_e32 v7, v71
	v_lshl_add_u64 v[12:13], v[10:11], 0, v[6:7]
	v_add_u32_e32 v6, v104, v105
	ds_read_b128 v[6:9], v6
	s_waitcnt lgkmcnt(1)
	global_store_dwordx4 v[12:13], v[2:5], off nt
	v_readlane_b32 s59, v250, 17
	v_readlane_b32 s60, v250, 18
	v_or_b32_e32 v2, s0, v103
	v_lshlrev_b32_e32 v2, 13, v2
	v_mov_b32_e32 v3, v71
	v_lshl_add_u64 v[2:3], v[10:11], 0, v[2:3]
	s_waitcnt lgkmcnt(0)
	global_store_dwordx4 v[2:3], v[6:9], off nt
	s_waitcnt lgkmcnt(0)
	v_readlane_b32 s61, v250, 19
	v_readlane_b32 s62, v250, 20
	v_readlane_b32 s63, v250, 21
	v_readlane_b32 s64, v250, 22
	v_readlane_b32 s65, v250, 23

; __device__ __forceinline__ void weights_pass(const Args& a, LAS unsigned char* scr, int gw, int NGW, int lane, int pass) {
;     ...
;     for (int it = gw + (pass == 1 ? PER_LAYER : 0); it < (pass == 2 ? PER_LAYER : 2 * PER_LAYER); it += NGW) {
;         const int l = it / PER_LAYER; int r = it % PER_LAYER;
;         { const bool shared = (r >= I_IN + I_OUT / 2 && r < I_IN + I_OUT) || (r >= I_IN + I_OUT + I_QM && r < I_IN + I_OUT + 3 * I_QM);
;           const int ip = (shared || (l == 0 && r < I_IN)) ? 0 : (l == 0 ? 2 : 1);
;           if (ip != pass) continue; }
;         unsigned char* wl = ws + WS_W + (size_t)l * WL_SIZE;
;         if (r < I_IN) { transpose_item<1>(a.in[I_WIN] + (size_t)l * DM * INW, DM, INW, (bf16_t*)(wl + WL_IN), a.in[I_GMIX] + l * DM, nullptr, 0, scr, r, lane); continue; } r -= I_IN;
;         if (r < I_OUT / 2) { transpose_item<0>(a.in[I_WOUT] + (size_t)l * DM * DM, 2048, DM, (bf16_t*)(wl + WL_OUT), nullptr, nullptr, 0, scr, r, lane, DM); continue; } r -= I_OUT / 2;
;         if (r < I_OUT / 2) { transpose_item<0>(a.in[I_WOUT] + (size_t)l * DM * DM + (size_t)2048 * DM, 2048, DM, (bf16_t*)(ws + WS_WLOW) + (size_t)l * DM * 2048, nullptr, nullptr, 0, scr, r, lane); continue; } r -= I_OUT / 2;
;         if (r < I_QM) { transpose_item<0>(a.in[I_WQM] + (size_t)l * DM * MW, DM, MW, (bf16_t*)(wl + WL_Q), a.in[I_GCROSS] + l * DM, nullptr, 0, scr, r, lane); continue; } r -= I_QM;
;         if (r < I_QM) { transpose_item<1>(a.in[I_WKM] + (size_t)l * DM * MW, DM, MW, (bf16_t*)(ws + WS_WKV) + (size_t)l * 1024 * DM, a.in[I_GMEM] + l * DM, nullptr, 0, scr, r, lane); continue; } r -= I_QM;
;         if (r < I_QM) { transpose_item<1>(a.in[I_WVM] + (size_t)l * DM * MW, DM, MW, (bf16_t*)(ws + WS_WKV) + (size_t)l * 1024 * DM, a.in[I_GMEM] + l * DM, nullptr, 512, scr, r, lane); continue; } r -= I_QM;
;         if (r < I_OMI) { transpose_item<0>(a.in[I_WOM] + (size_t)l * MW * DM, MW, DM, (bf16_t*)(wl + WL_OM), nullptr, nullptr, 0, scr, r, lane); continue; } r -= I_OMI;
;         if (r < I_G) { transpose_item<2>(a.in[I_WGATE] + (size_t)l * DM * DFF, DM, DFF, (bf16_t*)(wl + WL_GU), a.in[I_GFFN] + l * DM, nullptr, 0, scr, r, lane); continue; } r -= I_G;
;         if (r < I_G) { transpose_item<3>(a.in[I_WUP] + (size_t)l * DM * DFF, DM, DFF, (bf16_t*)(wl + WL_GU), a.in[I_GFFN] + l * DM, nullptr, 0, scr, r, lane); continue; } r -= I_G;
.LBB0_625:
	s_mul_hi_i32 s0, s8, 0xbfa02fe9
	s_add_i32 s0, s0, s8
	s_lshr_b32 s1, s0, 31
	s_ashr_i32 s0, s0, 15
	s_add_i32 s0, s0, s1
	s_mul_i32 s1, s0, 0xffff5500
	s_add_i32 s20, s8, s1
	s_add_i32 s21, s20, 0xffffe600
	s_cmpk_gt_u32 s21, 0x7ff
	s_cselect_b64 s[2:3], -1, 0
	s_and_b32 s1, s20, 0xfffffc00
	s_cmpk_lg_i32 s1, 0x2400
	s_cselect_b64 s[4:5], -1, 0
	s_and_b64 s[2:3], s[2:3], s[4:5]
	s_cmp_gt_i32 s8, 0xffff5500
	s_cselect_b64 s[4:5], -1, 0
	s_cmpk_gt_i32 s20, 0x11ff
	s_cselect_b64 s[6:7], -1, 0
	s_and_b64 s[4:5], s[4:5], s[6:7]
	s_and_b64 s[2:3], s[2:3], s[4:5]
	s_andn2_b64 vcc, exec, s[2:3]
	s_cbranch_vccnz .LBB0_624
	s_ashr_i32 s1, s0, 31
	s_mul_i32 s3, s0, 0x15000000
	v_readlane_b32 s4, v251, 12
	s_mul_hi_i32 s2, s0, 0x15000000
	s_add_u32 s18, s4, s3
	v_readlane_b32 s3, v251, 13
	s_addc_u32 s19, s3, s2
	s_cmpk_gt_u32 s20, 0x19ff
	s_mov_b64 s[4:5], -1
	s_cbranch_scc0 .LBB0_666
	s_cmpk_gt_u32 s20, 0x21ff
	s_cbranch_scc0 .LBB0_663
	s_cmpk_gt_u32 s20, 0x23ff
	s_cbranch_scc0 .LBB0_658
	s_cmpk_gt_u32 s20, 0x25ff
	s_cbranch_scc0 .LBB0_653
	s_cmpk_gt_u32 s20, 0x27ff
	s_cbranch_scc0 .LBB0_648
	s_cmpk_gt_u32 s20, 0x29ff
	s_cbranch_scc0 .LBB0_645
	s_cmpk_gt_u32 s20, 0x54ff
	s_mul_hi_i32 s2, s0, 0xac00000
	s_mul_i32 s3, s0, 0xac00000
	s_cbranch_scc0 .LBB0_640
	s_cmpk_gt_u32 s20, 0x7fff
	s_cbranch_scc0 .LBB0_635
	v_readlane_b32 s36, v250, 0
	v_readlane_b32 s42, v250, 6
	v_readlane_b32 s43, v250, 7
	s_add_u32 s6, s42, s3
	s_addc_u32 s7, s43, s2
	s_and_b32 s4, s20, 0xffc0
	s_xor_b32 s5, s4, 0x8000
	s_lshl_b32 s4, s20, 6
	v_lshlrev_b32_e32 v4, 2, v69
	s_and_b32 s4, s4, 0xfc0
	v_lshl_or_b32 v4, s5, 14, v4
	v_mov_b32_e32 v5, v2
	v_lshl_add_u64 v[4:5], s[6:7], 0, v[4:5]
	s_lshl_b32 s14, s4, 2
	v_lshl_add_u64 v[4:5], v[4:5], 0, s[14:15]
	v_lshlrev_b32_e32 v6, 2, v68
	v_mov_b32_e32 v7, v2
	v_lshl_add_u64 v[60:61], v[4:5], 0, v[6:7]
	s_movk_i32 s6, 0x4000
	v_add_co_u32_e32 v8, vcc, s6, v60
	s_mov_b32 s6, 0x24000
	s_nop 0
	v_addc_co_u32_e32 v9, vcc, 0, v61, vcc
	global_load_dwordx4 v[4:7], v[60:61], off nt
	s_nop 0
	global_load_dwordx4 v[8:11], v[8:9], off nt
	v_add_co_u32_e32 v12, vcc, s22, v60
	s_lshl_b32 s5, s5, 1
	s_nop 0
	v_addc_co_u32_e32 v13, vcc, 0, v61, vcc
	v_add_co_u32_e32 v16, vcc, s6, v60
	s_mov_b32 s6, 0x40000
	s_nop 0
	v_addc_co_u32_e32 v17, vcc, 0, v61, vcc
	global_load_dwordx4 v[12:15], v[12:13], off nt
	s_nop 0
	global_load_dwordx4 v[16:19], v[16:17], off nt
	v_add_co_u32_e32 v20, vcc, s6, v60
	s_mov_b32 s6, 0x44000
	s_nop 0
	v_addc_co_u32_e32 v21, vcc, 0, v61, vcc
	v_add_co_u32_e32 v24, vcc, s6, v60
	s_mov_b32 s6, 0x60000
	s_nop 0
	v_addc_co_u32_e32 v25, vcc, 0, v61, vcc
	global_load_dwordx4 v[20:23], v[20:21], off nt
	s_nop 0
	global_load_dwordx4 v[24:27], v[24:25], off nt
	v_add_co_u32_e32 v28, vcc, s6, v60
	s_mov_b32 s6, 0x64000
	s_nop 0
	v_addc_co_u32_e32 v29, vcc, 0, v61, vcc
	v_add_co_u32_e32 v32, vcc, s6, v60
	s_mov_b32 s6, 0x80000
	s_nop 0
	v_addc_co_u32_e32 v33, vcc, 0, v61, vcc
	global_load_dwordx4 v[28:31], v[28:29], off nt
	s_nop 0
	global_load_dwordx4 v[32:35], v[32:33], off nt
	v_add_co_u32_e32 v36, vcc, s6, v60
	s_mov_b32 s6, 0x84000
	s_nop 0
	v_addc_co_u32_e32 v37, vcc, 0, v61, vcc
	v_add_co_u32_e32 v40, vcc, s6, v60
	s_mov_b32 s6, 0xa0000
	s_nop 0
	v_addc_co_u32_e32 v41, vcc, 0, v61, vcc
	global_load_dwordx4 v[36:39], v[36:37], off nt
	s_nop 0
	global_load_dwordx4 v[40:43], v[40:41], off nt
	v_add_co_u32_e32 v44, vcc, s6, v60
	s_mov_b32 s6, 0xa4000
	s_nop 0
	v_addc_co_u32_e32 v45, vcc, 0, v61, vcc
	v_add_co_u32_e32 v48, vcc, s6, v60
	s_mov_b32 s6, 0xc0000
	s_nop 0
	v_addc_co_u32_e32 v49, vcc, 0, v61, vcc
	global_load_dwordx4 v[44:47], v[44:45], off nt
	s_nop 0
	global_load_dwordx4 v[48:51], v[48:49], off nt
	v_add_co_u32_e32 v52, vcc, s6, v60
	s_mov_b32 s6, 0xc4000
	s_nop 0
	v_addc_co_u32_e32 v53, vcc, 0, v61, vcc
	v_add_co_u32_e32 v56, vcc, s6, v60
	s_mov_b32 s6, 0xe0000
	s_nop 0
	v_addc_co_u32_e32 v57, vcc, 0, v61, vcc
	global_load_dwordx4 v[52:55], v[52:53], off nt
	s_nop 0
	global_load_dwordx4 v[56:59], v[56:57], off nt
	v_add_co_u32_e32 v62, vcc, s6, v60
	s_mov_b32 s6, 0xe4000
	s_nop 0
	v_addc_co_u32_e32 v63, vcc, 0, v61, vcc
	v_add_co_u32_e32 v64, vcc, s6, v60
	s_add_u32 s6, s18, s5
	s_nop 0
	v_addc_co_u32_e32 v65, vcc, 0, v61, vcc
	global_load_dwordx4 v[60:63], v[62:63], off nt
	s_nop 0
	global_load_dwordx4 v[64:67], v[64:65], off nt
	s_waitcnt vmcnt(0)
; #define LAS __attribute__((address_space(3)))
; #define LDS_WAIT() asm volatile("s_waitcnt lgkmcnt(0)" ::: "memory")
; __device__ __forceinline__ unsigned cvt_pk_bf16(float lo, float hi) { unsigned r; asm volatile("v_cvt_pk_bf16_f32 %0, %1, %2" : "=v"(r) : "v"(lo), "v"(hi)); return r; }
;     ...
; #pragma unroll
;     for (int i = 0; i < 8; ++i)
; #pragma unroll
;         for (int e = 0; e < 4; ++e) *(LAS unsigned*)(scr + (4 * r16 + e) * 128 + ((i ^ (r16 & 7)) * 16) + q * 4) = cvt_pk_bf16(v[2 * i][e], v[2 * i + 1][e]);
;     LDS_WAIT(); asm volatile("" ::: "memory");
;     const int c = lane & 7;
; #pragma unroll
;     for (int j = 0; j < 8; ++j) { const int row = (lane >> 3) + 8 * j; const u32x4 o = *(const LAS u32x4*)(scr + row * 128 + ((c ^ ((row >> 2) & 7)) * 16));
;         const int lc = col_off + n0 + row; int dr;
;         if (MODE == 0) dr = lc;
;         else if (MODE == 1) dr = (lc & ~255) + 128 * ((lc >> 5) & 1) + 32 * ((lc >> 6) & 3) + (lc & 31);
;         else if (MODE == 2) dr = 256 * (lc >> 7) + (lc & 127);
;         else dr = 256 * (lc >> 7) + 128 + (lc & 127);
;         *(u32x4*)(WT + (size_t)dr * (ldt ? ldt : K) + k0 + 8 * c) = o; }
;     LDS_WAIT(); asm volatile("" ::: "memory");
; __device__ __forceinline__ void weights_pass(const Args& a, LAS unsigned char* scr, int gw, int NGW, int lane, int pass) {
;     ...
;         transpose_item<0>(a.in[I_WDOWN] + (size_t)l * DFF * DM, DFF, DM, (bf16_t*)(wl + WL_D), nullptr, nullptr, 0, scr, r, lane);
	v_cvt_pk_bf16_f32 v4, v4, v8
	v_add_u32_e32 v8, v71, v73
	ds_write_b32 v8, v4
	v_cvt_pk_bf16_f32 v4, v5, v9
	ds_write_b32 v8, v4 offset:128
	v_cvt_pk_bf16_f32 v4, v6, v10
	ds_write_b32 v8, v4 offset:256
	v_cvt_pk_bf16_f32 v4, v7, v11
	ds_write_b32 v8, v4 offset:384
	v_cvt_pk_bf16_f32 v4, v12, v16
	v_add_u32_e32 v5, v74, v73
	ds_write_b32 v5, v4
	v_cvt_pk_bf16_f32 v4, v13, v17
	ds_write_b32 v5, v4 offset:128
	v_cvt_pk_bf16_f32 v4, v14, v18
	ds_write_b32 v5, v4 offset:256
	v_cvt_pk_bf16_f32 v4, v15, v19
	ds_write_b32 v5, v4 offset:384
	v_cvt_pk_bf16_f32 v4, v20, v24
	v_add_u32_e32 v5, v75, v73
	ds_write_b32 v5, v4
	v_cvt_pk_bf16_f32 v4, v21, v25
	ds_write_b32 v5, v4 offset:128
	v_cvt_pk_bf16_f32 v4, v22, v26
	ds_write_b32 v5, v4 offset:256
	v_cvt_pk_bf16_f32 v4, v23, v27
	ds_write_b32 v5, v4 offset:384
	v_cvt_pk_bf16_f32 v4, v28, v32
	v_add_u32_e32 v5, v76, v73
	ds_write_b32 v5, v4
	v_cvt_pk_bf16_f32 v4, v29, v33
	ds_write_b32 v5, v4 offset:128
	v_cvt_pk_bf16_f32 v4, v30, v34
	ds_write_b32 v5, v4 offset:256
	v_cvt_pk_bf16_f32 v4, v31, v35
	ds_write_b32 v5, v4 offset:384
	v_cvt_pk_bf16_f32 v4, v36, v40
	v_add_u32_e32 v5, v77, v73
	ds_write_b32 v5, v4
	v_cvt_pk_bf16_f32 v4, v37, v41
	ds_write_b32 v5, v4 offset:128
	v_cvt_pk_bf16_f32 v4, v38, v42
	ds_write_b32 v5, v4 offset:256
	v_cvt_pk_bf16_f32 v4, v39, v43
	ds_write_b32 v5, v4 offset:384
	v_cvt_pk_bf16_f32 v4, v44, v48
	v_add_u32_e32 v5, v78, v73
	ds_write_b32 v5, v4
	v_cvt_pk_bf16_f32 v4, v45, v49
	ds_write_b32 v5, v4 offset:128
	v_cvt_pk_bf16_f32 v4, v46, v50
	ds_write_b32 v5, v4 offset:256
	v_cvt_pk_bf16_f32 v4, v47, v51
	ds_write_b32 v5, v4 offset:384
	v_cvt_pk_bf16_f32 v4, v52, v56
	v_add_u32_e32 v5, v79, v73
	ds_write_b32 v5, v4
	v_cvt_pk_bf16_f32 v4, v53, v57
	ds_write_b32 v5, v4 offset:128
	v_cvt_pk_bf16_f32 v4, v54, v58
	ds_write_b32 v5, v4 offset:256
	v_cvt_pk_bf16_f32 v4, v55, v59
	ds_write_b32 v5, v4 offset:384
	v_cvt_pk_bf16_f32 v4, v60, v64
	v_add_u32_e32 v5, v80, v73
	ds_write_b32 v5, v4
	v_cvt_pk_bf16_f32 v4, v61, v65
	ds_write_b32 v5, v4 offset:128
	v_cvt_pk_bf16_f32 v4, v62, v66
	ds_write_b32 v5, v4 offset:256
	v_cvt_pk_bf16_f32 v4, v63, v67
	ds_write_b32 v5, v4 offset:384
	s_addc_u32 s7, s19, 0
	v_lshlrev_b32_e32 v4, 1, v70
	v_mov_b32_e32 v5, v2
	s_waitcnt lgkmcnt(0)
	v_lshl_add_u64 v[4:5], s[6:7], 0, v[4:5]
	s_mov_b64 s[6:7], 0xfa00000
	v_lshl_add_u64 v[12:13], v[4:5], 0, s[6:7]
	v_add_u32_e32 v4, v82, v83
	ds_read_b128 v[4:7], v4
	v_or_b32_e32 v8, s4, v81
	v_mul_u32_u24_e32 v8, 0x2b00, v8
	v_lshlrev_b32_e32 v8, 1, v8
	v_mov_b32_e32 v9, v2
	v_lshl_add_u64 v[14:15], v[12:13], 0, v[8:9]
	v_add_u32_e32 v8, v85, v86
	ds_read_b128 v[8:11], v8
	s_waitcnt lgkmcnt(1)
	global_store_dwordx4 v[14:15], v[4:7], off nt
	v_readlane_b32 s37, v250, 1
	v_readlane_b32 s38, v250, 2
	v_or_b32_e32 v4, s4, v84
	v_mul_u32_u24_e32 v4, 0x2b00, v4
	v_lshlrev_b32_e32 v4, 1, v4
	v_mov_b32_e32 v5, v2
	v_lshl_add_u64 v[4:5], v[12:13], 0, v[4:5]
	s_waitcnt lgkmcnt(0)
	global_store_dwordx4 v[4:5], v[8:11], off nt
	v_add_u32_e32 v4, v88, v89
	ds_read_b128 v[4:7], v4
	v_or_b32_e32 v8, s4, v87
	v_mul_u32_u24_e32 v8, 0x2b00, v8
	v_lshlrev_b32_e32 v8, 1, v8
	v_mov_b32_e32 v9, v2
	v_lshl_add_u64 v[14:15], v[12:13], 0, v[8:9]
	v_add_u32_e32 v8, v91, v92
	ds_read_b128 v[8:11], v8
	s_waitcnt lgkmcnt(1)
	global_store_dwordx4 v[14:15], v[4:7], off nt
	v_readlane_b32 s39, v250, 3
	v_readlane_b32 s40, v250, 4
	v_or_b32_e32 v4, s4, v90
	v_mul_u32_u24_e32 v4, 0x2b00, v4
	v_lshlrev_b32_e32 v4, 1, v4
	v_mov_b32_e32 v5, v2
	v_lshl_add_u64 v[4:5], v[12:13], 0, v[4:5]
	s_waitcnt lgkmcnt(0)
	global_store_dwordx4 v[4:5], v[8:11], off nt
	v_add_u32_e32 v4, v94, v83
	ds_read_b128 v[4:7], v4
	v_or_b32_e32 v8, s4, v93
	v_mul_u32_u24_e32 v8, 0x2b00, v8
	v_lshlrev_b32_e32 v8, 1, v8
	v_mov_b32_e32 v9, v2
	v_lshl_add_u64 v[14:15], v[12:13], 0, v[8:9]
	v_add_u32_e32 v8, v96, v97
	ds_read_b128 v[8:11], v8
	s_waitcnt lgkmcnt(1)
	global_store_dwordx4 v[14:15], v[4:7], off nt
	v_readlane_b32 s41, v250, 5
	s_nop 0
	v_or_b32_e32 v4, s4, v95
	v_mul_u32_u24_e32 v4, 0x2b00, v4
	v_lshlrev_b32_e32 v4, 1, v4
	v_mov_b32_e32 v5, v2
	v_lshl_add_u64 v[4:5], v[12:13], 0, v[4:5]
	s_waitcnt lgkmcnt(0)
	global_store_dwordx4 v[4:5], v[8:11], off nt
	v_add_u32_e32 v4, v99, v100
	ds_read_b128 v[4:7], v4
	v_or_b32_e32 v8, s4, v98
	v_mul_u32_u24_e32 v8, 0x2b00, v8
	v_lshlrev_b32_e32 v8, 1, v8
	v_mov_b32_e32 v9, v2
	v_lshl_add_u64 v[14:15], v[12:13], 0, v[8:9]
	v_add_u32_e32 v8, v102, v103
	ds_read_b128 v[8:11], v8
	s_waitcnt lgkmcnt(1)
	global_store_dwordx4 v[14:15], v[4:7], off nt
	s_nop 1
	v_or_b32_e32 v4, s4, v101
	v_mul_u32_u24_e32 v4, 0x2b00, v4
	v_lshlrev_b32_e32 v4, 1, v4
	v_mov_b32_e32 v5, v2
	v_lshl_add_u64 v[4:5], v[12:13], 0, v[4:5]
	s_waitcnt lgkmcnt(0)
	global_store_dwordx4 v[4:5], v[8:11], off nt
	s_waitcnt lgkmcnt(0)
	s_mov_b64 s[4:5], 0

; #define LAS __attribute__((address_space(3)))
; #define LDS_WAIT() asm volatile("s_waitcnt lgkmcnt(0)" ::: "memory")
; __device__ __forceinline__ unsigned cvt_pk_bf16(float lo, float hi) { unsigned r; asm volatile("v_cvt_pk_bf16_f32 %0, %1, %2" : "=v"(r) : "v"(lo), "v"(hi)); return r; }
;     ...
; #pragma unroll
;     for (int i = 0; i < 8; ++i)
; #pragma unroll
;         for (int e = 0; e < 4; ++e) *(LAS unsigned*)(scr + (4 * r16 + e) * 128 + ((i ^ (r16 & 7)) * 16) + q * 4) = cvt_pk_bf16(v[2 * i][e], v[2 * i + 1][e]);
;     LDS_WAIT(); asm volatile("" ::: "memory");
;     const int c = lane & 7;
; #pragma unroll
;     for (int j = 0; j < 8; ++j) { const int row = (lane >> 3) + 8 * j; const u32x4 o = *(const LAS u32x4*)(scr + row * 128 + ((c ^ ((row >> 2) & 7)) * 16));
;         const int lc = col_off + n0 + row; int dr;
;         if (MODE == 0) dr = lc;
;         else if (MODE == 1) dr = (lc & ~255) + 128 * ((lc >> 5) & 1) + 32 * ((lc >> 6) & 3) + (lc & 31);
;         else if (MODE == 2) dr = 256 * (lc >> 7) + (lc & 127);
;         else dr = 256 * (lc >> 7) + 128 + (lc & 127);
;         *(u32x4*)(WT + (size_t)dr * (ldt ? ldt : K) + k0 + 8 * c) = o; }
;     LDS_WAIT(); asm volatile("" ::: "memory");
; __device__ __forceinline__ void weights_pass(const Args& a, LAS unsigned char* scr, int gw, int NGW, int lane, int pass) {
;     ...
;         if (r < I_G) { transpose_item<3>(a.in[I_WUP] + (size_t)l * DM * DFF, DM, DFF, (bf16_t*)(wl + WL_GU), a.in[I_GFFN] + l * DM, nullptr, 0, scr, r, lane); continue; } r -= I_G;
.LBB0_638:
	s_waitcnt vmcnt(0)
	v_cvt_pk_bf16_f32 v60, v60, v64
	v_add_u32_e32 v64, v71, v73
	ds_write_b32 v64, v60
	v_cvt_pk_bf16_f32 v60, v61, v65
	ds_write_b32 v64, v60 offset:128
	v_cvt_pk_bf16_f32 v60, v62, v66
	ds_write_b32 v64, v60 offset:256
	v_cvt_pk_bf16_f32 v60, v63, v67
	ds_write_b32 v64, v60 offset:384
	v_cvt_pk_bf16_f32 v52, v52, v56
	v_add_u32_e32 v56, v74, v73
	ds_write_b32 v56, v52
	v_cvt_pk_bf16_f32 v52, v53, v57
	ds_write_b32 v56, v52 offset:128
	v_cvt_pk_bf16_f32 v52, v54, v58
	ds_write_b32 v56, v52 offset:256
	v_cvt_pk_bf16_f32 v52, v55, v59
	ds_write_b32 v56, v52 offset:384
	v_cvt_pk_bf16_f32 v44, v44, v48
	v_add_u32_e32 v48, v75, v73
	ds_write_b32 v48, v44
	v_cvt_pk_bf16_f32 v44, v45, v49
	ds_write_b32 v48, v44 offset:128
	v_cvt_pk_bf16_f32 v44, v46, v50
	ds_write_b32 v48, v44 offset:256
	v_cvt_pk_bf16_f32 v44, v47, v51
	ds_write_b32 v48, v44 offset:384
	v_cvt_pk_bf16_f32 v36, v36, v40
	v_add_u32_e32 v40, v76, v73
	ds_write_b32 v40, v36
	v_cvt_pk_bf16_f32 v36, v37, v41
	ds_write_b32 v40, v36 offset:128
	v_cvt_pk_bf16_f32 v36, v38, v42
	ds_write_b32 v40, v36 offset:256
	v_cvt_pk_bf16_f32 v36, v39, v43
	ds_write_b32 v40, v36 offset:384
	v_cvt_pk_bf16_f32 v20, v20, v32
	v_add_u32_e32 v32, v77, v73
	ds_write_b32 v32, v20
	v_cvt_pk_bf16_f32 v20, v21, v33
	ds_write_b32 v32, v20 offset:128
	v_cvt_pk_bf16_f32 v20, v22, v34
	ds_write_b32 v32, v20 offset:256
	v_cvt_pk_bf16_f32 v20, v23, v35
	ds_write_b32 v32, v20 offset:384
	v_cvt_pk_bf16_f32 v16, v16, v28
	v_add_u32_e32 v20, v78, v73
	ds_write_b32 v20, v16
	v_cvt_pk_bf16_f32 v16, v17, v29
	ds_write_b32 v20, v16 offset:128
	v_cvt_pk_bf16_f32 v16, v18, v30
	ds_write_b32 v20, v16 offset:256
	v_cvt_pk_bf16_f32 v16, v19, v31
	ds_write_b32 v20, v16 offset:384
	v_cvt_pk_bf16_f32 v8, v8, v24
	v_add_u32_e32 v16, v79, v73
	ds_write_b32 v16, v8
	v_cvt_pk_bf16_f32 v8, v9, v25
	ds_write_b32 v16, v8 offset:128
	v_cvt_pk_bf16_f32 v8, v10, v26
	ds_write_b32 v16, v8 offset:256
	v_cvt_pk_bf16_f32 v8, v11, v27
	s_lshl_b32 s4, s7, 6
	ds_write_b32 v16, v8 offset:384
	v_cvt_pk_bf16_f32 v4, v4, v12
	v_add_u32_e32 v8, v80, v73
	ds_write_b32 v8, v4
	v_cvt_pk_bf16_f32 v4, v5, v13
	s_lshl_b32 s5, s7, 7
	s_and_b32 s4, s4, 64
	ds_write_b32 v8, v4 offset:128
	v_cvt_pk_bf16_f32 v4, v6, v14
	s_or_b32 s7, s4, s5
	s_lshl_b32 s4, s6, 1
	ds_write_b32 v8, v4 offset:256
	v_cvt_pk_bf16_f32 v4, v7, v15
	s_add_u32 s4, s18, s4
	ds_write_b32 v8, v4 offset:384
	s_addc_u32 s5, s19, 0
	v_lshlrev_b32_e32 v4, 1, v70
	v_mov_b32_e32 v5, v2
	s_waitcnt lgkmcnt(0)
	v_lshl_add_u64 v[4:5], s[4:5], 0, v[4:5]
	s_mov_b64 s[4:5], 0x4e00000
	v_lshl_add_u64 v[12:13], v[4:5], 0, s[4:5]
	v_add_u32_e32 v4, v82, v83
	ds_read_b128 v[4:7], v4
	v_or_b32_e32 v8, s7, v81
	v_mov_b32_e32 v16, 0x100000
	v_lshl_or_b32 v8, v8, 13, v16
	v_mov_b32_e32 v9, v2
	v_lshl_add_u64 v[14:15], v[12:13], 0, v[8:9]
	v_add_u32_e32 v8, v85, v86
	ds_read_b128 v[8:11], v8
	s_waitcnt lgkmcnt(1)
	global_store_dwordx4 v[14:15], v[4:7], off nt
	s_nop 1
	v_or_b32_e32 v4, s7, v84
	v_lshl_or_b32 v4, v4, 13, v16
	v_mov_b32_e32 v5, v2
	v_lshl_add_u64 v[4:5], v[12:13], 0, v[4:5]
	s_waitcnt lgkmcnt(0)
	global_store_dwordx4 v[4:5], v[8:11], off nt
	v_add_u32_e32 v4, v88, v89
	ds_read_b128 v[4:7], v4
	v_or_b32_e32 v8, s7, v87
	v_lshl_or_b32 v8, v8, 13, v16
	v_mov_b32_e32 v9, v2
	v_lshl_add_u64 v[14:15], v[12:13], 0, v[8:9]
	v_add_u32_e32 v8, v91, v92
	ds_read_b128 v[8:11], v8
	s_waitcnt lgkmcnt(1)
	global_store_dwordx4 v[14:15], v[4:7], off nt
	s_nop 1
	v_or_b32_e32 v4, s7, v90
	v_lshl_or_b32 v4, v4, 13, v16
	v_mov_b32_e32 v5, v2
	v_lshl_add_u64 v[4:5], v[12:13], 0, v[4:5]
	s_waitcnt lgkmcnt(0)
	global_store_dwordx4 v[4:5], v[8:11], off nt
	v_add_u32_e32 v4, v94, v83
	ds_read_b128 v[4:7], v4
	v_or_b32_e32 v8, s7, v93
	v_lshl_or_b32 v8, v8, 13, v16
	v_mov_b32_e32 v9, v2
	v_lshl_add_u64 v[14:15], v[12:13], 0, v[8:9]
	v_add_u32_e32 v8, v96, v97
	ds_read_b128 v[8:11], v8
	s_waitcnt lgkmcnt(1)
	global_store_dwordx4 v[14:15], v[4:7], off nt
	s_nop 1
	v_or_b32_e32 v4, s7, v95
	v_lshl_or_b32 v4, v4, 13, v16
	v_mov_b32_e32 v5, v2
	v_lshl_add_u64 v[4:5], v[12:13], 0, v[4:5]
	s_waitcnt lgkmcnt(0)
	global_store_dwordx4 v[4:5], v[8:11], off nt
	v_add_u32_e32 v4, v99, v100
	ds_read_b128 v[4:7], v4
	v_or_b32_e32 v8, s7, v98
	v_lshl_or_b32 v8, v8, 13, v16
	v_mov_b32_e32 v9, v2
	v_lshl_add_u64 v[14:15], v[12:13], 0, v[8:9]
	v_add_u32_e32 v8, v102, v103
	ds_read_b128 v[8:11], v8
	s_waitcnt lgkmcnt(1)
	global_store_dwordx4 v[14:15], v[4:7], off nt
	s_nop 1
	v_or_b32_e32 v4, s7, v101
	v_lshl_or_b32 v4, v4, 13, v16
	v_mov_b32_e32 v5, v2
	v_lshl_add_u64 v[4:5], v[12:13], 0, v[4:5]
	s_waitcnt lgkmcnt(0)
	global_store_dwordx4 v[4:5], v[8:11], off nt
	s_waitcnt lgkmcnt(0)

; #define LAS __attribute__((address_space(3)))
; #define LDS_WAIT() asm volatile("s_waitcnt lgkmcnt(0)" ::: "memory")
; __device__ __forceinline__ unsigned cvt_pk_bf16(float lo, float hi) { unsigned r; asm volatile("v_cvt_pk_bf16_f32 %0, %1, %2" : "=v"(r) : "v"(lo), "v"(hi)); return r; }
;     ...
; #pragma unroll
;     for (int i = 0; i < 8; ++i)
; #pragma unroll
;         for (int e = 0; e < 4; ++e) *(LAS unsigned*)(scr + (4 * r16 + e) * 128 + ((i ^ (r16 & 7)) * 16) + q * 4) = cvt_pk_bf16(v[2 * i][e], v[2 * i + 1][e]);
;     LDS_WAIT(); asm volatile("" ::: "memory");
;     const int c = lane & 7;
; #pragma unroll
;     for (int j = 0; j < 8; ++j) { const int row = (lane >> 3) + 8 * j; const u32x4 o = *(const LAS u32x4*)(scr + row * 128 + ((c ^ ((row >> 2) & 7)) * 16));
;         const int lc = col_off + n0 + row; int dr;
;         if (MODE == 0) dr = lc;
;         else if (MODE == 1) dr = (lc & ~255) + 128 * ((lc >> 5) & 1) + 32 * ((lc >> 6) & 3) + (lc & 31);
;         else if (MODE == 2) dr = 256 * (lc >> 7) + (lc & 127);
;         else dr = 256 * (lc >> 7) + 128 + (lc & 127);
;         *(u32x4*)(WT + (size_t)dr * (ldt ? ldt : K) + k0 + 8 * c) = o; }
;     LDS_WAIT(); asm volatile("" ::: "memory");
; __device__ __forceinline__ void weights_pass(const Args& a, LAS unsigned char* scr, int gw, int NGW, int lane, int pass) {
;     ...
;         if (r < I_G) { transpose_item<2>(a.in[I_WGATE] + (size_t)l * DM * DFF, DM, DFF, (bf16_t*)(wl + WL_GU), a.in[I_GFFN] + l * DM, nullptr, 0, scr, r, lane); continue; } r -= I_G;
.LBB0_643:
	s_waitcnt vmcnt(0)
	v_cvt_pk_bf16_f32 v60, v60, v64
	v_add_u32_e32 v64, v71, v73
	ds_write_b32 v64, v60
	v_cvt_pk_bf16_f32 v60, v61, v65
	ds_write_b32 v64, v60 offset:128
	v_cvt_pk_bf16_f32 v60, v62, v66
	ds_write_b32 v64, v60 offset:256
	v_cvt_pk_bf16_f32 v60, v63, v67
	ds_write_b32 v64, v60 offset:384
	v_cvt_pk_bf16_f32 v52, v52, v56
	v_add_u32_e32 v56, v74, v73
	ds_write_b32 v56, v52
	v_cvt_pk_bf16_f32 v52, v53, v57
	ds_write_b32 v56, v52 offset:128
	v_cvt_pk_bf16_f32 v52, v54, v58
	ds_write_b32 v56, v52 offset:256
	v_cvt_pk_bf16_f32 v52, v55, v59
	ds_write_b32 v56, v52 offset:384
	v_cvt_pk_bf16_f32 v44, v44, v48
	v_add_u32_e32 v48, v75, v73
	ds_write_b32 v48, v44
	v_cvt_pk_bf16_f32 v44, v45, v49
	ds_write_b32 v48, v44 offset:128
	v_cvt_pk_bf16_f32 v44, v46, v50
	ds_write_b32 v48, v44 offset:256
	v_cvt_pk_bf16_f32 v44, v47, v51
	ds_write_b32 v48, v44 offset:384
	v_cvt_pk_bf16_f32 v36, v36, v40
	v_add_u32_e32 v40, v76, v73
	ds_write_b32 v40, v36
	v_cvt_pk_bf16_f32 v36, v37, v41
	ds_write_b32 v40, v36 offset:128
	v_cvt_pk_bf16_f32 v36, v38, v42
	ds_write_b32 v40, v36 offset:256
	v_cvt_pk_bf16_f32 v36, v39, v43
	ds_write_b32 v40, v36 offset:384
	v_cvt_pk_bf16_f32 v20, v20, v32
	v_add_u32_e32 v32, v77, v73
	ds_write_b32 v32, v20
	v_cvt_pk_bf16_f32 v20, v21, v33
	ds_write_b32 v32, v20 offset:128
	v_cvt_pk_bf16_f32 v20, v22, v34
	ds_write_b32 v32, v20 offset:256
	v_cvt_pk_bf16_f32 v20, v23, v35
	ds_write_b32 v32, v20 offset:384
	v_cvt_pk_bf16_f32 v16, v16, v28
	v_add_u32_e32 v20, v78, v73
	ds_write_b32 v20, v16
	v_cvt_pk_bf16_f32 v16, v17, v29
	ds_write_b32 v20, v16 offset:128
	v_cvt_pk_bf16_f32 v16, v18, v30
	ds_write_b32 v20, v16 offset:256
	v_cvt_pk_bf16_f32 v16, v19, v31
	ds_write_b32 v20, v16 offset:384
	v_cvt_pk_bf16_f32 v8, v8, v24
	v_add_u32_e32 v16, v79, v73
	ds_write_b32 v16, v8
	v_cvt_pk_bf16_f32 v8, v9, v25
	ds_write_b32 v16, v8 offset:128
	v_cvt_pk_bf16_f32 v8, v10, v26
	ds_write_b32 v16, v8 offset:256
	v_cvt_pk_bf16_f32 v8, v11, v27
	s_lshl_b32 s4, s3, 6
	ds_write_b32 v16, v8 offset:384
	v_cvt_pk_bf16_f32 v4, v4, v12
	v_add_u32_e32 v8, v80, v73
	s_lshl_b32 s3, s3, 7
	ds_write_b32 v8, v4
	v_cvt_pk_bf16_f32 v4, v5, v13
	s_and_b32 s3, s3, 0x7f00
	s_and_b32 s4, s4, 64
	ds_write_b32 v8, v4 offset:128
	v_cvt_pk_bf16_f32 v4, v6, v14
	s_or_b32 s4, s4, s3
	s_lshl_b32 s2, s2, 1
	ds_write_b32 v8, v4 offset:256
	v_cvt_pk_bf16_f32 v4, v7, v15
	s_add_u32 s2, s18, s2
	ds_write_b32 v8, v4 offset:384
	s_addc_u32 s3, s19, 0
	v_lshlrev_b32_e32 v4, 1, v70
	v_mov_b32_e32 v5, v2
	s_waitcnt lgkmcnt(0)
	v_lshl_add_u64 v[4:5], s[2:3], 0, v[4:5]
	s_mov_b64 s[2:3], 0x4e00000
	v_lshl_add_u64 v[12:13], v[4:5], 0, s[2:3]
	v_add_u32_e32 v4, v82, v83
	ds_read_b128 v[4:7], v4
	v_or_b32_e32 v8, s4, v81
	v_lshlrev_b32_e32 v8, 13, v8
	v_mov_b32_e32 v9, v2
	v_lshl_add_u64 v[14:15], v[12:13], 0, v[8:9]
	v_add_u32_e32 v8, v85, v86
	ds_read_b128 v[8:11], v8
	s_waitcnt lgkmcnt(1)
	global_store_dwordx4 v[14:15], v[4:7], off nt
	s_nop 1
	v_or_b32_e32 v4, s4, v84
	v_lshlrev_b32_e32 v4, 13, v4
	v_mov_b32_e32 v5, v2
	v_lshl_add_u64 v[4:5], v[12:13], 0, v[4:5]
	s_waitcnt lgkmcnt(0)
	global_store_dwordx4 v[4:5], v[8:11], off nt
	v_add_u32_e32 v4, v88, v89
	ds_read_b128 v[4:7], v4
	v_or_b32_e32 v8, s4, v87
	v_lshlrev_b32_e32 v8, 13, v8
	v_mov_b32_e32 v9, v2
	v_lshl_add_u64 v[14:15], v[12:13], 0, v[8:9]
	v_add_u32_e32 v8, v91, v92
	ds_read_b128 v[8:11], v8
	s_waitcnt lgkmcnt(1)
	global_store_dwordx4 v[14:15], v[4:7], off nt
	s_nop 1
	v_or_b32_e32 v4, s4, v90
	v_lshlrev_b32_e32 v4, 13, v4
	v_mov_b32_e32 v5, v2
	v_lshl_add_u64 v[4:5], v[12:13], 0, v[4:5]
	s_waitcnt lgkmcnt(0)
	global_store_dwordx4 v[4:5], v[8:11], off nt
	v_add_u32_e32 v4, v94, v83
	ds_read_b128 v[4:7], v4
	v_or_b32_e32 v8, s4, v93
	v_lshlrev_b32_e32 v8, 13, v8
	v_mov_b32_e32 v9, v2
	v_lshl_add_u64 v[14:15], v[12:13], 0, v[8:9]
	v_add_u32_e32 v8, v96, v97
	ds_read_b128 v[8:11], v8
	s_waitcnt lgkmcnt(1)
	global_store_dwordx4 v[14:15], v[4:7], off nt
	s_nop 1
	v_or_b32_e32 v4, s4, v95
	v_lshlrev_b32_e32 v4, 13, v4
	v_mov_b32_e32 v5, v2
	v_lshl_add_u64 v[4:5], v[12:13], 0, v[4:5]
	s_waitcnt lgkmcnt(0)
	global_store_dwordx4 v[4:5], v[8:11], off nt
	v_add_u32_e32 v4, v99, v100
	ds_read_b128 v[4:7], v4
	v_or_b32_e32 v8, s4, v98
	v_lshlrev_b32_e32 v8, 13, v8
	v_mov_b32_e32 v9, v2
	v_lshl_add_u64 v[14:15], v[12:13], 0, v[8:9]
	v_add_u32_e32 v8, v102, v103
	ds_read_b128 v[8:11], v8
	s_waitcnt lgkmcnt(1)
	global_store_dwordx4 v[14:15], v[4:7], off nt
	s_nop 1
	v_or_b32_e32 v4, s4, v101
	v_lshlrev_b32_e32 v4, 13, v4
	v_mov_b32_e32 v5, v2
	v_lshl_add_u64 v[4:5], v[12:13], 0, v[4:5]
	s_waitcnt lgkmcnt(0)
	global_store_dwordx4 v[4:5], v[8:11], off nt
	s_waitcnt lgkmcnt(0)

;     const int nblk = N / 64, kb = item / nblk, nb = item % nblk, k0 = 64 * kb, n0 = 64 * nb;
;     const int r16 = lane & 15, q = lane >> 4;
;     const float* src = W + (size_t)(k0 + 2 * q) * N + n0 + 4 * r16;
;     f32x4 v[16];
; #pragma unroll
;     for (int j = 0; j < 16; ++j) v[j] = *(const f32x4*)(src + (size_t)(8 * (j >> 1) + (j & 1)) * N);
; __device__ __forceinline__ void weights_pass(const Args& a, LAS unsigned char* scr, int gw, int NGW, int lane, int pass) {
;     ...
;         if (r < I_OMI) { transpose_item<0>(a.in[I_WOM] + (size_t)l * MW * DM, MW, DM, (bf16_t*)(wl + WL_OM), nullptr, nullptr, 0, scr, r, lane); continue; } r -= I_OMI;
.LBB0_645:
	s_andn2_b64 vcc, exec, s[4:5]
	s_cbranch_vccnz .LBB0_647
	v_readlane_b32 s36, v250, 46
	s_lshl_b64 s[2:3], s[0:1], 23
	v_readlane_b32 s50, v250, 60
	v_readlane_b32 s51, v250, 61
	s_add_u32 s4, s50, s2
	s_addc_u32 s5, s51, s3
	s_add_i32 s2, s20, 0xd800
	s_and_b32 s3, s2, 0xffc0
	s_lshl_b32 s2, s20, 6
	v_lshlrev_b32_e32 v4, 2, v69
	s_and_b32 s2, s2, 0xfc0
	v_lshl_or_b32 v4, s3, 14, v4
	v_mov_b32_e32 v5, v2
	v_lshl_add_u64 v[4:5], s[4:5], 0, v[4:5]
	s_lshl_b32 s14, s2, 2
	v_lshl_add_u64 v[4:5], v[4:5], 0, s[14:15]
	v_lshlrev_b32_e32 v6, 2, v68
	v_mov_b32_e32 v7, v2
	v_lshl_add_u64 v[60:61], v[4:5], 0, v[6:7]
	s_movk_i32 s4, 0x4000
	v_add_co_u32_e32 v8, vcc, s4, v60
	s_mov_b32 s4, 0x24000
	s_nop 0
	v_addc_co_u32_e32 v9, vcc, 0, v61, vcc
	global_load_dwordx4 v[4:7], v[60:61], off nt
	s_nop 0
	global_load_dwordx4 v[8:11], v[8:9], off nt
	v_add_co_u32_e32 v12, vcc, s22, v60
	s_lshl_b32 s3, s3, 1
	s_nop 0
	v_addc_co_u32_e32 v13, vcc, 0, v61, vcc
	v_add_co_u32_e32 v16, vcc, s4, v60
	s_mov_b32 s4, 0x40000
	s_nop 0
	v_addc_co_u32_e32 v17, vcc, 0, v61, vcc
	global_load_dwordx4 v[12:15], v[12:13], off nt
	s_nop 0
	global_load_dwordx4 v[16:19], v[16:17], off nt
	v_add_co_u32_e32 v20, vcc, s4, v60
	s_mov_b32 s4, 0x44000
	s_nop 0
	v_addc_co_u32_e32 v21, vcc, 0, v61, vcc
	v_add_co_u32_e32 v24, vcc, s4, v60
	s_mov_b32 s4, 0x60000
	s_nop 0
	v_addc_co_u32_e32 v25, vcc, 0, v61, vcc
	global_load_dwordx4 v[20:23], v[20:21], off nt
	s_nop 0
	global_load_dwordx4 v[24:27], v[24:25], off nt
	v_add_co_u32_e32 v28, vcc, s4, v60
	s_mov_b32 s4, 0x64000
	s_nop 0
	v_addc_co_u32_e32 v29, vcc, 0, v61, vcc
	v_add_co_u32_e32 v32, vcc, s4, v60
	s_mov_b32 s4, 0x80000
	s_nop 0
	v_addc_co_u32_e32 v33, vcc, 0, v61, vcc
	global_load_dwordx4 v[28:31], v[28:29], off nt
	s_nop 0
	global_load_dwordx4 v[32:35], v[32:33], off nt
	v_add_co_u32_e32 v36, vcc, s4, v60
	s_mov_b32 s4, 0x84000
	s_nop 0
	v_addc_co_u32_e32 v37, vcc, 0, v61, vcc
	v_add_co_u32_e32 v40, vcc, s4, v60
	s_mov_b32 s4, 0xa0000
	s_nop 0
	v_addc_co_u32_e32 v41, vcc, 0, v61, vcc
	global_load_dwordx4 v[36:39], v[36:37], off nt
	s_nop 0
	global_load_dwordx4 v[40:43], v[40:41], off nt
	v_add_co_u32_e32 v44, vcc, s4, v60
	s_mov_b32 s4, 0xa4000
	s_nop 0
	v_addc_co_u32_e32 v45, vcc, 0, v61, vcc
	v_add_co_u32_e32 v48, vcc, s4, v60
	s_mov_b32 s4, 0xc0000
	s_nop 0
	v_addc_co_u32_e32 v49, vcc, 0, v61, vcc
	global_load_dwordx4 v[44:47], v[44:45], off nt
	s_nop 0
	global_load_dwordx4 v[48:51], v[48:49], off nt
	v_add_co_u32_e32 v52, vcc, s4, v60
	s_mov_b32 s4, 0xc4000
	s_nop 0
	v_addc_co_u32_e32 v53, vcc, 0, v61, vcc
	v_add_co_u32_e32 v56, vcc, s4, v60
	s_mov_b32 s4, 0xe0000
	s_nop 0
	v_addc_co_u32_e32 v57, vcc, 0, v61, vcc
	global_load_dwordx4 v[52:55], v[52:53], off nt
	s_nop 0
	global_load_dwordx4 v[56:59], v[56:57], off nt
	v_add_co_u32_e32 v62, vcc, s4, v60
	s_mov_b32 s4, 0xe4000
	s_nop 0
	v_addc_co_u32_e32 v63, vcc, 0, v61, vcc
	v_add_co_u32_e32 v64, vcc, s4, v60
	s_add_u32 s4, s18, s3
	s_nop 0
	v_addc_co_u32_e32 v65, vcc, 0, v61, vcc
	global_load_dwordx4 v[60:63], v[62:63], off nt
	s_nop 0
	global_load_dwordx4 v[64:67], v[64:65], off nt
	s_waitcnt vmcnt(0)
; #define LAS __attribute__((address_space(3)))
; #define LDS_WAIT() asm volatile("s_waitcnt lgkmcnt(0)" ::: "memory")
; __device__ __forceinline__ unsigned cvt_pk_bf16(float lo, float hi) { unsigned r; asm volatile("v_cvt_pk_bf16_f32 %0, %1, %2" : "=v"(r) : "v"(lo), "v"(hi)); return r; }
;     ...
; #pragma unroll
;     for (int i = 0; i < 8; ++i)
; #pragma unroll
;         for (int e = 0; e < 4; ++e) *(LAS unsigned*)(scr + (4 * r16 + e) * 128 + ((i ^ (r16 & 7)) * 16) + q * 4) = cvt_pk_bf16(v[2 * i][e], v[2 * i + 1][e]);
;     LDS_WAIT(); asm volatile("" ::: "memory");
;     const int c = lane & 7;
; #pragma unroll
;     for (int j = 0; j < 8; ++j) { const int row = (lane >> 3) + 8 * j; const u32x4 o = *(const LAS u32x4*)(scr + row * 128 + ((c ^ ((row >> 2) & 7)) * 16));
;         const int lc = col_off + n0 + row; int dr;
;         if (MODE == 0) dr = lc;
;         else if (MODE == 1) dr = (lc & ~255) + 128 * ((lc >> 5) & 1) + 32 * ((lc >> 6) & 3) + (lc & 31);
;         else if (MODE == 2) dr = 256 * (lc >> 7) + (lc & 127);
;         else dr = 256 * (lc >> 7) + 128 + (lc & 127);
;         *(u32x4*)(WT + (size_t)dr * (ldt ? ldt : K) + k0 + 8 * c) = o; }
;     LDS_WAIT(); asm volatile("" ::: "memory");
	v_cvt_pk_bf16_f32 v4, v4, v8
	v_add_u32_e32 v8, v71, v73
	ds_write_b32 v8, v4
	v_cvt_pk_bf16_f32 v4, v5, v9
	ds_write_b32 v8, v4 offset:128
	v_cvt_pk_bf16_f32 v4, v6, v10
	ds_write_b32 v8, v4 offset:256
	v_cvt_pk_bf16_f32 v4, v7, v11
	ds_write_b32 v8, v4 offset:384
	v_cvt_pk_bf16_f32 v4, v12, v16
	v_add_u32_e32 v5, v74, v73
	ds_write_b32 v5, v4
	v_cvt_pk_bf16_f32 v4, v13, v17
	ds_write_b32 v5, v4 offset:128
	v_cvt_pk_bf16_f32 v4, v14, v18
	ds_write_b32 v5, v4 offset:256
	v_cvt_pk_bf16_f32 v4, v15, v19
	ds_write_b32 v5, v4 offset:384
	v_cvt_pk_bf16_f32 v4, v20, v24
	v_add_u32_e32 v5, v75, v73
	ds_write_b32 v5, v4
	v_cvt_pk_bf16_f32 v4, v21, v25
	ds_write_b32 v5, v4 offset:128
	v_cvt_pk_bf16_f32 v4, v22, v26
	ds_write_b32 v5, v4 offset:256
	v_cvt_pk_bf16_f32 v4, v23, v27
	ds_write_b32 v5, v4 offset:384
	v_cvt_pk_bf16_f32 v4, v28, v32
	v_add_u32_e32 v5, v76, v73
	ds_write_b32 v5, v4
	v_cvt_pk_bf16_f32 v4, v29, v33
	ds_write_b32 v5, v4 offset:128
	v_cvt_pk_bf16_f32 v4, v30, v34
	ds_write_b32 v5, v4 offset:256
	v_cvt_pk_bf16_f32 v4, v31, v35
	ds_write_b32 v5, v4 offset:384
	v_cvt_pk_bf16_f32 v4, v36, v40
	v_add_u32_e32 v5, v77, v73
	ds_write_b32 v5, v4
	v_cvt_pk_bf16_f32 v4, v37, v41
	ds_write_b32 v5, v4 offset:128
	v_cvt_pk_bf16_f32 v4, v38, v42
	ds_write_b32 v5, v4 offset:256
	v_cvt_pk_bf16_f32 v4, v39, v43
	ds_write_b32 v5, v4 offset:384
	v_cvt_pk_bf16_f32 v4, v44, v48
	v_add_u32_e32 v5, v78, v73
	ds_write_b32 v5, v4
	v_cvt_pk_bf16_f32 v4, v45, v49
	ds_write_b32 v5, v4 offset:128
	v_cvt_pk_bf16_f32 v4, v46, v50
	ds_write_b32 v5, v4 offset:256
	v_cvt_pk_bf16_f32 v4, v47, v51
	ds_write_b32 v5, v4 offset:384
	v_cvt_pk_bf16_f32 v4, v52, v56
	v_add_u32_e32 v5, v79, v73
	ds_write_b32 v5, v4
	v_cvt_pk_bf16_f32 v4, v53, v57
	ds_write_b32 v5, v4 offset:128
	v_cvt_pk_bf16_f32 v4, v54, v58
	ds_write_b32 v5, v4 offset:256
	v_cvt_pk_bf16_f32 v4, v55, v59
	ds_write_b32 v5, v4 offset:384
	v_cvt_pk_bf16_f32 v4, v60, v64
	v_add_u32_e32 v5, v80, v73
	ds_write_b32 v5, v4
	v_cvt_pk_bf16_f32 v4, v61, v65
	ds_write_b32 v5, v4 offset:128
	v_cvt_pk_bf16_f32 v4, v62, v66
	ds_write_b32 v5, v4 offset:256
	v_cvt_pk_bf16_f32 v4, v63, v67
	ds_write_b32 v5, v4 offset:384
	s_addc_u32 s5, s19, 0
	v_lshlrev_b32_e32 v4, 1, v70
	v_mov_b32_e32 v5, v2
	s_waitcnt lgkmcnt(0)
	v_lshl_add_u64 v[4:5], s[4:5], 0, v[4:5]
	s_mov_b64 s[4:5], 0x4a00000
	v_lshl_add_u64 v[12:13], v[4:5], 0, s[4:5]
	v_add_u32_e32 v4, v82, v83
	ds_read_b128 v[4:7], v4
	v_or_b32_e32 v8, s2, v81
	v_lshlrev_b32_e32 v8, 10, v8
	v_mov_b32_e32 v9, v2
	v_lshl_add_u64 v[14:15], v[12:13], 0, v[8:9]
	v_add_u32_e32 v8, v85, v86
	ds_read_b128 v[8:11], v8
	s_waitcnt lgkmcnt(1)
	global_store_dwordx4 v[14:15], v[4:7], off nt
	v_readlane_b32 s46, v250, 56
	v_readlane_b32 s47, v250, 57
	v_or_b32_e32 v4, s2, v84
	v_lshlrev_b32_e32 v4, 10, v4
	v_mov_b32_e32 v5, v2
	v_lshl_add_u64 v[4:5], v[12:13], 0, v[4:5]
	s_waitcnt lgkmcnt(0)
	global_store_dwordx4 v[4:5], v[8:11], off nt
	v_add_u32_e32 v4, v88, v89
	ds_read_b128 v[4:7], v4
	v_or_b32_e32 v8, s2, v87
	v_lshlrev_b32_e32 v8, 10, v8
	v_mov_b32_e32 v9, v2
	v_lshl_add_u64 v[14:15], v[12:13], 0, v[8:9]
	v_add_u32_e32 v8, v91, v92
	ds_read_b128 v[8:11], v8
	s_waitcnt lgkmcnt(1)
	global_store_dwordx4 v[14:15], v[4:7], off nt
	v_readlane_b32 s46, v255, 36
	v_readlane_b32 s47, v255, 37
	v_or_b32_e32 v4, s2, v90
	v_lshlrev_b32_e32 v4, 10, v4
	v_mov_b32_e32 v5, v2
	v_lshl_add_u64 v[4:5], v[12:13], 0, v[4:5]
	s_waitcnt lgkmcnt(0)
	global_store_dwordx4 v[4:5], v[8:11], off nt
	v_add_u32_e32 v4, v94, v83
	ds_read_b128 v[4:7], v4
	v_or_b32_e32 v8, s2, v93
	v_lshlrev_b32_e32 v8, 10, v8
	v_mov_b32_e32 v9, v2
	v_lshl_add_u64 v[14:15], v[12:13], 0, v[8:9]
	v_add_u32_e32 v8, v96, v97
	ds_read_b128 v[8:11], v8
	s_waitcnt lgkmcnt(1)
	global_store_dwordx4 v[14:15], v[4:7], off nt
	v_readlane_b32 s37, v250, 47
	v_readlane_b32 s38, v250, 48
	v_or_b32_e32 v4, s2, v95
	v_lshlrev_b32_e32 v4, 10, v4
	v_mov_b32_e32 v5, v2
	v_lshl_add_u64 v[4:5], v[12:13], 0, v[4:5]
	s_waitcnt lgkmcnt(0)
	global_store_dwordx4 v[4:5], v[8:11], off nt
	v_add_u32_e32 v4, v99, v100
	ds_read_b128 v[4:7], v4
	v_or_b32_e32 v8, s2, v98
	v_lshlrev_b32_e32 v8, 10, v8
	v_mov_b32_e32 v9, v2
	v_lshl_add_u64 v[14:15], v[12:13], 0, v[8:9]
	v_add_u32_e32 v8, v102, v103
	ds_read_b128 v[8:11], v8
	s_waitcnt lgkmcnt(1)
	global_store_dwordx4 v[14:15], v[4:7], off nt
	v_readlane_b32 s39, v250, 49
	v_readlane_b32 s40, v250, 50
	v_or_b32_e32 v4, s2, v101
	v_lshlrev_b32_e32 v4, 10, v4
	v_mov_b32_e32 v5, v2
	v_lshl_add_u64 v[4:5], v[12:13], 0, v[4:5]
	s_waitcnt lgkmcnt(0)
	global_store_dwordx4 v[4:5], v[8:11], off nt
	s_waitcnt lgkmcnt(0)
	v_readlane_b32 s41, v250, 51
	v_readlane_b32 s42, v250, 52
	v_readlane_b32 s43, v250, 53
	v_readlane_b32 s44, v250, 54
	v_readlane_b32 s45, v250, 55
	v_readlane_b32 s48, v250, 58
	v_readlane_b32 s49, v250, 59

; #define LAS __attribute__((address_space(3)))
; #define LDS_WAIT() asm volatile("s_waitcnt lgkmcnt(0)" ::: "memory")
; __device__ __forceinline__ unsigned cvt_pk_bf16(float lo, float hi) { unsigned r; asm volatile("v_cvt_pk_bf16_f32 %0, %1, %2" : "=v"(r) : "v"(lo), "v"(hi)); return r; }
;     ...
; #pragma unroll
;     for (int i = 0; i < 8; ++i)
; #pragma unroll
;         for (int e = 0; e < 4; ++e) *(LAS unsigned*)(scr + (4 * r16 + e) * 128 + ((i ^ (r16 & 7)) * 16) + q * 4) = cvt_pk_bf16(v[2 * i][e], v[2 * i + 1][e]);
;     LDS_WAIT(); asm volatile("" ::: "memory");
;     const int c = lane & 7;
; #pragma unroll
;     for (int j = 0; j < 8; ++j) { const int row = (lane >> 3) + 8 * j; const u32x4 o = *(const LAS u32x4*)(scr + row * 128 + ((c ^ ((row >> 2) & 7)) * 16));
;         const int lc = col_off + n0 + row; int dr;
;         if (MODE == 0) dr = lc;
;         else if (MODE == 1) dr = (lc & ~255) + 128 * ((lc >> 5) & 1) + 32 * ((lc >> 6) & 3) + (lc & 31);
;         else if (MODE == 2) dr = 256 * (lc >> 7) + (lc & 127);
;         else dr = 256 * (lc >> 7) + 128 + (lc & 127);
;         *(u32x4*)(WT + (size_t)dr * (ldt ? ldt : K) + k0 + 8 * c) = o; }
;     LDS_WAIT(); asm volatile("" ::: "memory");
; __device__ __forceinline__ void weights_pass(const Args& a, LAS unsigned char* scr, int gw, int NGW, int lane, int pass) {
;     ...
;         if (r < I_QM) { transpose_item<1>(a.in[I_WVM] + (size_t)l * DM * MW, DM, MW, (bf16_t*)(ws + WS_WKV) + (size_t)l * 1024 * DM, a.in[I_GMEM] + l * DM, nullptr, 512, scr, r, lane); continue; } r -= I_QM;
.LBB0_651:
	s_waitcnt vmcnt(0)
	v_cvt_pk_bf16_f32 v60, v60, v64
	v_add_u32_e32 v64, v71, v73
	ds_write_b32 v64, v60
	v_cvt_pk_bf16_f32 v60, v61, v65
	ds_write_b32 v64, v60 offset:128
	v_cvt_pk_bf16_f32 v60, v62, v66
	ds_write_b32 v64, v60 offset:256
	v_cvt_pk_bf16_f32 v60, v63, v67
	ds_write_b32 v64, v60 offset:384
	v_cvt_pk_bf16_f32 v52, v52, v56
	v_add_u32_e32 v56, v74, v73
	ds_write_b32 v56, v52
	v_cvt_pk_bf16_f32 v52, v53, v57
	ds_write_b32 v56, v52 offset:128
	v_cvt_pk_bf16_f32 v52, v54, v58
	ds_write_b32 v56, v52 offset:256
	v_cvt_pk_bf16_f32 v52, v55, v59
	ds_write_b32 v56, v52 offset:384
	v_cvt_pk_bf16_f32 v44, v44, v48
	v_add_u32_e32 v48, v75, v73
	ds_write_b32 v48, v44
	v_cvt_pk_bf16_f32 v44, v45, v49
	ds_write_b32 v48, v44 offset:128
	v_cvt_pk_bf16_f32 v44, v46, v50
	ds_write_b32 v48, v44 offset:256
	v_cvt_pk_bf16_f32 v44, v47, v51
	ds_write_b32 v48, v44 offset:384
	v_cvt_pk_bf16_f32 v36, v36, v40
	v_add_u32_e32 v40, v76, v73
	ds_write_b32 v40, v36
	v_cvt_pk_bf16_f32 v36, v37, v41
	ds_write_b32 v40, v36 offset:128
	v_cvt_pk_bf16_f32 v36, v38, v42
	ds_write_b32 v40, v36 offset:256
	v_cvt_pk_bf16_f32 v36, v39, v43
	ds_write_b32 v40, v36 offset:384
	v_cvt_pk_bf16_f32 v28, v28, v32
	v_add_u32_e32 v32, v77, v73
	ds_write_b32 v32, v28
	v_cvt_pk_bf16_f32 v28, v29, v33
	ds_write_b32 v32, v28 offset:128
	v_cvt_pk_bf16_f32 v28, v30, v34
	ds_write_b32 v32, v28 offset:256
	v_cvt_pk_bf16_f32 v28, v31, v35
	ds_write_b32 v32, v28 offset:384
	v_cvt_pk_bf16_f32 v20, v20, v24
	v_add_u32_e32 v24, v78, v73
	ds_write_b32 v24, v20
	v_cvt_pk_bf16_f32 v20, v21, v25
	ds_write_b32 v24, v20 offset:128
	v_cvt_pk_bf16_f32 v20, v22, v26
	ds_write_b32 v24, v20 offset:256
	v_cvt_pk_bf16_f32 v20, v23, v27
	ds_write_b32 v24, v20 offset:384
	v_cvt_pk_bf16_f32 v12, v12, v16
	v_add_u32_e32 v16, v79, v73
	ds_write_b32 v16, v12
	v_cvt_pk_bf16_f32 v12, v13, v17
	ds_write_b32 v16, v12 offset:128
	v_cvt_pk_bf16_f32 v12, v14, v18
	ds_write_b32 v16, v12 offset:256
	v_cvt_pk_bf16_f32 v12, v15, v19
	ds_write_b32 v16, v12 offset:384
	v_cvt_pk_bf16_f32 v4, v4, v8
	v_add_u32_e32 v8, v80, v73
	v_readlane_b32 s6, v251, 16
	ds_write_b32 v8, v4
	v_cvt_pk_bf16_f32 v4, v5, v9
	s_add_u32 s4, s6, s4
	v_readlane_b32 s6, v251, 17
	ds_write_b32 v8, v4 offset:128
	v_cvt_pk_bf16_f32 v4, v6, v10
	s_addc_u32 s5, s6, s5
	ds_write_b32 v8, v4 offset:256
	v_cvt_pk_bf16_f32 v4, v7, v11
	ds_write_b32 v8, v4 offset:384
	s_or_b32 s6, s3, 0x200
	s_lshl_b32 s2, s2, 1
	s_waitcnt lgkmcnt(0)
	s_add_u32 s2, s4, s2
	s_addc_u32 s3, s5, 0
	v_lshlrev_b32_e32 v4, 1, v70
	v_mov_b32_e32 v5, v2
	v_add_u32_e32 v10, v82, v83
	v_lshl_add_u64 v[16:17], s[2:3], 0, v[4:5]
	ds_read_b128 v[4:7], v10
	s_and_b32 s2, s12, 0x60
	s_and_b32 s3, s6, 0x300
	s_or_b32 s3, s3, s2
	v_or_b32_e32 v8, s3, v81
	v_or_b32_e32 v12, s3, v84
	v_lshlrev_b32_e32 v8, 13, v8
	v_mov_b32_e32 v9, v2
	v_lshlrev_b32_e32 v12, 13, v12
	v_mov_b32_e32 v13, v2
	v_lshl_add_u64 v[18:19], v[16:17], 0, v[8:9]
	v_lshl_add_u64 v[20:21], v[16:17], 0, v[12:13]
	v_add_u32_e32 v12, v88, v89
	ds_read_b128 v[12:15], v12
	s_waitcnt lgkmcnt(1)
	global_store_dwordx4 v[18:19], v[4:7], off nt
	ds_read_b128 v[8:11], v10 offset:4096
	v_readlane_b32 s46, v255, 36
	v_add_u32_e32 v4, v85, v86
	ds_read_b128 v[4:7], v4
	v_readlane_b32 s47, v255, 37
	s_waitcnt lgkmcnt(0)
	global_store_dwordx4 v[20:21], v[4:7], off nt
	s_nop 1
	v_or_b32_e32 v4, s3, v87
	v_lshlrev_b32_e32 v4, 13, v4
	v_mov_b32_e32 v5, v2
	v_lshl_add_u64 v[4:5], v[16:17], 0, v[4:5]
	global_store_dwordx4 v[4:5], v[12:15], off nt
	v_add_u32_e32 v4, v91, v92
	ds_read_b128 v[4:7], v4
	v_or_b32_e32 v12, s3, v90
	v_lshlrev_b32_e32 v12, 13, v12
	v_mov_b32_e32 v13, v2
	v_lshl_add_u64 v[20:21], v[16:17], 0, v[12:13]
	v_add_u32_e32 v12, v96, v97
	s_mov_b32 s3, 0x100000
	ds_read_b128 v[12:15], v12
	s_waitcnt lgkmcnt(1)
	global_store_dwordx4 v[20:21], v[4:7], off nt
	s_nop 1
	v_add_co_u32_e32 v4, vcc, s3, v18
	s_nop 1
	v_addc_co_u32_e32 v5, vcc, 0, v19, vcc
	global_store_dwordx4 v[4:5], v[8:11], off nt
	v_mov_b32_e32 v4, 0x30f
	v_bitop3_b32 v4, s6, v4, v95 bitop3:0xc8
	v_or_b32_e32 v4, s2, v4
	v_lshlrev_b32_e32 v4, 13, v4
	v_mov_b32_e32 v5, v2
	v_lshl_add_u64 v[4:5], v[16:17], 0, v[4:5]
	v_add_co_u32_e32 v4, vcc, s3, v4
	v_mov_b32_e32 v8, 0x317
	s_nop 0
	v_addc_co_u32_e32 v5, vcc, 0, v5, vcc
	s_waitcnt lgkmcnt(0)
	global_store_dwordx4 v[4:5], v[12:15], off nt
	v_add_u32_e32 v4, v99, v100
	v_bitop3_b32 v8, s6, v8, v98 bitop3:0xc8
	ds_read_b128 v[4:7], v4
	v_or_b32_e32 v8, s2, v8
	v_lshlrev_b32_e32 v8, 13, v8
	v_mov_b32_e32 v9, v2
	v_lshl_add_u64 v[8:9], v[16:17], 0, v[8:9]
	v_add_co_u32_e32 v12, vcc, s3, v8
	v_add_u32_e32 v8, v102, v103
	s_nop 0
	v_addc_co_u32_e32 v13, vcc, 0, v9, vcc
	ds_read_b128 v[8:11], v8
	s_waitcnt lgkmcnt(1)
	global_store_dwordx4 v[12:13], v[4:7], off nt
	s_nop 1
	v_mov_b32_e32 v4, 0x31f
	v_bitop3_b32 v4, s6, v4, v101 bitop3:0xc8
	v_or_b32_e32 v4, s2, v4
	v_lshlrev_b32_e32 v4, 13, v4
	v_mov_b32_e32 v5, v2
	v_lshl_add_u64 v[4:5], v[16:17], 0, v[4:5]
	v_add_co_u32_e32 v4, vcc, 0x100000, v4
	s_nop 1
	v_addc_co_u32_e32 v5, vcc, 0, v5, vcc
	s_waitcnt lgkmcnt(0)
	global_store_dwordx4 v[4:5], v[8:11], off nt
	s_waitcnt lgkmcnt(0)

; #define LAS __attribute__((address_space(3)))
; #define LDS_WAIT() asm volatile("s_waitcnt lgkmcnt(0)" ::: "memory")
; __device__ __forceinline__ unsigned cvt_pk_bf16(float lo, float hi) { unsigned r; asm volatile("v_cvt_pk_bf16_f32 %0, %1, %2" : "=v"(r) : "v"(lo), "v"(hi)); return r; }
;     ...
;         for (int e = 0; e < 4; ++e) *(LAS unsigned*)(scr + (4 * r16 + e) * 128 + ((i ^ (r16 & 7)) * 16) + q * 4) = cvt_pk_bf16(v[2 * i][e], v[2 * i + 1][e]);
;     LDS_WAIT(); asm volatile("" ::: "memory");
;     const int c = lane & 7;
; #pragma unroll
;     for (int j = 0; j < 8; ++j) { const int row = (lane >> 3) + 8 * j; const u32x4 o = *(const LAS u32x4*)(scr + row * 128 + ((c ^ ((row >> 2) & 7)) * 16));
;         const int lc = col_off + n0 + row; int dr;
;         if (MODE == 0) dr = lc;
;         else if (MODE == 1) dr = (lc & ~255) + 128 * ((lc >> 5) & 1) + 32 * ((lc >> 6) & 3) + (lc & 31);
;         else if (MODE == 2) dr = 256 * (lc >> 7) + (lc & 127);
;         else dr = 256 * (lc >> 7) + 128 + (lc & 127);
;         *(u32x4*)(WT + (size_t)dr * (ldt ? ldt : K) + k0 + 8 * c) = o; }
; __device__ __forceinline__ void weights_pass(const Args& a, LAS unsigned char* scr, int gw, int NGW, int lane, int pass) {
;     ...
;         if (r < I_QM) { transpose_item<1>(a.in[I_WKM] + (size_t)l * DM * MW, DM, MW, (bf16_t*)(ws + WS_WKV) + (size_t)l * 1024 * DM, a.in[I_GMEM] + l * DM, nullptr, 0, scr, r, lane); continue; } r -= I_QM;
.LBB0_656:
	s_waitcnt vmcnt(0)
	v_cvt_pk_bf16_f32 v60, v60, v64
	v_add_u32_e32 v64, v71, v73
	ds_write_b32 v64, v60
	v_cvt_pk_bf16_f32 v60, v61, v65
	ds_write_b32 v64, v60 offset:128
	v_cvt_pk_bf16_f32 v60, v62, v66
	ds_write_b32 v64, v60 offset:256
	v_cvt_pk_bf16_f32 v60, v63, v67
	ds_write_b32 v64, v60 offset:384
	v_cvt_pk_bf16_f32 v52, v52, v56
	v_add_u32_e32 v56, v74, v73
	ds_write_b32 v56, v52
	v_cvt_pk_bf16_f32 v52, v53, v57
	ds_write_b32 v56, v52 offset:128
	v_cvt_pk_bf16_f32 v52, v54, v58
	ds_write_b32 v56, v52 offset:256
	v_cvt_pk_bf16_f32 v52, v55, v59
	ds_write_b32 v56, v52 offset:384
	v_cvt_pk_bf16_f32 v44, v44, v48
	v_add_u32_e32 v48, v75, v73
	ds_write_b32 v48, v44
	v_cvt_pk_bf16_f32 v44, v45, v49
	ds_write_b32 v48, v44 offset:128
	v_cvt_pk_bf16_f32 v44, v46, v50
	ds_write_b32 v48, v44 offset:256
	v_cvt_pk_bf16_f32 v44, v47, v51
	ds_write_b32 v48, v44 offset:384
	v_cvt_pk_bf16_f32 v36, v36, v40
	v_add_u32_e32 v40, v76, v73
	ds_write_b32 v40, v36
	v_cvt_pk_bf16_f32 v36, v37, v41
	ds_write_b32 v40, v36 offset:128
	v_cvt_pk_bf16_f32 v36, v38, v42
	ds_write_b32 v40, v36 offset:256
	v_cvt_pk_bf16_f32 v36, v39, v43
	ds_write_b32 v40, v36 offset:384
	v_cvt_pk_bf16_f32 v28, v28, v32
	v_add_u32_e32 v32, v77, v73
	ds_write_b32 v32, v28
	v_cvt_pk_bf16_f32 v28, v29, v33
	ds_write_b32 v32, v28 offset:128
	v_cvt_pk_bf16_f32 v28, v30, v34
	ds_write_b32 v32, v28 offset:256
	v_cvt_pk_bf16_f32 v28, v31, v35
	ds_write_b32 v32, v28 offset:384
	v_cvt_pk_bf16_f32 v20, v20, v24
	v_add_u32_e32 v24, v78, v73
	ds_write_b32 v24, v20
	v_cvt_pk_bf16_f32 v20, v21, v25
	ds_write_b32 v24, v20 offset:128
	v_cvt_pk_bf16_f32 v20, v22, v26
	ds_write_b32 v24, v20 offset:256
	v_cvt_pk_bf16_f32 v20, v23, v27
	ds_write_b32 v24, v20 offset:384
	v_cvt_pk_bf16_f32 v12, v12, v16
	v_add_u32_e32 v16, v79, v73
	ds_write_b32 v16, v12
	v_cvt_pk_bf16_f32 v12, v13, v17
	ds_write_b32 v16, v12 offset:128
	v_cvt_pk_bf16_f32 v12, v14, v18
	ds_write_b32 v16, v12 offset:256
	v_cvt_pk_bf16_f32 v12, v15, v19
	ds_write_b32 v16, v12 offset:384
	v_cvt_pk_bf16_f32 v4, v4, v8
	v_add_u32_e32 v8, v80, v73
	v_readlane_b32 s6, v251, 16
	ds_write_b32 v8, v4
	v_cvt_pk_bf16_f32 v4, v5, v9
	s_add_u32 s4, s6, s4
	v_readlane_b32 s6, v251, 17
	ds_write_b32 v8, v4 offset:128
	v_cvt_pk_bf16_f32 v4, v6, v10
	s_addc_u32 s5, s6, s5
	ds_write_b32 v8, v4 offset:256
	v_cvt_pk_bf16_f32 v4, v7, v11
	ds_write_b32 v8, v4 offset:384
	s_lshl_b32 s3, s3, 1
	s_waitcnt lgkmcnt(0)
	s_add_u32 s4, s4, s3
	s_addc_u32 s5, s5, 0
	v_lshlrev_b32_e32 v4, 1, v70
	v_mov_b32_e32 v5, v2
	v_add_u32_e32 v10, v82, v83
	v_lshl_add_u64 v[16:17], s[4:5], 0, v[4:5]
	ds_read_b128 v[4:7], v10
	s_and_b32 s3, s12, 0x60
	s_and_b32 s4, s2, 0x100
	s_or_b32 s4, s4, s3
	v_or_b32_e32 v8, s4, v81
	v_or_b32_e32 v12, s4, v84
	v_lshlrev_b32_e32 v8, 13, v8
	v_mov_b32_e32 v9, v2
	v_lshlrev_b32_e32 v12, 13, v12
	v_mov_b32_e32 v13, v2
	v_lshl_add_u64 v[18:19], v[16:17], 0, v[8:9]
	v_lshl_add_u64 v[20:21], v[16:17], 0, v[12:13]
	v_add_u32_e32 v12, v88, v89
	ds_read_b128 v[12:15], v12
	s_waitcnt lgkmcnt(1)
	global_store_dwordx4 v[18:19], v[4:7], off nt
	ds_read_b128 v[8:11], v10 offset:4096
	v_readlane_b32 s46, v255, 36
	v_add_u32_e32 v4, v85, v86
	ds_read_b128 v[4:7], v4
	v_readlane_b32 s47, v255, 37
	s_waitcnt lgkmcnt(0)
	global_store_dwordx4 v[20:21], v[4:7], off nt
	s_nop 1
	v_or_b32_e32 v4, s4, v87
	v_lshlrev_b32_e32 v4, 13, v4
	v_mov_b32_e32 v5, v2
	v_lshl_add_u64 v[4:5], v[16:17], 0, v[4:5]
	global_store_dwordx4 v[4:5], v[12:15], off nt
	v_add_u32_e32 v4, v91, v92
	ds_read_b128 v[4:7], v4
	v_or_b32_e32 v12, s4, v90
	v_lshlrev_b32_e32 v12, 13, v12
	v_mov_b32_e32 v13, v2
	v_lshl_add_u64 v[20:21], v[16:17], 0, v[12:13]
	v_add_u32_e32 v12, v96, v97
	s_mov_b32 s4, 0x100000
	ds_read_b128 v[12:15], v12
	s_waitcnt lgkmcnt(1)
	global_store_dwordx4 v[20:21], v[4:7], off nt
	s_nop 1
	v_add_co_u32_e32 v4, vcc, s4, v18
	v_add_u32_e32 v18, s2, v81
	s_nop 0
	v_addc_co_u32_e32 v5, vcc, 0, v19, vcc
	global_store_dwordx4 v[4:5], v[8:11], off nt
	v_add_u32_e32 v4, 40, v18
	v_and_b32_e32 v4, 0x10f, v4
	v_or_b32_e32 v4, s3, v4
	v_lshlrev_b32_e32 v4, 13, v4
	v_mov_b32_e32 v5, v2
	v_lshl_add_u64 v[4:5], v[16:17], 0, v[4:5]
	v_add_co_u32_e32 v4, vcc, s4, v4
	v_add_u32_e32 v8, 48, v18
	s_nop 0
	v_addc_co_u32_e32 v5, vcc, 0, v5, vcc
	s_waitcnt lgkmcnt(0)
	global_store_dwordx4 v[4:5], v[12:15], off nt
	v_add_u32_e32 v4, v99, v100
	v_and_b32_e32 v8, 0x117, v8
	ds_read_b128 v[4:7], v4
	v_or_b32_e32 v8, s3, v8
	v_lshlrev_b32_e32 v8, 13, v8
	v_mov_b32_e32 v9, v2
	v_lshl_add_u64 v[8:9], v[16:17], 0, v[8:9]
	v_add_co_u32_e32 v12, vcc, s4, v8
	v_add_u32_e32 v8, v102, v103
	s_nop 0
	v_addc_co_u32_e32 v13, vcc, 0, v9, vcc
	ds_read_b128 v[8:11], v8
	s_waitcnt lgkmcnt(1)
	global_store_dwordx4 v[12:13], v[4:7], off nt
	s_nop 1
	v_add_u32_e32 v4, 56, v18
	v_and_b32_e32 v4, 0x11f, v4
	v_or_b32_e32 v4, s3, v4
	v_lshlrev_b32_e32 v4, 13, v4
	v_mov_b32_e32 v5, v2
	v_lshl_add_u64 v[4:5], v[16:17], 0, v[4:5]
	v_add_co_u32_e32 v4, vcc, 0x100000, v4
	s_nop 1
	v_addc_co_u32_e32 v5, vcc, 0, v5, vcc
	s_waitcnt lgkmcnt(0)
	global_store_dwordx4 v[4:5], v[8:11], off nt
	s_waitcnt lgkmcnt(0)

; #define LAS __attribute__((address_space(3)))
; #define LDS_WAIT() asm volatile("s_waitcnt lgkmcnt(0)" ::: "memory")
; __device__ __forceinline__ unsigned cvt_pk_bf16(float lo, float hi) { unsigned r; asm volatile("v_cvt_pk_bf16_f32 %0, %1, %2" : "=v"(r) : "v"(lo), "v"(hi)); return r; }
;     ...
;         for (int e = 0; e < 4; ++e) *(LAS unsigned*)(scr + (4 * r16 + e) * 128 + ((i ^ (r16 & 7)) * 16) + q * 4) = cvt_pk_bf16(v[2 * i][e], v[2 * i + 1][e]);
;     LDS_WAIT(); asm volatile("" ::: "memory");
;     const int c = lane & 7;
; #pragma unroll
;     for (int j = 0; j < 8; ++j) { const int row = (lane >> 3) + 8 * j; const u32x4 o = *(const LAS u32x4*)(scr + row * 128 + ((c ^ ((row >> 2) & 7)) * 16));
;         const int lc = col_off + n0 + row; int dr;
;         if (MODE == 0) dr = lc;
;         else if (MODE == 1) dr = (lc & ~255) + 128 * ((lc >> 5) & 1) + 32 * ((lc >> 6) & 3) + (lc & 31);
;         else if (MODE == 2) dr = 256 * (lc >> 7) + (lc & 127);
;         else dr = 256 * (lc >> 7) + 128 + (lc & 127);
;         *(u32x4*)(WT + (size_t)dr * (ldt ? ldt : K) + k0 + 8 * c) = o; }
; __device__ __forceinline__ void weights_pass(const Args& a, LAS unsigned char* scr, int gw, int NGW, int lane, int pass) {
;     ...
;         if (r < I_QM) { transpose_item<0>(a.in[I_WQM] + (size_t)l * DM * MW, DM, MW, (bf16_t*)(wl + WL_Q), a.in[I_GCROSS] + l * DM, nullptr, 0, scr, r, lane); continue; } r -= I_QM;
.LBB0_661:
	s_waitcnt vmcnt(0)
	v_cvt_pk_bf16_f32 v60, v60, v64
	v_add_u32_e32 v64, v71, v73
	ds_write_b32 v64, v60
	v_cvt_pk_bf16_f32 v60, v61, v65
	ds_write_b32 v64, v60 offset:128
	v_cvt_pk_bf16_f32 v60, v62, v66
	ds_write_b32 v64, v60 offset:256
	v_cvt_pk_bf16_f32 v60, v63, v67
	ds_write_b32 v64, v60 offset:384
	v_cvt_pk_bf16_f32 v52, v52, v56
	v_add_u32_e32 v56, v74, v73
	ds_write_b32 v56, v52
	v_cvt_pk_bf16_f32 v52, v53, v57
	ds_write_b32 v56, v52 offset:128
	v_cvt_pk_bf16_f32 v52, v54, v58
	ds_write_b32 v56, v52 offset:256
	v_cvt_pk_bf16_f32 v52, v55, v59
	ds_write_b32 v56, v52 offset:384
	v_cvt_pk_bf16_f32 v44, v44, v48
	v_add_u32_e32 v48, v75, v73
	ds_write_b32 v48, v44
	v_cvt_pk_bf16_f32 v44, v45, v49
	ds_write_b32 v48, v44 offset:128
	v_cvt_pk_bf16_f32 v44, v46, v50
	ds_write_b32 v48, v44 offset:256
	v_cvt_pk_bf16_f32 v44, v47, v51
	ds_write_b32 v48, v44 offset:384
	v_cvt_pk_bf16_f32 v36, v36, v40
	v_add_u32_e32 v40, v76, v73
	ds_write_b32 v40, v36
	v_cvt_pk_bf16_f32 v36, v37, v41
	ds_write_b32 v40, v36 offset:128
	v_cvt_pk_bf16_f32 v36, v38, v42
	ds_write_b32 v40, v36 offset:256
	v_cvt_pk_bf16_f32 v36, v39, v43
	ds_write_b32 v40, v36 offset:384
	v_cvt_pk_bf16_f32 v28, v28, v32
	v_add_u32_e32 v32, v77, v73
	ds_write_b32 v32, v28
	v_cvt_pk_bf16_f32 v28, v29, v33
	ds_write_b32 v32, v28 offset:128
	v_cvt_pk_bf16_f32 v28, v30, v34
	ds_write_b32 v32, v28 offset:256
	v_cvt_pk_bf16_f32 v28, v31, v35
	ds_write_b32 v32, v28 offset:384
	v_cvt_pk_bf16_f32 v20, v20, v24
	v_add_u32_e32 v24, v78, v73
	ds_write_b32 v24, v20
	v_cvt_pk_bf16_f32 v20, v21, v25
	ds_write_b32 v24, v20 offset:128
	v_cvt_pk_bf16_f32 v20, v22, v26
	ds_write_b32 v24, v20 offset:256
	v_cvt_pk_bf16_f32 v20, v23, v27
	ds_write_b32 v24, v20 offset:384
	v_cvt_pk_bf16_f32 v12, v12, v16
	v_add_u32_e32 v16, v79, v73
	ds_write_b32 v16, v12
	v_cvt_pk_bf16_f32 v12, v13, v17
	ds_write_b32 v16, v12 offset:128
	v_cvt_pk_bf16_f32 v12, v14, v18
	ds_write_b32 v16, v12 offset:256
	v_cvt_pk_bf16_f32 v12, v15, v19
	ds_write_b32 v16, v12 offset:384
	v_cvt_pk_bf16_f32 v4, v4, v8
	v_add_u32_e32 v8, v80, v73
	ds_write_b32 v8, v4
	v_cvt_pk_bf16_f32 v4, v5, v9
	s_and_b32 s3, 0xffff, s3
	ds_write_b32 v8, v4 offset:128
	v_cvt_pk_bf16_f32 v4, v6, v10
	s_lshl_b32 s2, s2, 1
	ds_write_b32 v8, v4 offset:256
	v_cvt_pk_bf16_f32 v4, v7, v11
	s_add_u32 s4, s18, s2
	ds_write_b32 v8, v4 offset:384
	s_addc_u32 s5, s19, 0
	v_lshlrev_b32_e32 v4, 1, v70
	v_mov_b32_e32 v5, v2
	s_waitcnt lgkmcnt(0)
	v_lshl_add_u64 v[4:5], s[4:5], 0, v[4:5]
	s_mov_b64 s[4:5], 0x4600000
	v_lshl_add_u64 v[12:13], v[4:5], 0, s[4:5]
	v_add_u32_e32 v4, v82, v83
	ds_read_b128 v[4:7], v4
	v_or_b32_e32 v8, s3, v81
	v_lshlrev_b32_e32 v8, 13, v8
	v_mov_b32_e32 v9, v2
	v_lshl_add_u64 v[14:15], v[12:13], 0, v[8:9]
	v_add_u32_e32 v8, v85, v86
	ds_read_b128 v[8:11], v8
	s_waitcnt lgkmcnt(1)
	global_store_dwordx4 v[14:15], v[4:7], off nt
	v_readlane_b32 s46, v255, 36
	v_readlane_b32 s47, v255, 37
	v_or_b32_e32 v4, s3, v84
	v_lshlrev_b32_e32 v4, 13, v4
	v_mov_b32_e32 v5, v2
	v_lshl_add_u64 v[4:5], v[12:13], 0, v[4:5]
	s_waitcnt lgkmcnt(0)
	global_store_dwordx4 v[4:5], v[8:11], off nt
	v_add_u32_e32 v4, v88, v89
	ds_read_b128 v[4:7], v4
	v_or_b32_e32 v8, s3, v87
	v_lshlrev_b32_e32 v8, 13, v8
	v_mov_b32_e32 v9, v2
	v_lshl_add_u64 v[14:15], v[12:13], 0, v[8:9]
	v_add_u32_e32 v8, v91, v92
	ds_read_b128 v[8:11], v8
	s_waitcnt lgkmcnt(1)
	global_store_dwordx4 v[14:15], v[4:7], off nt
	s_nop 1
	v_or_b32_e32 v4, s3, v90
	v_lshlrev_b32_e32 v4, 13, v4
	v_mov_b32_e32 v5, v2
	v_lshl_add_u64 v[4:5], v[12:13], 0, v[4:5]
	s_waitcnt lgkmcnt(0)
	global_store_dwordx4 v[4:5], v[8:11], off nt
	v_add_u32_e32 v4, v94, v83
	ds_read_b128 v[4:7], v4
	v_or_b32_e32 v8, s3, v93
	v_lshlrev_b32_e32 v8, 13, v8
	v_mov_b32_e32 v9, v2
	v_lshl_add_u64 v[14:15], v[12:13], 0, v[8:9]
	v_add_u32_e32 v8, v96, v97
	ds_read_b128 v[8:11], v8
	s_waitcnt lgkmcnt(1)
	global_store_dwordx4 v[14:15], v[4:7], off nt
	s_nop 1
	v_or_b32_e32 v4, s3, v95
	v_lshlrev_b32_e32 v4, 13, v4
	v_mov_b32_e32 v5, v2
	v_lshl_add_u64 v[4:5], v[12:13], 0, v[4:5]
	s_waitcnt lgkmcnt(0)
	global_store_dwordx4 v[4:5], v[8:11], off nt
	v_add_u32_e32 v4, v99, v100
	ds_read_b128 v[4:7], v4
	v_or_b32_e32 v8, s3, v98
	v_lshlrev_b32_e32 v8, 13, v8
	v_mov_b32_e32 v9, v2
	v_lshl_add_u64 v[14:15], v[12:13], 0, v[8:9]
	v_add_u32_e32 v8, v102, v103
	ds_read_b128 v[8:11], v8
	s_waitcnt lgkmcnt(1)
	global_store_dwordx4 v[14:15], v[4:7], off nt
	s_nop 1
	v_or_b32_e32 v4, s3, v101
	v_lshlrev_b32_e32 v4, 13, v4
	v_mov_b32_e32 v5, v2
	v_lshl_add_u64 v[4:5], v[12:13], 0, v[4:5]
	s_waitcnt lgkmcnt(0)
	global_store_dwordx4 v[4:5], v[8:11], off nt
	s_waitcnt lgkmcnt(0)

;     const int nblk = N / 64, kb = item / nblk, nb = item % nblk, k0 = 64 * kb, n0 = 64 * nb;
;     const int r16 = lane & 15, q = lane >> 4;
;     const float* src = W + (size_t)(k0 + 2 * q) * N + n0 + 4 * r16;
;     f32x4 v[16];
; #pragma unroll
;     for (int j = 0; j < 16; ++j) v[j] = *(const f32x4*)(src + (size_t)(8 * (j >> 1) + (j & 1)) * N);
; __device__ __forceinline__ void weights_pass(const Args& a, LAS unsigned char* scr, int gw, int NGW, int lane, int pass) {
;     ...
;         if (r < I_OUT / 2) { transpose_item<0>(a.in[I_WOUT] + (size_t)l * DM * DM + (size_t)2048 * DM, 2048, DM, (bf16_t*)(ws + WS_WLOW) + (size_t)l * DM * 2048, nullptr, nullptr, 0, scr, r, lane); continue; } r -= I_OUT / 2;
.LBB0_663:
	s_andn2_b64 vcc, exec, s[4:5]
	s_cbranch_vccnz .LBB0_665
	s_lshl_b64 s[2:3], s[0:1], 26
	s_add_u32 s6, s74, s2
	s_addc_u32 s7, s75, s3
	s_lshl_b64 s[4:5], s[0:1], 24
	v_readlane_b32 s2, v252, 53
	s_add_u32 s3, s2, s4
	v_readlane_b32 s2, v252, 54
	s_addc_u32 s4, s2, s5
	s_and_b32 s5, s21, 0xffc0
	s_lshl_b32 s2, s20, 6
	v_lshlrev_b32_e32 v4, 2, v69
	s_and_b32 s2, s2, 0xfc0
	v_lshl_or_b32 v4, s5, 14, v4
	v_mov_b32_e32 v5, v2
	v_lshl_add_u64 v[4:5], s[6:7], 0, v[4:5]
	s_lshl_b32 s14, s2, 2
	v_lshl_add_u64 v[4:5], v[4:5], 0, s[14:15]
	v_lshlrev_b32_e32 v6, 2, v68
	v_mov_b32_e32 v7, v2
	v_lshl_add_u64 v[60:61], v[4:5], 0, v[6:7]
	s_brev_b32 s6, 64
	v_add_co_u32_e32 v4, vcc, s6, v60
	s_mov_b32 s6, 0x2004000
	s_nop 0
	v_addc_co_u32_e32 v5, vcc, 0, v61, vcc
	v_add_co_u32_e32 v8, vcc, s6, v60
	s_mov_b32 s6, 0x2020000
	s_nop 0
	v_addc_co_u32_e32 v9, vcc, 0, v61, vcc
	global_load_dwordx4 v[4:7], v[4:5], off nt
	s_nop 0
	global_load_dwordx4 v[8:11], v[8:9], off nt
	v_add_co_u32_e32 v12, vcc, s6, v60
	s_mov_b32 s6, 0x2024000
	s_nop 0
	v_addc_co_u32_e32 v13, vcc, 0, v61, vcc
	v_add_co_u32_e32 v16, vcc, s6, v60
	s_mov_b32 s6, 0x2040000
	s_nop 0
	v_addc_co_u32_e32 v17, vcc, 0, v61, vcc
	global_load_dwordx4 v[12:15], v[12:13], off nt
	s_nop 0
	global_load_dwordx4 v[16:19], v[16:17], off nt
	v_add_co_u32_e32 v20, vcc, s6, v60
	s_mov_b32 s6, 0x2044000
	s_nop 0
	v_addc_co_u32_e32 v21, vcc, 0, v61, vcc
	v_add_co_u32_e32 v24, vcc, s6, v60
	s_mov_b32 s6, 0x2060000
	s_nop 0
	v_addc_co_u32_e32 v25, vcc, 0, v61, vcc
	global_load_dwordx4 v[20:23], v[20:21], off nt
	s_nop 0
	global_load_dwordx4 v[24:27], v[24:25], off nt
	v_add_co_u32_e32 v28, vcc, s6, v60
	s_mov_b32 s6, 0x2064000
	s_nop 0
	v_addc_co_u32_e32 v29, vcc, 0, v61, vcc
	v_add_co_u32_e32 v32, vcc, s6, v60
	s_mov_b32 s6, 0x2080000
	s_nop 0
	v_addc_co_u32_e32 v33, vcc, 0, v61, vcc
	global_load_dwordx4 v[28:31], v[28:29], off nt
	s_nop 0
	global_load_dwordx4 v[32:35], v[32:33], off nt
	v_add_co_u32_e32 v36, vcc, s6, v60
	s_mov_b32 s6, 0x2084000
	s_nop 0
	v_addc_co_u32_e32 v37, vcc, 0, v61, vcc
	v_add_co_u32_e32 v40, vcc, s6, v60
	s_mov_b32 s6, 0x20a0000
	s_nop 0
	v_addc_co_u32_e32 v41, vcc, 0, v61, vcc
	global_load_dwordx4 v[36:39], v[36:37], off nt
	s_nop 0
	global_load_dwordx4 v[40:43], v[40:41], off nt
	v_add_co_u32_e32 v44, vcc, s6, v60
	s_mov_b32 s6, 0x20a4000
	s_nop 0
	v_addc_co_u32_e32 v45, vcc, 0, v61, vcc
	v_add_co_u32_e32 v48, vcc, s6, v60
	s_mov_b32 s6, 0x20c0000
	s_nop 0
	v_addc_co_u32_e32 v49, vcc, 0, v61, vcc
	global_load_dwordx4 v[44:47], v[44:45], off nt
	s_nop 0
	global_load_dwordx4 v[48:51], v[48:49], off nt
	v_add_co_u32_e32 v52, vcc, s6, v60
	s_mov_b32 s6, 0x20c4000
	s_nop 0
	v_addc_co_u32_e32 v53, vcc, 0, v61, vcc
	v_add_co_u32_e32 v56, vcc, s6, v60
	s_mov_b32 s6, 0x20e0000
	s_nop 0
	v_addc_co_u32_e32 v57, vcc, 0, v61, vcc
	global_load_dwordx4 v[52:55], v[52:53], off nt
	s_nop 0
	global_load_dwordx4 v[56:59], v[56:57], off nt
	v_add_co_u32_e32 v62, vcc, s6, v60
	s_mov_b32 s6, 0x20e4000
	s_nop 0
	v_addc_co_u32_e32 v63, vcc, 0, v61, vcc
	v_add_co_u32_e32 v64, vcc, s6, v60
	s_lshl_b32 s5, s5, 1
	s_nop 0
	v_addc_co_u32_e32 v65, vcc, 0, v61, vcc
	global_load_dwordx4 v[60:63], v[62:63], off nt
	s_nop 0
	global_load_dwordx4 v[64:67], v[64:65], off nt
	s_waitcnt vmcnt(0)
; #define LAS __attribute__((address_space(3)))
; #define LDS_WAIT() asm volatile("s_waitcnt lgkmcnt(0)" ::: "memory")
; __device__ __forceinline__ unsigned cvt_pk_bf16(float lo, float hi) { unsigned r; asm volatile("v_cvt_pk_bf16_f32 %0, %1, %2" : "=v"(r) : "v"(lo), "v"(hi)); return r; }
;     ...
;         for (int e = 0; e < 4; ++e) *(LAS unsigned*)(scr + (4 * r16 + e) * 128 + ((i ^ (r16 & 7)) * 16) + q * 4) = cvt_pk_bf16(v[2 * i][e], v[2 * i + 1][e]);
;     LDS_WAIT(); asm volatile("" ::: "memory");
;     const int c = lane & 7;
; #pragma unroll
;     for (int j = 0; j < 8; ++j) { const int row = (lane >> 3) + 8 * j; const u32x4 o = *(const LAS u32x4*)(scr + row * 128 + ((c ^ ((row >> 2) & 7)) * 16));
;         const int lc = col_off + n0 + row; int dr;
;         if (MODE == 0) dr = lc;
;         else if (MODE == 1) dr = (lc & ~255) + 128 * ((lc >> 5) & 1) + 32 * ((lc >> 6) & 3) + (lc & 31);
;         else if (MODE == 2) dr = 256 * (lc >> 7) + (lc & 127);
;         else dr = 256 * (lc >> 7) + 128 + (lc & 127);
;         *(u32x4*)(WT + (size_t)dr * (ldt ? ldt : K) + k0 + 8 * c) = o; }
; __device__ __forceinline__ void weights_pass(const Args& a, LAS unsigned char* scr, int gw, int NGW, int lane, int pass) {
;     ...
;         if (r < I_OUT / 2) { transpose_item<0>(a.in[I_WOUT] + (size_t)l * DM * DM + (size_t)2048 * DM, 2048, DM, (bf16_t*)(ws + WS_WLOW) + (size_t)l * DM * 2048, nullptr, nullptr, 0, scr, r, lane); continue; } r -= I_OUT / 2;
	v_cvt_pk_bf16_f32 v4, v4, v8
	v_add_u32_e32 v8, v71, v73
	ds_write_b32 v8, v4
	v_cvt_pk_bf16_f32 v4, v5, v9
	ds_write_b32 v8, v4 offset:128
	v_cvt_pk_bf16_f32 v4, v6, v10
	ds_write_b32 v8, v4 offset:256
	v_cvt_pk_bf16_f32 v4, v7, v11
	ds_write_b32 v8, v4 offset:384
	v_cvt_pk_bf16_f32 v4, v12, v16
	v_add_u32_e32 v5, v74, v73
	ds_write_b32 v5, v4
	v_cvt_pk_bf16_f32 v4, v13, v17
	ds_write_b32 v5, v4 offset:128
	v_cvt_pk_bf16_f32 v4, v14, v18
	ds_write_b32 v5, v4 offset:256
	v_cvt_pk_bf16_f32 v4, v15, v19
	ds_write_b32 v5, v4 offset:384
	v_cvt_pk_bf16_f32 v4, v20, v24
	v_add_u32_e32 v5, v75, v73
	ds_write_b32 v5, v4
	v_cvt_pk_bf16_f32 v4, v21, v25
	ds_write_b32 v5, v4 offset:128
	v_cvt_pk_bf16_f32 v4, v22, v26
	ds_write_b32 v5, v4 offset:256
	v_cvt_pk_bf16_f32 v4, v23, v27
	ds_write_b32 v5, v4 offset:384
	v_cvt_pk_bf16_f32 v4, v28, v32
	v_add_u32_e32 v5, v76, v73
	ds_write_b32 v5, v4
	v_cvt_pk_bf16_f32 v4, v29, v33
	ds_write_b32 v5, v4 offset:128
	v_cvt_pk_bf16_f32 v4, v30, v34
	ds_write_b32 v5, v4 offset:256
	v_cvt_pk_bf16_f32 v4, v31, v35
	ds_write_b32 v5, v4 offset:384
	v_cvt_pk_bf16_f32 v4, v36, v40
	v_add_u32_e32 v5, v77, v73
	ds_write_b32 v5, v4
	v_cvt_pk_bf16_f32 v4, v37, v41
	ds_write_b32 v5, v4 offset:128
	v_cvt_pk_bf16_f32 v4, v38, v42
	ds_write_b32 v5, v4 offset:256
	v_cvt_pk_bf16_f32 v4, v39, v43
	ds_write_b32 v5, v4 offset:384
	v_cvt_pk_bf16_f32 v4, v44, v48
	v_add_u32_e32 v5, v78, v73
	ds_write_b32 v5, v4
	v_cvt_pk_bf16_f32 v4, v45, v49
	ds_write_b32 v5, v4 offset:128
	v_cvt_pk_bf16_f32 v4, v46, v50
	ds_write_b32 v5, v4 offset:256
	v_cvt_pk_bf16_f32 v4, v47, v51
	ds_write_b32 v5, v4 offset:384
	v_cvt_pk_bf16_f32 v4, v52, v56
	v_add_u32_e32 v5, v79, v73
	ds_write_b32 v5, v4
	v_cvt_pk_bf16_f32 v4, v53, v57
	ds_write_b32 v5, v4 offset:128
	v_cvt_pk_bf16_f32 v4, v54, v58
	ds_write_b32 v5, v4 offset:256
	v_cvt_pk_bf16_f32 v4, v55, v59
	ds_write_b32 v5, v4 offset:384
	v_cvt_pk_bf16_f32 v4, v60, v64
	v_add_u32_e32 v5, v80, v73
	ds_write_b32 v5, v4
	v_cvt_pk_bf16_f32 v4, v61, v65
	ds_write_b32 v5, v4 offset:128
	v_cvt_pk_bf16_f32 v4, v62, v66
	ds_write_b32 v5, v4 offset:256
	v_cvt_pk_bf16_f32 v4, v63, v67
	ds_write_b32 v5, v4 offset:384
	s_add_u32 s6, s3, s5
	s_waitcnt lgkmcnt(0)
	s_addc_u32 s7, s4, 0
	v_lshlrev_b32_e32 v4, 1, v70
	v_mov_b32_e32 v5, v2
	v_lshl_add_u64 v[12:13], s[6:7], 0, v[4:5]
	v_add_u32_e32 v4, v82, v83
	ds_read_b128 v[4:7], v4
	v_or_b32_e32 v8, s2, v81
	v_lshlrev_b32_e32 v8, 12, v8
	v_mov_b32_e32 v9, v2
	v_lshl_add_u64 v[14:15], v[12:13], 0, v[8:9]
	v_add_u32_e32 v8, v85, v86
	ds_read_b128 v[8:11], v8
	s_waitcnt lgkmcnt(1)
	global_store_dwordx4 v[14:15], v[4:7], off nt
	s_nop 1
	v_or_b32_e32 v4, s2, v84
	v_lshlrev_b32_e32 v4, 12, v4
	v_mov_b32_e32 v5, v2
	v_lshl_add_u64 v[4:5], v[12:13], 0, v[4:5]
	s_waitcnt lgkmcnt(0)
	global_store_dwordx4 v[4:5], v[8:11], off nt
	v_add_u32_e32 v4, v88, v89
	ds_read_b128 v[4:7], v4
	v_or_b32_e32 v8, s2, v87
	v_lshlrev_b32_e32 v8, 12, v8
	v_mov_b32_e32 v9, v2
	v_lshl_add_u64 v[14:15], v[12:13], 0, v[8:9]
	v_add_u32_e32 v8, v91, v92
	ds_read_b128 v[8:11], v8
	s_waitcnt lgkmcnt(1)
	global_store_dwordx4 v[14:15], v[4:7], off nt
	s_nop 1
	v_or_b32_e32 v4, s2, v90
	v_lshlrev_b32_e32 v4, 12, v4
	v_mov_b32_e32 v5, v2
	v_lshl_add_u64 v[4:5], v[12:13], 0, v[4:5]
	s_waitcnt lgkmcnt(0)
	global_store_dwordx4 v[4:5], v[8:11], off nt
	v_add_u32_e32 v4, v94, v83
	ds_read_b128 v[4:7], v4
	v_or_b32_e32 v8, s2, v93
	v_lshlrev_b32_e32 v8, 12, v8
	v_mov_b32_e32 v9, v2
	v_lshl_add_u64 v[14:15], v[12:13], 0, v[8:9]
	v_add_u32_e32 v8, v96, v97
	ds_read_b128 v[8:11], v8
	s_waitcnt lgkmcnt(1)
	global_store_dwordx4 v[14:15], v[4:7], off nt
	s_nop 1
	v_or_b32_e32 v4, s2, v95
	v_lshlrev_b32_e32 v4, 12, v4
	v_mov_b32_e32 v5, v2
	v_lshl_add_u64 v[4:5], v[12:13], 0, v[4:5]
	s_waitcnt lgkmcnt(0)
	global_store_dwordx4 v[4:5], v[8:11], off nt
	v_add_u32_e32 v4, v99, v100
	ds_read_b128 v[4:7], v4
	v_or_b32_e32 v8, s2, v98
	v_lshlrev_b32_e32 v8, 12, v8
	v_mov_b32_e32 v9, v2
	v_lshl_add_u64 v[14:15], v[12:13], 0, v[8:9]
	v_add_u32_e32 v8, v102, v103
	ds_read_b128 v[8:11], v8
	s_waitcnt lgkmcnt(1)
	global_store_dwordx4 v[14:15], v[4:7], off nt
	s_nop 1
	v_or_b32_e32 v4, s2, v101
	v_lshlrev_b32_e32 v4, 12, v4
	v_mov_b32_e32 v5, v2
	v_lshl_add_u64 v[4:5], v[12:13], 0, v[4:5]
	s_waitcnt lgkmcnt(0)
	global_store_dwordx4 v[4:5], v[8:11], off nt
	s_waitcnt lgkmcnt(0)

;     const int nblk = N / 64, kb = item / nblk, nb = item % nblk, k0 = 64 * kb, n0 = 64 * nb;
;     const int r16 = lane & 15, q = lane >> 4;
;     const float* src = W + (size_t)(k0 + 2 * q) * N + n0 + 4 * r16;
;     f32x4 v[16];
; #pragma unroll
;     for (int j = 0; j < 16; ++j) v[j] = *(const f32x4*)(src + (size_t)(8 * (j >> 1) + (j & 1)) * N);
; __device__ __forceinline__ void weights_pass(const Args& a, LAS unsigned char* scr, int gw, int NGW, int lane, int pass) {
;     ...
;         if (r < I_OUT / 2) { transpose_item<0>(a.in[I_WOUT] + (size_t)l * DM * DM, 2048, DM, (bf16_t*)(wl + WL_OUT), nullptr, nullptr, 0, scr, r, lane, DM); continue; } r -= I_OUT / 2;
.LBB0_666:
	s_andn2_b64 vcc, exec, s[4:5]
	s_cbranch_vccnz .LBB0_624
	s_lshl_b64 s[0:1], s[0:1], 26
	s_add_u32 s2, s74, s0
	s_addc_u32 s3, s75, s1
	s_add_i32 s0, s20, 0xee00
	s_and_b32 s1, s0, 0xffc0
	s_lshl_b32 s0, s20, 6
	v_lshlrev_b32_e32 v4, 2, v69
	s_and_b32 s0, s0, 0xfc0
	v_lshl_or_b32 v4, s1, 14, v4
	v_mov_b32_e32 v5, v2
	v_lshl_add_u64 v[4:5], s[2:3], 0, v[4:5]
	s_lshl_b32 s14, s0, 2
	v_lshl_add_u64 v[4:5], v[4:5], 0, s[14:15]
	v_lshlrev_b32_e32 v6, 2, v68
	v_mov_b32_e32 v7, v2
	v_lshl_add_u64 v[60:61], v[4:5], 0, v[6:7]
	s_movk_i32 s2, 0x4000
	v_add_co_u32_e32 v8, vcc, s2, v60
	s_mov_b32 s2, 0x24000
	s_nop 0
	v_addc_co_u32_e32 v9, vcc, 0, v61, vcc
	global_load_dwordx4 v[4:7], v[60:61], off nt
	s_nop 0
	global_load_dwordx4 v[8:11], v[8:9], off nt
	v_add_co_u32_e32 v12, vcc, s22, v60
	s_lshl_b32 s1, s1, 1
	s_nop 0
	v_addc_co_u32_e32 v13, vcc, 0, v61, vcc
	v_add_co_u32_e32 v16, vcc, s2, v60
	s_mov_b32 s2, 0x40000
	s_nop 0
	v_addc_co_u32_e32 v17, vcc, 0, v61, vcc
	global_load_dwordx4 v[12:15], v[12:13], off nt
	s_nop 0
	global_load_dwordx4 v[16:19], v[16:17], off nt
	v_add_co_u32_e32 v20, vcc, s2, v60
	s_mov_b32 s2, 0x44000
	s_nop 0
	v_addc_co_u32_e32 v21, vcc, 0, v61, vcc
	v_add_co_u32_e32 v24, vcc, s2, v60
	s_mov_b32 s2, 0x60000
	s_nop 0
	v_addc_co_u32_e32 v25, vcc, 0, v61, vcc
	global_load_dwordx4 v[20:23], v[20:21], off nt
	s_nop 0
	global_load_dwordx4 v[24:27], v[24:25], off nt
	v_add_co_u32_e32 v28, vcc, s2, v60
	s_mov_b32 s2, 0x64000
	s_nop 0
	v_addc_co_u32_e32 v29, vcc, 0, v61, vcc
	v_add_co_u32_e32 v32, vcc, s2, v60
	s_mov_b32 s2, 0x80000
	s_nop 0
	v_addc_co_u32_e32 v33, vcc, 0, v61, vcc
	global_load_dwordx4 v[28:31], v[28:29], off nt
	s_nop 0
	global_load_dwordx4 v[32:35], v[32:33], off nt
	v_add_co_u32_e32 v36, vcc, s2, v60
	s_mov_b32 s2, 0x84000
	s_nop 0
	v_addc_co_u32_e32 v37, vcc, 0, v61, vcc
	v_add_co_u32_e32 v40, vcc, s2, v60
	s_mov_b32 s2, 0xa0000
	s_nop 0
	v_addc_co_u32_e32 v41, vcc, 0, v61, vcc
	global_load_dwordx4 v[36:39], v[36:37], off nt
	s_nop 0
	global_load_dwordx4 v[40:43], v[40:41], off nt
	v_add_co_u32_e32 v44, vcc, s2, v60
	s_mov_b32 s2, 0xa4000
	s_nop 0
	v_addc_co_u32_e32 v45, vcc, 0, v61, vcc
	v_add_co_u32_e32 v48, vcc, s2, v60
	s_mov_b32 s2, 0xc0000
	s_nop 0
	v_addc_co_u32_e32 v49, vcc, 0, v61, vcc
	global_load_dwordx4 v[44:47], v[44:45], off nt
	s_nop 0
	global_load_dwordx4 v[48:51], v[48:49], off nt
	v_add_co_u32_e32 v52, vcc, s2, v60
	s_mov_b32 s2, 0xc4000
	s_nop 0
	v_addc_co_u32_e32 v53, vcc, 0, v61, vcc
	v_add_co_u32_e32 v56, vcc, s2, v60
	s_mov_b32 s2, 0xe0000
	s_nop 0
	v_addc_co_u32_e32 v57, vcc, 0, v61, vcc
	global_load_dwordx4 v[52:55], v[52:53], off nt
	s_nop 0
	global_load_dwordx4 v[56:59], v[56:57], off nt
	v_add_co_u32_e32 v62, vcc, s2, v60
	s_mov_b32 s2, 0xe4000
	s_nop 0
	v_addc_co_u32_e32 v63, vcc, 0, v61, vcc
	v_add_co_u32_e32 v64, vcc, s2, v60
	s_add_u32 s2, s18, s1
	s_nop 0
	v_addc_co_u32_e32 v65, vcc, 0, v61, vcc
	global_load_dwordx4 v[60:63], v[62:63], off nt
	s_nop 0
	global_load_dwordx4 v[64:67], v[64:65], off nt
	s_waitcnt vmcnt(0)
; #define LAS __attribute__((address_space(3)))
; #define LDS_WAIT() asm volatile("s_waitcnt lgkmcnt(0)" ::: "memory")
; __device__ __forceinline__ unsigned cvt_pk_bf16(float lo, float hi) { unsigned r; asm volatile("v_cvt_pk_bf16_f32 %0, %1, %2" : "=v"(r) : "v"(lo), "v"(hi)); return r; }
;     ...
;         for (int e = 0; e < 4; ++e) *(LAS unsigned*)(scr + (4 * r16 + e) * 128 + ((i ^ (r16 & 7)) * 16) + q * 4) = cvt_pk_bf16(v[2 * i][e], v[2 * i + 1][e]);
;     LDS_WAIT(); asm volatile("" ::: "memory");
;     const int c = lane & 7;
; #pragma unroll
;     for (int j = 0; j < 8; ++j) { const int row = (lane >> 3) + 8 * j; const u32x4 o = *(const LAS u32x4*)(scr + row * 128 + ((c ^ ((row >> 2) & 7)) * 16));
;         const int lc = col_off + n0 + row; int dr;
;         if (MODE == 0) dr = lc;
;         else if (MODE == 1) dr = (lc & ~255) + 128 * ((lc >> 5) & 1) + 32 * ((lc >> 6) & 3) + (lc & 31);
;         else if (MODE == 2) dr = 256 * (lc >> 7) + (lc & 127);
;         else dr = 256 * (lc >> 7) + 128 + (lc & 127);
;         *(u32x4*)(WT + (size_t)dr * (ldt ? ldt : K) + k0 + 8 * c) = o; }
; __device__ __forceinline__ void weights_pass(const Args& a, LAS unsigned char* scr, int gw, int NGW, int lane, int pass) {
;     ...
;         if (r < I_OUT / 2) { transpose_item<0>(a.in[I_WOUT] + (size_t)l * DM * DM, 2048, DM, (bf16_t*)(wl + WL_OUT), nullptr, nullptr, 0, scr, r, lane, DM); continue; } r -= I_OUT / 2;
	v_cvt_pk_bf16_f32 v4, v4, v8
	v_add_u32_e32 v8, v71, v73
	ds_write_b32 v8, v4
	v_cvt_pk_bf16_f32 v4, v5, v9
	ds_write_b32 v8, v4 offset:128
	v_cvt_pk_bf16_f32 v4, v6, v10
	ds_write_b32 v8, v4 offset:256
	v_cvt_pk_bf16_f32 v4, v7, v11
	ds_write_b32 v8, v4 offset:384
	v_cvt_pk_bf16_f32 v4, v12, v16
	v_add_u32_e32 v5, v74, v73
	ds_write_b32 v5, v4
	v_cvt_pk_bf16_f32 v4, v13, v17
	ds_write_b32 v5, v4 offset:128
	v_cvt_pk_bf16_f32 v4, v14, v18
	ds_write_b32 v5, v4 offset:256
	v_cvt_pk_bf16_f32 v4, v15, v19
	ds_write_b32 v5, v4 offset:384
	v_cvt_pk_bf16_f32 v4, v20, v24
	v_add_u32_e32 v5, v75, v73
	ds_write_b32 v5, v4
	v_cvt_pk_bf16_f32 v4, v21, v25
	ds_write_b32 v5, v4 offset:128
	v_cvt_pk_bf16_f32 v4, v22, v26
	ds_write_b32 v5, v4 offset:256
	v_cvt_pk_bf16_f32 v4, v23, v27
	ds_write_b32 v5, v4 offset:384
	v_cvt_pk_bf16_f32 v4, v28, v32
	v_add_u32_e32 v5, v76, v73
	ds_write_b32 v5, v4
	v_cvt_pk_bf16_f32 v4, v29, v33
	ds_write_b32 v5, v4 offset:128
	v_cvt_pk_bf16_f32 v4, v30, v34
	ds_write_b32 v5, v4 offset:256
	v_cvt_pk_bf16_f32 v4, v31, v35
	ds_write_b32 v5, v4 offset:384
	v_cvt_pk_bf16_f32 v4, v36, v40
	v_add_u32_e32 v5, v77, v73
	ds_write_b32 v5, v4
	v_cvt_pk_bf16_f32 v4, v37, v41
	ds_write_b32 v5, v4 offset:128
	v_cvt_pk_bf16_f32 v4, v38, v42
	ds_write_b32 v5, v4 offset:256
	v_cvt_pk_bf16_f32 v4, v39, v43
	ds_write_b32 v5, v4 offset:384
	v_cvt_pk_bf16_f32 v4, v44, v48
	v_add_u32_e32 v5, v78, v73
	ds_write_b32 v5, v4
	v_cvt_pk_bf16_f32 v4, v45, v49
	ds_write_b32 v5, v4 offset:128
	v_cvt_pk_bf16_f32 v4, v46, v50
	ds_write_b32 v5, v4 offset:256
	v_cvt_pk_bf16_f32 v4, v47, v51
	ds_write_b32 v5, v4 offset:384
	v_cvt_pk_bf16_f32 v4, v52, v56
	v_add_u32_e32 v5, v79, v73
	ds_write_b32 v5, v4
	v_cvt_pk_bf16_f32 v4, v53, v57
	ds_write_b32 v5, v4 offset:128
	v_cvt_pk_bf16_f32 v4, v54, v58
	ds_write_b32 v5, v4 offset:256
	v_cvt_pk_bf16_f32 v4, v55, v59
	ds_write_b32 v5, v4 offset:384
	v_cvt_pk_bf16_f32 v4, v60, v64
	v_add_u32_e32 v5, v80, v73
	ds_write_b32 v5, v4
	v_cvt_pk_bf16_f32 v4, v61, v65
	ds_write_b32 v5, v4 offset:128
	v_cvt_pk_bf16_f32 v4, v62, v66
	ds_write_b32 v5, v4 offset:256
	v_cvt_pk_bf16_f32 v4, v63, v67
	ds_write_b32 v5, v4 offset:384
	s_addc_u32 s3, s19, 0
	v_lshlrev_b32_e32 v4, 1, v70
	v_mov_b32_e32 v5, v2
	s_waitcnt lgkmcnt(0)
	v_lshl_add_u64 v[4:5], s[2:3], 0, v[4:5]
	s_mov_b64 s[2:3], 0x2600000
	v_lshl_add_u64 v[12:13], v[4:5], 0, s[2:3]
	v_add_u32_e32 v4, v82, v83
	ds_read_b128 v[4:7], v4
	v_or_b32_e32 v8, s0, v81
	v_lshlrev_b32_e32 v8, 13, v8
	v_mov_b32_e32 v9, v2
	v_lshl_add_u64 v[14:15], v[12:13], 0, v[8:9]
	v_add_u32_e32 v8, v85, v86
	ds_read_b128 v[8:11], v8
	s_waitcnt lgkmcnt(1)
	global_store_dwordx4 v[14:15], v[4:7], off nt
	s_nop 1
	v_or_b32_e32 v4, s0, v84
	v_lshlrev_b32_e32 v4, 13, v4
	v_mov_b32_e32 v5, v2
	v_lshl_add_u64 v[4:5], v[12:13], 0, v[4:5]
	s_waitcnt lgkmcnt(0)
	global_store_dwordx4 v[4:5], v[8:11], off nt
	v_add_u32_e32 v4, v88, v89
	ds_read_b128 v[4:7], v4
	v_or_b32_e32 v8, s0, v87
	v_lshlrev_b32_e32 v8, 13, v8
	v_mov_b32_e32 v9, v2
	v_lshl_add_u64 v[14:15], v[12:13], 0, v[8:9]
	v_add_u32_e32 v8, v91, v92
	ds_read_b128 v[8:11], v8
	s_waitcnt lgkmcnt(1)
	global_store_dwordx4 v[14:15], v[4:7], off nt
	s_nop 1
	v_or_b32_e32 v4, s0, v90
	v_lshlrev_b32_e32 v4, 13, v4
	v_mov_b32_e32 v5, v2
	v_lshl_add_u64 v[4:5], v[12:13], 0, v[4:5]
	s_waitcnt lgkmcnt(0)
	global_store_dwordx4 v[4:5], v[8:11], off nt
	v_add_u32_e32 v4, v94, v83
	ds_read_b128 v[4:7], v4
	v_or_b32_e32 v8, s0, v93
	v_lshlrev_b32_e32 v8, 13, v8
	v_mov_b32_e32 v9, v2
	v_lshl_add_u64 v[14:15], v[12:13], 0, v[8:9]
	v_add_u32_e32 v8, v96, v97
	ds_read_b128 v[8:11], v8
	s_waitcnt lgkmcnt(1)
	global_store_dwordx4 v[14:15], v[4:7], off nt
	s_nop 1
	v_or_b32_e32 v4, s0, v95
	v_lshlrev_b32_e32 v4, 13, v4
	v_mov_b32_e32 v5, v2
	v_lshl_add_u64 v[4:5], v[12:13], 0, v[4:5]
	s_waitcnt lgkmcnt(0)
	global_store_dwordx4 v[4:5], v[8:11], off nt
	v_add_u32_e32 v4, v99, v100
	ds_read_b128 v[4:7], v4
	v_or_b32_e32 v8, s0, v98
	v_lshlrev_b32_e32 v8, 13, v8
	v_mov_b32_e32 v9, v2
	v_lshl_add_u64 v[14:15], v[12:13], 0, v[8:9]
	v_add_u32_e32 v8, v102, v103
	ds_read_b128 v[8:11], v8
	s_waitcnt lgkmcnt(1)
	global_store_dwordx4 v[14:15], v[4:7], off nt
	s_nop 1
	v_or_b32_e32 v4, s0, v101
	v_lshlrev_b32_e32 v4, 13, v4
	v_mov_b32_e32 v5, v2
	v_lshl_add_u64 v[4:5], v[12:13], 0, v[4:5]
	s_waitcnt lgkmcnt(0)
	global_store_dwordx4 v[4:5], v[8:11], off nt
	s_waitcnt lgkmcnt(0)
	s_branch .LBB0_624

; #define LAS __attribute__((address_space(3)))
; #define LDS_WAIT() asm volatile("s_waitcnt lgkmcnt(0)" ::: "memory")
; __device__ __forceinline__ unsigned cvt_pk_bf16(float lo, float hi) { unsigned r; asm volatile("v_cvt_pk_bf16_f32 %0, %1, %2" : "=v"(r) : "v"(lo), "v"(hi)); return r; }
;     ...
;         for (int e = 0; e < 4; ++e) *(LAS unsigned*)(scr + (4 * r16 + e) * 128 + ((i ^ (r16 & 7)) * 16) + q * 4) = cvt_pk_bf16(v[2 * i][e], v[2 * i + 1][e]);
;     LDS_WAIT(); asm volatile("" ::: "memory");
;     const int c = lane & 7;
; #pragma unroll
;     for (int j = 0; j < 8; ++j) { const int row = (lane >> 3) + 8 * j; const u32x4 o = *(const LAS u32x4*)(scr + row * 128 + ((c ^ ((row >> 2) & 7)) * 16));
;         const int lc = col_off + n0 + row; int dr;
;         if (MODE == 0) dr = lc;
;         else if (MODE == 1) dr = (lc & ~255) + 128 * ((lc >> 5) & 1) + 32 * ((lc >> 6) & 3) + (lc & 31);
;         else if (MODE == 2) dr = 256 * (lc >> 7) + (lc & 127);
;         else dr = 256 * (lc >> 7) + 128 + (lc & 127);
;         *(u32x4*)(WT + (size_t)dr * (ldt ? ldt : K) + k0 + 8 * c) = o; }
; __device__ __forceinline__ void weights_pass(const Args& a, LAS unsigned char* scr, int gw, int NGW, int lane, int pass) {
;     ...
;         if (r < I_IN) { transpose_item<1>(a.in[I_WIN] + (size_t)l * DM * INW, DM, INW, (bf16_t*)(wl + WL_IN), a.in[I_GMIX] + l * DM, nullptr, 0, scr, r, lane); continue; } r -= I_IN;
.LBB0_1666:
	s_waitcnt vmcnt(0)
	v_cvt_pk_bf16_f32 v60, v60, v64
	v_add_u32_e32 v64, v69, v71
	ds_write_b32 v64, v60
	v_cvt_pk_bf16_f32 v60, v61, v65
	ds_write_b32 v64, v60 offset:128
	v_cvt_pk_bf16_f32 v60, v62, v66
	ds_write_b32 v64, v60 offset:256
	v_cvt_pk_bf16_f32 v60, v63, v67
	ds_write_b32 v64, v60 offset:384
	v_cvt_pk_bf16_f32 v52, v52, v56
	v_add_u32_e32 v56, v73, v71
	ds_write_b32 v56, v52
	v_cvt_pk_bf16_f32 v52, v53, v57
	ds_write_b32 v56, v52 offset:128
	v_cvt_pk_bf16_f32 v52, v54, v58
	ds_write_b32 v56, v52 offset:256
	v_cvt_pk_bf16_f32 v52, v55, v59
	ds_write_b32 v56, v52 offset:384
	v_cvt_pk_bf16_f32 v44, v44, v48
	v_add_u32_e32 v48, v74, v71
	ds_write_b32 v48, v44
	v_cvt_pk_bf16_f32 v44, v45, v49
	ds_write_b32 v48, v44 offset:128
	v_cvt_pk_bf16_f32 v44, v46, v50
	ds_write_b32 v48, v44 offset:256
	v_cvt_pk_bf16_f32 v44, v47, v51
	ds_write_b32 v48, v44 offset:384
	v_cvt_pk_bf16_f32 v28, v28, v40
	v_add_u32_e32 v40, v75, v71
	ds_write_b32 v40, v28
	v_cvt_pk_bf16_f32 v28, v29, v41
	ds_write_b32 v40, v28 offset:128
	v_cvt_pk_bf16_f32 v28, v30, v42
	ds_write_b32 v40, v28 offset:256
	v_cvt_pk_bf16_f32 v28, v31, v43
	ds_write_b32 v40, v28 offset:384
	v_cvt_pk_bf16_f32 v20, v20, v36
	v_add_u32_e32 v28, v76, v71
	ds_write_b32 v28, v20
	v_cvt_pk_bf16_f32 v20, v21, v37
	ds_write_b32 v28, v20 offset:128
	v_cvt_pk_bf16_f32 v20, v22, v38
	ds_write_b32 v28, v20 offset:256
	v_cvt_pk_bf16_f32 v20, v23, v39
	ds_write_b32 v28, v20 offset:384
	v_cvt_pk_bf16_f32 v16, v16, v32
	v_add_u32_e32 v20, v77, v71
	ds_write_b32 v20, v16
	v_cvt_pk_bf16_f32 v16, v17, v33
	ds_write_b32 v20, v16 offset:128
	v_cvt_pk_bf16_f32 v16, v18, v34
	ds_write_b32 v20, v16 offset:256
	v_cvt_pk_bf16_f32 v16, v19, v35
	ds_write_b32 v20, v16 offset:384
	v_cvt_pk_bf16_f32 v8, v8, v24
	v_add_u32_e32 v16, v78, v71
	ds_write_b32 v16, v8
	v_cvt_pk_bf16_f32 v8, v9, v25
	ds_write_b32 v16, v8 offset:128
	v_cvt_pk_bf16_f32 v8, v10, v26
	ds_write_b32 v16, v8 offset:256
	v_cvt_pk_bf16_f32 v8, v11, v27
	ds_write_b32 v16, v8 offset:384
	v_cvt_pk_bf16_f32 v4, v4, v12
	v_add_u32_e32 v8, v79, v71
	ds_write_b32 v8, v4
	v_cvt_pk_bf16_f32 v4, v5, v13
	ds_write_b32 v8, v4 offset:128
	v_cvt_pk_bf16_f32 v4, v6, v14
	s_lshl_b64 s[0:1], s[8:9], 1
	ds_write_b32 v8, v4 offset:256
	v_cvt_pk_bf16_f32 v4, v7, v15
	s_add_u32 s0, s19, s0
	ds_write_b32 v8, v4 offset:384
	s_addc_u32 s1, s20, s1
	v_lshlrev_b32_e32 v4, 1, v70
	v_mov_b32_e32 v5, v2
	s_waitcnt lgkmcnt(0)
	v_lshl_add_u64 v[16:17], s[0:1], 0, v[4:5]
	s_lshr_b32 s0, s6, 1
	v_add_u32_e32 v10, v81, v82
	s_and_b32 s0, s0, 0x60
	s_and_b32 s1, s6, 0xffffff00
	ds_read_b128 v[4:7], v10
	s_or_b32 s1, s0, s1
	v_or_b32_e32 v18, s1, v80
	v_ashrrev_i32_e32 v19, 31, v18
	v_lshlrev_b64 v[8:9], 13, v[18:19]
	v_lshl_add_u64 v[12:13], v[16:17], 0, v[8:9]
	s_waitcnt lgkmcnt(0)
	global_store_dwordx4 v[12:13], v[4:7], off nt
	ds_read_b128 v[8:11], v10 offset:4096
	v_or_b32_e32 v12, s1, v83
	v_add_u32_e32 v4, v84, v85
	ds_read_b128 v[4:7], v4
	v_ashrrev_i32_e32 v13, 31, v12
	v_lshlrev_b64 v[12:13], 13, v[12:13]
	v_lshl_add_u64 v[20:21], v[16:17], 0, v[12:13]
	v_add_u32_e32 v12, v87, v88
	ds_read_b128 v[12:15], v12
	s_waitcnt lgkmcnt(1)
	global_store_dwordx4 v[20:21], v[4:7], off nt
	s_nop 1
	v_or_b32_e32 v4, s1, v86
	v_ashrrev_i32_e32 v5, 31, v4
	v_lshlrev_b64 v[4:5], 13, v[4:5]
	v_lshl_add_u64 v[4:5], v[16:17], 0, v[4:5]
	s_waitcnt lgkmcnt(0)
	global_store_dwordx4 v[4:5], v[12:15], off nt
	v_add_u32_e32 v4, v90, v91
	ds_read_b128 v[4:7], v4
	v_or_b32_e32 v12, s1, v89
	v_ashrrev_i32_e32 v13, 31, v12
	v_lshlrev_b64 v[12:13], 13, v[12:13]
	v_lshl_add_u64 v[20:21], v[16:17], 0, v[12:13]
	v_add_u32_e32 v12, v95, v96
	ds_read_b128 v[12:15], v12
	s_waitcnt lgkmcnt(1)
	global_store_dwordx4 v[20:21], v[4:7], off nt
	s_nop 1
	v_or_b32_e32 v4, 0x80, v18
	v_ashrrev_i32_e32 v5, 31, v4
	v_lshlrev_b64 v[4:5], 13, v[4:5]
	v_lshl_add_u64 v[4:5], v[16:17], 0, v[4:5]
	global_store_dwordx4 v[4:5], v[8:11], off nt
	v_bitop3_b32 v4, s6, v241, v94 bitop3:0xc8
	v_or_b32_e32 v4, s0, v4
	v_or_b32_e32 v4, 0x80, v4
	v_ashrrev_i32_e32 v5, 31, v4
	v_lshlrev_b64 v[4:5], 13, v[4:5]
	v_lshl_add_u64 v[4:5], v[16:17], 0, v[4:5]
	s_waitcnt lgkmcnt(0)
	global_store_dwordx4 v[4:5], v[12:15], off nt
	v_add_u32_e32 v4, v98, v99
	v_bitop3_b32 v8, s6, v242, v97 bitop3:0xc8
	ds_read_b128 v[4:7], v4
	v_or_b32_e32 v8, s0, v8
	v_or_b32_e32 v8, 0x80, v8
	v_ashrrev_i32_e32 v9, 31, v8
	v_lshlrev_b64 v[8:9], 13, v[8:9]
	v_lshl_add_u64 v[12:13], v[16:17], 0, v[8:9]
	v_add_u32_e32 v8, v101, v102
	ds_read_b128 v[8:11], v8
	s_waitcnt lgkmcnt(1)
	global_store_dwordx4 v[12:13], v[4:7], off nt
	s_nop 1
	v_bitop3_b32 v4, s6, v236, v100 bitop3:0xc8
	v_or_b32_e32 v4, s0, v4
	v_or_b32_e32 v4, 0x80, v4
	v_ashrrev_i32_e32 v5, 31, v4
	v_lshlrev_b64 v[4:5], 13, v[4:5]
	v_lshl_add_u64 v[4:5], v[16:17], 0, v[4:5]
	s_waitcnt lgkmcnt(0)
	global_store_dwordx4 v[4:5], v[8:11], off nt
	s_waitcnt lgkmcnt(0)

; __device__ __forceinline__ void weights_pass(const Args& a, LAS unsigned char* scr, int gw, int NGW, int lane, int pass) {
;     ...
;     for (int it = gw + (pass == 1 ? PER_LAYER : 0); it < (pass == 2 ? PER_LAYER : 2 * PER_LAYER); it += NGW) {
;         const int l = it / PER_LAYER; int r = it % PER_LAYER;
;         { const bool shared = (r >= I_IN + I_OUT / 2 && r < I_IN + I_OUT) || (r >= I_IN + I_OUT + I_QM && r < I_IN + I_OUT + 3 * I_QM);
;           const int ip = (shared || (l == 0 && r < I_IN)) ? 0 : (l == 0 ? 2 : 1);
;           if (ip != pass) continue; }
;         unsigned char* wl = ws + WS_W + (size_t)l * WL_SIZE;
;         if (r < I_IN) { transpose_item<1>(a.in[I_WIN] + (size_t)l * DM * INW, DM, INW, (bf16_t*)(wl + WL_IN), a.in[I_GMIX] + l * DM, nullptr, 0, scr, r, lane); continue; } r -= I_IN;
;         if (r < I_OUT / 2) { transpose_item<0>(a.in[I_WOUT] + (size_t)l * DM * DM, 2048, DM, (bf16_t*)(wl + WL_OUT), nullptr, nullptr, 0, scr, r, lane, DM); continue; } r -= I_OUT / 2;
;         if (r < I_OUT / 2) { transpose_item<0>(a.in[I_WOUT] + (size_t)l * DM * DM + (size_t)2048 * DM, 2048, DM, (bf16_t*)(ws + WS_WLOW) + (size_t)l * DM * 2048, nullptr, nullptr, 0, scr, r, lane); continue; } r -= I_OUT / 2;
;         if (r < I_QM) { transpose_item<0>(a.in[I_WQM] + (size_t)l * DM * MW, DM, MW, (bf16_t*)(wl + WL_Q), a.in[I_GCROSS] + l * DM, nullptr, 0, scr, r, lane); continue; } r -= I_QM;
;         if (r < I_QM) { transpose_item<1>(a.in[I_WKM] + (size_t)l * DM * MW, DM, MW, (bf16_t*)(ws + WS_WKV) + (size_t)l * 1024 * DM, a.in[I_GMEM] + l * DM, nullptr, 0, scr, r, lane); continue; } r -= I_QM;
;         if (r < I_QM) { transpose_item<1>(a.in[I_WVM] + (size_t)l * DM * MW, DM, MW, (bf16_t*)(ws + WS_WKV) + (size_t)l * 1024 * DM, a.in[I_GMEM] + l * DM, nullptr, 512, scr, r, lane); continue; } r -= I_QM;
;         if (r < I_OMI) { transpose_item<0>(a.in[I_WOM] + (size_t)l * MW * DM, MW, DM, (bf16_t*)(wl + WL_OM), nullptr, nullptr, 0, scr, r, lane); continue; } r -= I_OMI;
;         if (r < I_G) { transpose_item<2>(a.in[I_WGATE] + (size_t)l * DM * DFF, DM, DFF, (bf16_t*)(wl + WL_GU), a.in[I_GFFN] + l * DM, nullptr, 0, scr, r, lane); continue; } r -= I_G;
;         if (r < I_G) { transpose_item<3>(a.in[I_WUP] + (size_t)l * DM * DFF, DM, DFF, (bf16_t*)(wl + WL_GU), a.in[I_GFFN] + l * DM, nullptr, 0, scr, r, lane); continue; } r -= I_G;
.LBB0_1668:
	s_mul_hi_i32 s0, s10, 0xbfa02fe9
	s_add_i32 s0, s0, s10
	s_lshr_b32 s1, s0, 31
	s_ashr_i32 s0, s0, 15
	s_add_i32 s0, s0, s1
	s_mul_i32 s1, s0, 0xffff5500
	s_add_i32 s21, s10, s1
	s_add_i32 s23, s21, 0xffffe600
	s_cmpk_lt_u32 s23, 0x800
	s_cselect_b64 s[2:3], -1, 0
	s_and_b32 s1, s21, 0xfffffc00
	s_cmpk_eq_i32 s1, 0x2400
	s_cselect_b64 s[6:7], -1, 0
	s_or_b64 s[2:3], s[2:3], s[6:7]
	s_add_i32 s1, s10, 0xffff5500
	s_cmp_gt_u32 s1, 0xfffeaa00
	s_cselect_b64 s[6:7], -1, 0
	s_or_b64 s[2:3], s[6:7], s[2:3]
	s_and_b64 vcc, exec, s[2:3]
	s_cbranch_vccnz .LBB0_1667
	s_ashr_i32 s1, s0, 31
	s_mul_i32 s3, s0, 0x15000000
	v_readlane_b32 s6, v251, 12
	s_mul_hi_i32 s2, s0, 0x15000000
	s_add_u32 s19, s6, s3
	v_readlane_b32 s3, v251, 13
	s_addc_u32 s20, s3, s2
	s_cmpk_gt_i32 s21, 0x11ff
	s_mov_b64 s[6:7], -1
	s_cbranch_scc0 .LBB0_1713
	s_cmpk_gt_u32 s21, 0x19ff
	s_cbranch_scc0 .LBB0_1710
	s_cmpk_gt_u32 s21, 0x21ff
	s_cbranch_scc0 .LBB0_1707
	s_cmpk_gt_u32 s21, 0x23ff
	s_cbranch_scc0 .LBB0_1702
	s_cmpk_gt_u32 s21, 0x25ff
	s_cbranch_scc0 .LBB0_1697
	s_cmpk_gt_u32 s21, 0x27ff
	s_cbranch_scc0 .LBB0_1692
	s_cmpk_gt_u32 s21, 0x29ff
	s_cbranch_scc0 .LBB0_1689
	s_cmpk_gt_u32 s21, 0x54ff
	s_mul_hi_i32 s2, s0, 0xac00000
	s_mul_i32 s3, s0, 0xac00000
	s_cbranch_scc0 .LBB0_1684
	s_cmpk_gt_u32 s21, 0x7fff
	s_cbranch_scc0 .LBB0_1679
	v_readlane_b32 s36, v250, 0
	v_readlane_b32 s42, v250, 6
	v_readlane_b32 s43, v250, 7
	s_add_u32 s8, s42, s3
	s_addc_u32 s9, s43, s2
	s_and_b32 s6, s21, 0xffc0
	s_xor_b32 s7, s6, 0x8000
	s_lshl_b32 s6, s21, 6
	v_lshlrev_b32_e32 v4, 2, v3
	s_and_b32 s6, s6, 0xfc0
	v_lshl_or_b32 v4, s7, 14, v4
	v_mov_b32_e32 v5, v2
	v_lshl_add_u64 v[4:5], s[8:9], 0, v[4:5]
	s_lshl_b32 s14, s6, 2
	v_lshl_add_u64 v[4:5], v[4:5], 0, s[14:15]
	v_lshlrev_b32_e32 v6, 2, v68
	v_mov_b32_e32 v7, v2
	v_lshl_add_u64 v[60:61], v[4:5], 0, v[6:7]
	s_movk_i32 s8, 0x4000
	v_add_co_u32_e32 v8, vcc, s8, v60
	s_mov_b32 s8, 0x24000
	s_nop 0
	v_addc_co_u32_e32 v9, vcc, 0, v61, vcc
	global_load_dwordx4 v[4:7], v[60:61], off nt
	s_nop 0
	global_load_dwordx4 v[8:11], v[8:9], off nt
	v_add_co_u32_e32 v12, vcc, s22, v60
	s_lshl_b32 s7, s7, 1
	s_nop 0
	v_addc_co_u32_e32 v13, vcc, 0, v61, vcc
	v_add_co_u32_e32 v16, vcc, s8, v60
	s_mov_b32 s8, 0x40000
	s_nop 0
	v_addc_co_u32_e32 v17, vcc, 0, v61, vcc
	global_load_dwordx4 v[12:15], v[12:13], off nt
	s_nop 0
	global_load_dwordx4 v[16:19], v[16:17], off nt
	v_add_co_u32_e32 v20, vcc, s8, v60
	s_mov_b32 s8, 0x44000
	s_nop 0
	v_addc_co_u32_e32 v21, vcc, 0, v61, vcc
	v_add_co_u32_e32 v24, vcc, s8, v60
	s_mov_b32 s8, 0x60000
	s_nop 0
	v_addc_co_u32_e32 v25, vcc, 0, v61, vcc
	global_load_dwordx4 v[20:23], v[20:21], off nt
	s_nop 0
	global_load_dwordx4 v[24:27], v[24:25], off nt
	v_add_co_u32_e32 v28, vcc, s8, v60
	s_mov_b32 s8, 0x64000
	s_nop 0
	v_addc_co_u32_e32 v29, vcc, 0, v61, vcc
	v_add_co_u32_e32 v32, vcc, s8, v60
	s_mov_b32 s8, 0x80000
	s_nop 0
	v_addc_co_u32_e32 v33, vcc, 0, v61, vcc
	global_load_dwordx4 v[28:31], v[28:29], off nt
	s_nop 0
	global_load_dwordx4 v[32:35], v[32:33], off nt
	v_add_co_u32_e32 v36, vcc, s8, v60
	s_mov_b32 s8, 0x84000
	s_nop 0
	v_addc_co_u32_e32 v37, vcc, 0, v61, vcc
	v_add_co_u32_e32 v40, vcc, s8, v60
	s_mov_b32 s8, 0xa0000
	s_nop 0
	v_addc_co_u32_e32 v41, vcc, 0, v61, vcc
	global_load_dwordx4 v[36:39], v[36:37], off nt
	s_nop 0
	global_load_dwordx4 v[40:43], v[40:41], off nt
	v_add_co_u32_e32 v44, vcc, s8, v60
	s_mov_b32 s8, 0xa4000
	s_nop 0
	v_addc_co_u32_e32 v45, vcc, 0, v61, vcc
	v_add_co_u32_e32 v48, vcc, s8, v60
	s_mov_b32 s8, 0xc0000
	s_nop 0
	v_addc_co_u32_e32 v49, vcc, 0, v61, vcc
	global_load_dwordx4 v[44:47], v[44:45], off nt
	s_nop 0
	global_load_dwordx4 v[48:51], v[48:49], off nt
	v_add_co_u32_e32 v52, vcc, s8, v60
	s_mov_b32 s8, 0xc4000
	s_nop 0
	v_addc_co_u32_e32 v53, vcc, 0, v61, vcc
	v_add_co_u32_e32 v56, vcc, s8, v60
	s_mov_b32 s8, 0xe0000
	s_nop 0
	v_addc_co_u32_e32 v57, vcc, 0, v61, vcc
	global_load_dwordx4 v[52:55], v[52:53], off nt
	s_nop 0
	global_load_dwordx4 v[56:59], v[56:57], off nt
	v_add_co_u32_e32 v62, vcc, s8, v60
	s_mov_b32 s8, 0xe4000
	s_nop 0
	v_addc_co_u32_e32 v63, vcc, 0, v61, vcc
	v_add_co_u32_e32 v64, vcc, s8, v60
	s_add_u32 s8, s19, s7
	s_nop 0
	v_addc_co_u32_e32 v65, vcc, 0, v61, vcc
	global_load_dwordx4 v[60:63], v[62:63], off nt
	s_nop 0
	global_load_dwordx4 v[64:67], v[64:65], off nt
	s_waitcnt vmcnt(0)
; #define LAS __attribute__((address_space(3)))
; #define LDS_WAIT() asm volatile("s_waitcnt lgkmcnt(0)" ::: "memory")
; __device__ __forceinline__ unsigned cvt_pk_bf16(float lo, float hi) { unsigned r; asm volatile("v_cvt_pk_bf16_f32 %0, %1, %2" : "=v"(r) : "v"(lo), "v"(hi)); return r; }
;     ...
;         for (int e = 0; e < 4; ++e) *(LAS unsigned*)(scr + (4 * r16 + e) * 128 + ((i ^ (r16 & 7)) * 16) + q * 4) = cvt_pk_bf16(v[2 * i][e], v[2 * i + 1][e]);
;     LDS_WAIT(); asm volatile("" ::: "memory");
;     const int c = lane & 7;
; #pragma unroll
;     for (int j = 0; j < 8; ++j) { const int row = (lane >> 3) + 8 * j; const u32x4 o = *(const LAS u32x4*)(scr + row * 128 + ((c ^ ((row >> 2) & 7)) * 16));
;         const int lc = col_off + n0 + row; int dr;
;         if (MODE == 0) dr = lc;
;         else if (MODE == 1) dr = (lc & ~255) + 128 * ((lc >> 5) & 1) + 32 * ((lc >> 6) & 3) + (lc & 31);
;         else if (MODE == 2) dr = 256 * (lc >> 7) + (lc & 127);
;         else dr = 256 * (lc >> 7) + 128 + (lc & 127);
;         *(u32x4*)(WT + (size_t)dr * (ldt ? ldt : K) + k0 + 8 * c) = o; }
; __device__ __forceinline__ void weights_pass(const Args& a, LAS unsigned char* scr, int gw, int NGW, int lane, int pass) {
;     ...
;         transpose_item<0>(a.in[I_WDOWN] + (size_t)l * DFF * DM, DFF, DM, (bf16_t*)(wl + WL_D), nullptr, nullptr, 0, scr, r, lane);
	v_cvt_pk_bf16_f32 v4, v4, v8
	v_add_u32_e32 v8, v69, v71
	ds_write_b32 v8, v4
	v_cvt_pk_bf16_f32 v4, v5, v9
	ds_write_b32 v8, v4 offset:128
	v_cvt_pk_bf16_f32 v4, v6, v10
	ds_write_b32 v8, v4 offset:256
	v_cvt_pk_bf16_f32 v4, v7, v11
	ds_write_b32 v8, v4 offset:384
	v_cvt_pk_bf16_f32 v4, v12, v16
	v_add_u32_e32 v5, v73, v71
	ds_write_b32 v5, v4
	v_cvt_pk_bf16_f32 v4, v13, v17
	ds_write_b32 v5, v4 offset:128
	v_cvt_pk_bf16_f32 v4, v14, v18
	ds_write_b32 v5, v4 offset:256
	v_cvt_pk_bf16_f32 v4, v15, v19
	ds_write_b32 v5, v4 offset:384
	v_cvt_pk_bf16_f32 v4, v20, v24
	v_add_u32_e32 v5, v74, v71
	ds_write_b32 v5, v4
	v_cvt_pk_bf16_f32 v4, v21, v25
	ds_write_b32 v5, v4 offset:128
	v_cvt_pk_bf16_f32 v4, v22, v26
	ds_write_b32 v5, v4 offset:256
	v_cvt_pk_bf16_f32 v4, v23, v27
	ds_write_b32 v5, v4 offset:384
	v_cvt_pk_bf16_f32 v4, v28, v32
	v_add_u32_e32 v5, v75, v71
	ds_write_b32 v5, v4
	v_cvt_pk_bf16_f32 v4, v29, v33
	ds_write_b32 v5, v4 offset:128
	v_cvt_pk_bf16_f32 v4, v30, v34
	ds_write_b32 v5, v4 offset:256
	v_cvt_pk_bf16_f32 v4, v31, v35
	ds_write_b32 v5, v4 offset:384
	v_cvt_pk_bf16_f32 v4, v36, v40
	v_add_u32_e32 v5, v76, v71
	ds_write_b32 v5, v4
	v_cvt_pk_bf16_f32 v4, v37, v41
	ds_write_b32 v5, v4 offset:128
	v_cvt_pk_bf16_f32 v4, v38, v42
	ds_write_b32 v5, v4 offset:256
	v_cvt_pk_bf16_f32 v4, v39, v43
	ds_write_b32 v5, v4 offset:384
	v_cvt_pk_bf16_f32 v4, v44, v48
	v_add_u32_e32 v5, v77, v71
	ds_write_b32 v5, v4
	v_cvt_pk_bf16_f32 v4, v45, v49
	ds_write_b32 v5, v4 offset:128
	v_cvt_pk_bf16_f32 v4, v46, v50
	ds_write_b32 v5, v4 offset:256
	v_cvt_pk_bf16_f32 v4, v47, v51
	ds_write_b32 v5, v4 offset:384
	v_cvt_pk_bf16_f32 v4, v52, v56
	v_add_u32_e32 v5, v78, v71
	ds_write_b32 v5, v4
	v_cvt_pk_bf16_f32 v4, v53, v57
	ds_write_b32 v5, v4 offset:128
	v_cvt_pk_bf16_f32 v4, v54, v58
	ds_write_b32 v5, v4 offset:256
	v_cvt_pk_bf16_f32 v4, v55, v59
	ds_write_b32 v5, v4 offset:384
	v_cvt_pk_bf16_f32 v4, v60, v64
	v_add_u32_e32 v5, v79, v71
	ds_write_b32 v5, v4
	v_cvt_pk_bf16_f32 v4, v61, v65
	ds_write_b32 v5, v4 offset:128
	v_cvt_pk_bf16_f32 v4, v62, v66
	ds_write_b32 v5, v4 offset:256
	v_cvt_pk_bf16_f32 v4, v63, v67
	ds_write_b32 v5, v4 offset:384
	s_addc_u32 s9, s20, 0
	v_lshlrev_b32_e32 v4, 1, v70
	v_mov_b32_e32 v5, v2
	s_waitcnt lgkmcnt(0)
	v_lshl_add_u64 v[4:5], s[8:9], 0, v[4:5]
	s_mov_b64 s[8:9], 0xfa00000
	v_lshl_add_u64 v[12:13], v[4:5], 0, s[8:9]
	v_add_u32_e32 v4, v81, v82
	ds_read_b128 v[4:7], v4
	v_or_b32_e32 v8, s6, v80
	v_mul_u32_u24_e32 v8, 0x2b00, v8
	v_lshlrev_b32_e32 v8, 1, v8
	v_mov_b32_e32 v9, v2
	v_lshl_add_u64 v[14:15], v[12:13], 0, v[8:9]
	v_add_u32_e32 v8, v84, v85
	ds_read_b128 v[8:11], v8
	s_waitcnt lgkmcnt(1)
	global_store_dwordx4 v[14:15], v[4:7], off nt
	v_readlane_b32 s37, v250, 1
	v_readlane_b32 s38, v250, 2
	v_or_b32_e32 v4, s6, v83
	v_mul_u32_u24_e32 v4, 0x2b00, v4
	v_lshlrev_b32_e32 v4, 1, v4
	v_mov_b32_e32 v5, v2
	v_lshl_add_u64 v[4:5], v[12:13], 0, v[4:5]
	s_waitcnt lgkmcnt(0)
	global_store_dwordx4 v[4:5], v[8:11], off nt
	v_add_u32_e32 v4, v87, v88
	ds_read_b128 v[4:7], v4
	v_or_b32_e32 v8, s6, v86
	v_mul_u32_u24_e32 v8, 0x2b00, v8
	v_lshlrev_b32_e32 v8, 1, v8
	v_mov_b32_e32 v9, v2
	v_lshl_add_u64 v[14:15], v[12:13], 0, v[8:9]
	v_add_u32_e32 v8, v90, v91
	ds_read_b128 v[8:11], v8
	s_waitcnt lgkmcnt(1)
	global_store_dwordx4 v[14:15], v[4:7], off nt
	v_readlane_b32 s39, v250, 3
	v_readlane_b32 s40, v250, 4
	v_or_b32_e32 v4, s6, v89
	v_mul_u32_u24_e32 v4, 0x2b00, v4
	v_lshlrev_b32_e32 v4, 1, v4
	v_mov_b32_e32 v5, v2
	v_lshl_add_u64 v[4:5], v[12:13], 0, v[4:5]
	s_waitcnt lgkmcnt(0)
	global_store_dwordx4 v[4:5], v[8:11], off nt
	v_add_u32_e32 v4, v93, v82
	ds_read_b128 v[4:7], v4
	v_or_b32_e32 v8, s6, v92
	v_mul_u32_u24_e32 v8, 0x2b00, v8
	v_lshlrev_b32_e32 v8, 1, v8
	v_mov_b32_e32 v9, v2
	v_lshl_add_u64 v[14:15], v[12:13], 0, v[8:9]
	v_add_u32_e32 v8, v95, v96
	ds_read_b128 v[8:11], v8
	s_waitcnt lgkmcnt(1)
	global_store_dwordx4 v[14:15], v[4:7], off nt
	v_readlane_b32 s41, v250, 5
	s_nop 0
	v_or_b32_e32 v4, s6, v94
	v_mul_u32_u24_e32 v4, 0x2b00, v4
	v_lshlrev_b32_e32 v4, 1, v4
	v_mov_b32_e32 v5, v2
	v_lshl_add_u64 v[4:5], v[12:13], 0, v[4:5]
	s_waitcnt lgkmcnt(0)
	global_store_dwordx4 v[4:5], v[8:11], off nt
	v_add_u32_e32 v4, v98, v99
	ds_read_b128 v[4:7], v4
	v_or_b32_e32 v8, s6, v97
	v_mul_u32_u24_e32 v8, 0x2b00, v8
	v_lshlrev_b32_e32 v8, 1, v8
	v_mov_b32_e32 v9, v2
	v_lshl_add_u64 v[14:15], v[12:13], 0, v[8:9]
	v_add_u32_e32 v8, v101, v102
	ds_read_b128 v[8:11], v8
	s_waitcnt lgkmcnt(1)
	global_store_dwordx4 v[14:15], v[4:7], off nt
	s_nop 1
	v_or_b32_e32 v4, s6, v100
	v_mul_u32_u24_e32 v4, 0x2b00, v4
	v_lshlrev_b32_e32 v4, 1, v4
	v_mov_b32_e32 v5, v2
	v_lshl_add_u64 v[4:5], v[12:13], 0, v[4:5]
	s_waitcnt lgkmcnt(0)
	global_store_dwordx4 v[4:5], v[8:11], off nt
	s_waitcnt lgkmcnt(0)
	s_mov_b64 s[6:7], 0

; #define LAS __attribute__((address_space(3)))
; #define LDS_WAIT() asm volatile("s_waitcnt lgkmcnt(0)" ::: "memory")
; __device__ __forceinline__ unsigned cvt_pk_bf16(float lo, float hi) { unsigned r; asm volatile("v_cvt_pk_bf16_f32 %0, %1, %2" : "=v"(r) : "v"(lo), "v"(hi)); return r; }
;     ...
;         for (int e = 0; e < 4; ++e) *(LAS unsigned*)(scr + (4 * r16 + e) * 128 + ((i ^ (r16 & 7)) * 16) + q * 4) = cvt_pk_bf16(v[2 * i][e], v[2 * i + 1][e]);
;     LDS_WAIT(); asm volatile("" ::: "memory");
;     const int c = lane & 7;
; #pragma unroll
;     for (int j = 0; j < 8; ++j) { const int row = (lane >> 3) + 8 * j; const u32x4 o = *(const LAS u32x4*)(scr + row * 128 + ((c ^ ((row >> 2) & 7)) * 16));
;         const int lc = col_off + n0 + row; int dr;
;         if (MODE == 0) dr = lc;
;         else if (MODE == 1) dr = (lc & ~255) + 128 * ((lc >> 5) & 1) + 32 * ((lc >> 6) & 3) + (lc & 31);
;         else if (MODE == 2) dr = 256 * (lc >> 7) + (lc & 127);
;         else dr = 256 * (lc >> 7) + 128 + (lc & 127);
;         *(u32x4*)(WT + (size_t)dr * (ldt ? ldt : K) + k0 + 8 * c) = o; }
; __device__ __forceinline__ void weights_pass(const Args& a, LAS unsigned char* scr, int gw, int NGW, int lane, int pass) {
;     ...
;         if (r < I_G) { transpose_item<3>(a.in[I_WUP] + (size_t)l * DM * DFF, DM, DFF, (bf16_t*)(wl + WL_GU), a.in[I_GFFN] + l * DM, nullptr, 0, scr, r, lane); continue; } r -= I_G;
.LBB0_1682:
	s_waitcnt vmcnt(0)
	v_cvt_pk_bf16_f32 v60, v60, v64
	v_add_u32_e32 v64, v69, v71
	ds_write_b32 v64, v60
	v_cvt_pk_bf16_f32 v60, v61, v65
	ds_write_b32 v64, v60 offset:128
	v_cvt_pk_bf16_f32 v60, v62, v66
	ds_write_b32 v64, v60 offset:256
	v_cvt_pk_bf16_f32 v60, v63, v67
	ds_write_b32 v64, v60 offset:384
	v_cvt_pk_bf16_f32 v52, v52, v56
	v_add_u32_e32 v56, v73, v71
	ds_write_b32 v56, v52
	v_cvt_pk_bf16_f32 v52, v53, v57
	ds_write_b32 v56, v52 offset:128
	v_cvt_pk_bf16_f32 v52, v54, v58
	ds_write_b32 v56, v52 offset:256
	v_cvt_pk_bf16_f32 v52, v55, v59
	ds_write_b32 v56, v52 offset:384
	v_cvt_pk_bf16_f32 v44, v44, v48
	v_add_u32_e32 v48, v74, v71
	ds_write_b32 v48, v44
	v_cvt_pk_bf16_f32 v44, v45, v49
	ds_write_b32 v48, v44 offset:128
	v_cvt_pk_bf16_f32 v44, v46, v50
	ds_write_b32 v48, v44 offset:256
	v_cvt_pk_bf16_f32 v44, v47, v51
	ds_write_b32 v48, v44 offset:384
	v_cvt_pk_bf16_f32 v36, v36, v40
	v_add_u32_e32 v40, v75, v71
	ds_write_b32 v40, v36
	v_cvt_pk_bf16_f32 v36, v37, v41
	ds_write_b32 v40, v36 offset:128
	v_cvt_pk_bf16_f32 v36, v38, v42
	ds_write_b32 v40, v36 offset:256
	v_cvt_pk_bf16_f32 v36, v39, v43
	ds_write_b32 v40, v36 offset:384
	v_cvt_pk_bf16_f32 v20, v20, v32
	v_add_u32_e32 v32, v76, v71
	ds_write_b32 v32, v20
	v_cvt_pk_bf16_f32 v20, v21, v33
	ds_write_b32 v32, v20 offset:128
	v_cvt_pk_bf16_f32 v20, v22, v34
	ds_write_b32 v32, v20 offset:256
	v_cvt_pk_bf16_f32 v20, v23, v35
	ds_write_b32 v32, v20 offset:384
	v_cvt_pk_bf16_f32 v16, v16, v28
	v_add_u32_e32 v20, v77, v71
	ds_write_b32 v20, v16
	v_cvt_pk_bf16_f32 v16, v17, v29
	ds_write_b32 v20, v16 offset:128
	v_cvt_pk_bf16_f32 v16, v18, v30
	ds_write_b32 v20, v16 offset:256
	v_cvt_pk_bf16_f32 v16, v19, v31
	ds_write_b32 v20, v16 offset:384
	v_cvt_pk_bf16_f32 v8, v8, v24
	v_add_u32_e32 v16, v78, v71
	ds_write_b32 v16, v8
	v_cvt_pk_bf16_f32 v8, v9, v25
	ds_write_b32 v16, v8 offset:128
	v_cvt_pk_bf16_f32 v8, v10, v26
	ds_write_b32 v16, v8 offset:256
	v_cvt_pk_bf16_f32 v8, v11, v27
	s_lshl_b32 s6, s9, 6
	ds_write_b32 v16, v8 offset:384
	v_cvt_pk_bf16_f32 v4, v4, v12
	v_add_u32_e32 v8, v79, v71
	ds_write_b32 v8, v4
	v_cvt_pk_bf16_f32 v4, v5, v13
	s_lshl_b32 s7, s9, 7
	s_and_b32 s6, s6, 64
	ds_write_b32 v8, v4 offset:128
	v_cvt_pk_bf16_f32 v4, v6, v14
	s_or_b32 s9, s6, s7
	s_lshl_b32 s6, s8, 1
	ds_write_b32 v8, v4 offset:256
	v_cvt_pk_bf16_f32 v4, v7, v15
	s_add_u32 s6, s19, s6
	ds_write_b32 v8, v4 offset:384
	s_addc_u32 s7, s20, 0
	v_lshlrev_b32_e32 v4, 1, v70
	v_mov_b32_e32 v5, v2
	s_waitcnt lgkmcnt(0)
	v_lshl_add_u64 v[4:5], s[6:7], 0, v[4:5]
	s_mov_b64 s[6:7], 0x4e00000
	v_lshl_add_u64 v[12:13], v[4:5], 0, s[6:7]
	v_add_u32_e32 v4, v81, v82
	ds_read_b128 v[4:7], v4
	v_or_b32_e32 v8, s9, v80
	v_mov_b32_e32 v16, 0x100000
	v_lshl_or_b32 v8, v8, 13, v16
	v_mov_b32_e32 v9, v2
	v_lshl_add_u64 v[14:15], v[12:13], 0, v[8:9]
	v_add_u32_e32 v8, v84, v85
	ds_read_b128 v[8:11], v8
	s_waitcnt lgkmcnt(1)
	global_store_dwordx4 v[14:15], v[4:7], off nt
	s_nop 1
	v_or_b32_e32 v4, s9, v83
	v_lshl_or_b32 v4, v4, 13, v16
	v_mov_b32_e32 v5, v2
	v_lshl_add_u64 v[4:5], v[12:13], 0, v[4:5]
	s_waitcnt lgkmcnt(0)
	global_store_dwordx4 v[4:5], v[8:11], off nt
	v_add_u32_e32 v4, v87, v88
	ds_read_b128 v[4:7], v4
	v_or_b32_e32 v8, s9, v86
	v_lshl_or_b32 v8, v8, 13, v16
	v_mov_b32_e32 v9, v2
	v_lshl_add_u64 v[14:15], v[12:13], 0, v[8:9]
	v_add_u32_e32 v8, v90, v91
	ds_read_b128 v[8:11], v8
	s_waitcnt lgkmcnt(1)
	global_store_dwordx4 v[14:15], v[4:7], off nt
	s_nop 1
	v_or_b32_e32 v4, s9, v89
	v_lshl_or_b32 v4, v4, 13, v16
	v_mov_b32_e32 v5, v2
	v_lshl_add_u64 v[4:5], v[12:13], 0, v[4:5]
	s_waitcnt lgkmcnt(0)
	global_store_dwordx4 v[4:5], v[8:11], off nt
	v_add_u32_e32 v4, v93, v82
	ds_read_b128 v[4:7], v4
	v_or_b32_e32 v8, s9, v92
	v_lshl_or_b32 v8, v8, 13, v16
	v_mov_b32_e32 v9, v2
	v_lshl_add_u64 v[14:15], v[12:13], 0, v[8:9]
	v_add_u32_e32 v8, v95, v96
	ds_read_b128 v[8:11], v8
	s_waitcnt lgkmcnt(1)
	global_store_dwordx4 v[14:15], v[4:7], off nt
	s_nop 1
	v_or_b32_e32 v4, s9, v94
	v_lshl_or_b32 v4, v4, 13, v16
	v_mov_b32_e32 v5, v2
	v_lshl_add_u64 v[4:5], v[12:13], 0, v[4:5]
	s_waitcnt lgkmcnt(0)
	global_store_dwordx4 v[4:5], v[8:11], off nt
	v_add_u32_e32 v4, v98, v99
	ds_read_b128 v[4:7], v4
	v_or_b32_e32 v8, s9, v97
	v_lshl_or_b32 v8, v8, 13, v16
	v_mov_b32_e32 v9, v2
	v_lshl_add_u64 v[14:15], v[12:13], 0, v[8:9]
	v_add_u32_e32 v8, v101, v102
	ds_read_b128 v[8:11], v8
	s_waitcnt lgkmcnt(1)
	global_store_dwordx4 v[14:15], v[4:7], off nt
	s_nop 1
	v_or_b32_e32 v4, s9, v100
	v_lshl_or_b32 v4, v4, 13, v16
	v_mov_b32_e32 v5, v2
	v_lshl_add_u64 v[4:5], v[12:13], 0, v[4:5]
	s_waitcnt lgkmcnt(0)
	global_store_dwordx4 v[4:5], v[8:11], off nt
	s_waitcnt lgkmcnt(0)

; #define LAS __attribute__((address_space(3)))
; #define LDS_WAIT() asm volatile("s_waitcnt lgkmcnt(0)" ::: "memory")
; __device__ __forceinline__ unsigned cvt_pk_bf16(float lo, float hi) { unsigned r; asm volatile("v_cvt_pk_bf16_f32 %0, %1, %2" : "=v"(r) : "v"(lo), "v"(hi)); return r; }
;     ...
;         for (int e = 0; e < 4; ++e) *(LAS unsigned*)(scr + (4 * r16 + e) * 128 + ((i ^ (r16 & 7)) * 16) + q * 4) = cvt_pk_bf16(v[2 * i][e], v[2 * i + 1][e]);
;     LDS_WAIT(); asm volatile("" ::: "memory");
;     const int c = lane & 7;
; #pragma unroll
;     for (int j = 0; j < 8; ++j) { const int row = (lane >> 3) + 8 * j; const u32x4 o = *(const LAS u32x4*)(scr + row * 128 + ((c ^ ((row >> 2) & 7)) * 16));
;         const int lc = col_off + n0 + row; int dr;
;         if (MODE == 0) dr = lc;
;         else if (MODE == 1) dr = (lc & ~255) + 128 * ((lc >> 5) & 1) + 32 * ((lc >> 6) & 3) + (lc & 31);
;         else if (MODE == 2) dr = 256 * (lc >> 7) + (lc & 127);
;         else dr = 256 * (lc >> 7) + 128 + (lc & 127);
;         *(u32x4*)(WT + (size_t)dr * (ldt ? ldt : K) + k0 + 8 * c) = o; }
; __device__ __forceinline__ void weights_pass(const Args& a, LAS unsigned char* scr, int gw, int NGW, int lane, int pass) {
;     ...
;         if (r < I_G) { transpose_item<2>(a.in[I_WGATE] + (size_t)l * DM * DFF, DM, DFF, (bf16_t*)(wl + WL_GU), a.in[I_GFFN] + l * DM, nullptr, 0, scr, r, lane); continue; } r -= I_G;
.LBB0_1687:
	s_waitcnt vmcnt(0)
	v_cvt_pk_bf16_f32 v60, v60, v64
	v_add_u32_e32 v64, v69, v71
	ds_write_b32 v64, v60
	v_cvt_pk_bf16_f32 v60, v61, v65
	ds_write_b32 v64, v60 offset:128
	v_cvt_pk_bf16_f32 v60, v62, v66
	ds_write_b32 v64, v60 offset:256
	v_cvt_pk_bf16_f32 v60, v63, v67
	ds_write_b32 v64, v60 offset:384
	v_cvt_pk_bf16_f32 v52, v52, v56
	v_add_u32_e32 v56, v73, v71
	ds_write_b32 v56, v52
	v_cvt_pk_bf16_f32 v52, v53, v57
	ds_write_b32 v56, v52 offset:128
	v_cvt_pk_bf16_f32 v52, v54, v58
	ds_write_b32 v56, v52 offset:256
	v_cvt_pk_bf16_f32 v52, v55, v59
	ds_write_b32 v56, v52 offset:384
	v_cvt_pk_bf16_f32 v44, v44, v48
	v_add_u32_e32 v48, v74, v71
	ds_write_b32 v48, v44
	v_cvt_pk_bf16_f32 v44, v45, v49
	ds_write_b32 v48, v44 offset:128
	v_cvt_pk_bf16_f32 v44, v46, v50
	ds_write_b32 v48, v44 offset:256
	v_cvt_pk_bf16_f32 v44, v47, v51
	ds_write_b32 v48, v44 offset:384
	v_cvt_pk_bf16_f32 v36, v36, v40
	v_add_u32_e32 v40, v75, v71
	ds_write_b32 v40, v36
	v_cvt_pk_bf16_f32 v36, v37, v41
	ds_write_b32 v40, v36 offset:128
	v_cvt_pk_bf16_f32 v36, v38, v42
	ds_write_b32 v40, v36 offset:256
	v_cvt_pk_bf16_f32 v36, v39, v43
	ds_write_b32 v40, v36 offset:384
	v_cvt_pk_bf16_f32 v20, v20, v32
	v_add_u32_e32 v32, v76, v71
	ds_write_b32 v32, v20
	v_cvt_pk_bf16_f32 v20, v21, v33
	ds_write_b32 v32, v20 offset:128
	v_cvt_pk_bf16_f32 v20, v22, v34
	ds_write_b32 v32, v20 offset:256
	v_cvt_pk_bf16_f32 v20, v23, v35
	ds_write_b32 v32, v20 offset:384
	v_cvt_pk_bf16_f32 v16, v16, v28
	v_add_u32_e32 v20, v77, v71
	ds_write_b32 v20, v16
	v_cvt_pk_bf16_f32 v16, v17, v29
	ds_write_b32 v20, v16 offset:128
	v_cvt_pk_bf16_f32 v16, v18, v30
	ds_write_b32 v20, v16 offset:256
	v_cvt_pk_bf16_f32 v16, v19, v31
	ds_write_b32 v20, v16 offset:384
	v_cvt_pk_bf16_f32 v8, v8, v24
	v_add_u32_e32 v16, v78, v71
	ds_write_b32 v16, v8
	v_cvt_pk_bf16_f32 v8, v9, v25
	ds_write_b32 v16, v8 offset:128
	v_cvt_pk_bf16_f32 v8, v10, v26
	ds_write_b32 v16, v8 offset:256
	v_cvt_pk_bf16_f32 v8, v11, v27
	s_lshl_b32 s6, s3, 6
	ds_write_b32 v16, v8 offset:384
	v_cvt_pk_bf16_f32 v4, v4, v12
	v_add_u32_e32 v8, v79, v71
	s_lshl_b32 s3, s3, 7
	ds_write_b32 v8, v4
	v_cvt_pk_bf16_f32 v4, v5, v13
	s_and_b32 s3, s3, 0x7f00
	s_and_b32 s6, s6, 64
	ds_write_b32 v8, v4 offset:128
	v_cvt_pk_bf16_f32 v4, v6, v14
	s_or_b32 s6, s6, s3
	s_lshl_b32 s2, s2, 1
	ds_write_b32 v8, v4 offset:256
	v_cvt_pk_bf16_f32 v4, v7, v15
	s_add_u32 s2, s19, s2
	ds_write_b32 v8, v4 offset:384
	s_addc_u32 s3, s20, 0
	v_lshlrev_b32_e32 v4, 1, v70
	v_mov_b32_e32 v5, v2
	s_waitcnt lgkmcnt(0)
	v_lshl_add_u64 v[4:5], s[2:3], 0, v[4:5]
	s_mov_b64 s[2:3], 0x4e00000
	v_lshl_add_u64 v[12:13], v[4:5], 0, s[2:3]
	v_add_u32_e32 v4, v81, v82
	ds_read_b128 v[4:7], v4
	v_or_b32_e32 v8, s6, v80
	v_lshlrev_b32_e32 v8, 13, v8
	v_mov_b32_e32 v9, v2
	v_lshl_add_u64 v[14:15], v[12:13], 0, v[8:9]
	v_add_u32_e32 v8, v84, v85
	ds_read_b128 v[8:11], v8
	s_waitcnt lgkmcnt(1)
	global_store_dwordx4 v[14:15], v[4:7], off nt
	s_nop 1
	v_or_b32_e32 v4, s6, v83
	v_lshlrev_b32_e32 v4, 13, v4
	v_mov_b32_e32 v5, v2
	v_lshl_add_u64 v[4:5], v[12:13], 0, v[4:5]
	s_waitcnt lgkmcnt(0)
	global_store_dwordx4 v[4:5], v[8:11], off nt
	v_add_u32_e32 v4, v87, v88
	ds_read_b128 v[4:7], v4
	v_or_b32_e32 v8, s6, v86
	v_lshlrev_b32_e32 v8, 13, v8
	v_mov_b32_e32 v9, v2
	v_lshl_add_u64 v[14:15], v[12:13], 0, v[8:9]
	v_add_u32_e32 v8, v90, v91
	ds_read_b128 v[8:11], v8
	s_waitcnt lgkmcnt(1)
	global_store_dwordx4 v[14:15], v[4:7], off nt
	s_nop 1
	v_or_b32_e32 v4, s6, v89
	v_lshlrev_b32_e32 v4, 13, v4
	v_mov_b32_e32 v5, v2
	v_lshl_add_u64 v[4:5], v[12:13], 0, v[4:5]
	s_waitcnt lgkmcnt(0)
	global_store_dwordx4 v[4:5], v[8:11], off nt
	v_add_u32_e32 v4, v93, v82
	ds_read_b128 v[4:7], v4
	v_or_b32_e32 v8, s6, v92
	v_lshlrev_b32_e32 v8, 13, v8
	v_mov_b32_e32 v9, v2
	v_lshl_add_u64 v[14:15], v[12:13], 0, v[8:9]
	v_add_u32_e32 v8, v95, v96
	ds_read_b128 v[8:11], v8
	s_waitcnt lgkmcnt(1)
	global_store_dwordx4 v[14:15], v[4:7], off nt
	s_nop 1
	v_or_b32_e32 v4, s6, v94
	v_lshlrev_b32_e32 v4, 13, v4
	v_mov_b32_e32 v5, v2
	v_lshl_add_u64 v[4:5], v[12:13], 0, v[4:5]
	s_waitcnt lgkmcnt(0)
	global_store_dwordx4 v[4:5], v[8:11], off nt
	v_add_u32_e32 v4, v98, v99
	ds_read_b128 v[4:7], v4
	v_or_b32_e32 v8, s6, v97
	v_lshlrev_b32_e32 v8, 13, v8
	v_mov_b32_e32 v9, v2
	v_lshl_add_u64 v[14:15], v[12:13], 0, v[8:9]
	v_add_u32_e32 v8, v101, v102
	ds_read_b128 v[8:11], v8
	s_waitcnt lgkmcnt(1)
	global_store_dwordx4 v[14:15], v[4:7], off nt
	s_nop 1
	v_or_b32_e32 v4, s6, v100
	v_lshlrev_b32_e32 v4, 13, v4
	v_mov_b32_e32 v5, v2
	v_lshl_add_u64 v[4:5], v[12:13], 0, v[4:5]
	s_waitcnt lgkmcnt(0)
	global_store_dwordx4 v[4:5], v[8:11], off nt
	s_waitcnt lgkmcnt(0)

;     const int nblk = N / 64, kb = item / nblk, nb = item % nblk, k0 = 64 * kb, n0 = 64 * nb;
;     const int r16 = lane & 15, q = lane >> 4;
;     const float* src = W + (size_t)(k0 + 2 * q) * N + n0 + 4 * r16;
;     f32x4 v[16];
; #pragma unroll
;     for (int j = 0; j < 16; ++j) v[j] = *(const f32x4*)(src + (size_t)(8 * (j >> 1) + (j & 1)) * N);
; __device__ __forceinline__ void weights_pass(const Args& a, LAS unsigned char* scr, int gw, int NGW, int lane, int pass) {
;     ...
;         if (r < I_OMI) { transpose_item<0>(a.in[I_WOM] + (size_t)l * MW * DM, MW, DM, (bf16_t*)(wl + WL_OM), nullptr, nullptr, 0, scr, r, lane); continue; } r -= I_OMI;
.LBB0_1689:
	s_andn2_b64 vcc, exec, s[6:7]
	s_cbranch_vccnz .LBB0_1691
	v_readlane_b32 s36, v250, 46
	s_lshl_b64 s[2:3], s[0:1], 23
	v_readlane_b32 s50, v250, 60
	v_readlane_b32 s51, v250, 61
	s_add_u32 s6, s50, s2
	s_addc_u32 s7, s51, s3
	s_add_i32 s2, s21, 0xd800
	s_and_b32 s3, s2, 0xffc0
	s_lshl_b32 s2, s21, 6
	v_lshlrev_b32_e32 v4, 2, v3
	s_and_b32 s2, s2, 0xfc0
	v_lshl_or_b32 v4, s3, 14, v4
	v_mov_b32_e32 v5, v2
	v_lshl_add_u64 v[4:5], s[6:7], 0, v[4:5]
	s_lshl_b32 s14, s2, 2
	v_lshl_add_u64 v[4:5], v[4:5], 0, s[14:15]
	v_lshlrev_b32_e32 v6, 2, v68
	v_mov_b32_e32 v7, v2
	v_lshl_add_u64 v[60:61], v[4:5], 0, v[6:7]
	s_movk_i32 s6, 0x4000
	v_add_co_u32_e32 v8, vcc, s6, v60
	s_mov_b32 s6, 0x24000
	s_nop 0
	v_addc_co_u32_e32 v9, vcc, 0, v61, vcc
	global_load_dwordx4 v[4:7], v[60:61], off nt
	s_nop 0
	global_load_dwordx4 v[8:11], v[8:9], off nt
	v_add_co_u32_e32 v12, vcc, s22, v60
	s_lshl_b32 s3, s3, 1
	s_nop 0
	v_addc_co_u32_e32 v13, vcc, 0, v61, vcc
	v_add_co_u32_e32 v16, vcc, s6, v60
	s_mov_b32 s6, 0x40000
	s_nop 0
	v_addc_co_u32_e32 v17, vcc, 0, v61, vcc
	global_load_dwordx4 v[12:15], v[12:13], off nt
	s_nop 0
	global_load_dwordx4 v[16:19], v[16:17], off nt
	v_add_co_u32_e32 v20, vcc, s6, v60
	s_mov_b32 s6, 0x44000
	s_nop 0
	v_addc_co_u32_e32 v21, vcc, 0, v61, vcc
	v_add_co_u32_e32 v24, vcc, s6, v60
	s_mov_b32 s6, 0x60000
	s_nop 0
	v_addc_co_u32_e32 v25, vcc, 0, v61, vcc
	global_load_dwordx4 v[20:23], v[20:21], off nt
	s_nop 0
	global_load_dwordx4 v[24:27], v[24:25], off nt
	v_add_co_u32_e32 v28, vcc, s6, v60
	s_mov_b32 s6, 0x64000
	s_nop 0
	v_addc_co_u32_e32 v29, vcc, 0, v61, vcc
	v_add_co_u32_e32 v32, vcc, s6, v60
	s_mov_b32 s6, 0x80000
	s_nop 0
	v_addc_co_u32_e32 v33, vcc, 0, v61, vcc
	global_load_dwordx4 v[28:31], v[28:29], off nt
	s_nop 0
	global_load_dwordx4 v[32:35], v[32:33], off nt
	v_add_co_u32_e32 v36, vcc, s6, v60
	s_mov_b32 s6, 0x84000
	s_nop 0
	v_addc_co_u32_e32 v37, vcc, 0, v61, vcc
	v_add_co_u32_e32 v40, vcc, s6, v60
	s_mov_b32 s6, 0xa0000
	s_nop 0
	v_addc_co_u32_e32 v41, vcc, 0, v61, vcc
	global_load_dwordx4 v[36:39], v[36:37], off nt
	s_nop 0
	global_load_dwordx4 v[40:43], v[40:41], off nt
	v_add_co_u32_e32 v44, vcc, s6, v60
	s_mov_b32 s6, 0xa4000
	s_nop 0
	v_addc_co_u32_e32 v45, vcc, 0, v61, vcc
	v_add_co_u32_e32 v48, vcc, s6, v60
	s_mov_b32 s6, 0xc0000
	s_nop 0
	v_addc_co_u32_e32 v49, vcc, 0, v61, vcc
	global_load_dwordx4 v[44:47], v[44:45], off nt
	s_nop 0
	global_load_dwordx4 v[48:51], v[48:49], off nt
	v_add_co_u32_e32 v52, vcc, s6, v60
	s_mov_b32 s6, 0xc4000
	s_nop 0
	v_addc_co_u32_e32 v53, vcc, 0, v61, vcc
	v_add_co_u32_e32 v56, vcc, s6, v60
	s_mov_b32 s6, 0xe0000
	s_nop 0
	v_addc_co_u32_e32 v57, vcc, 0, v61, vcc
	global_load_dwordx4 v[52:55], v[52:53], off nt
	s_nop 0
	global_load_dwordx4 v[56:59], v[56:57], off nt
	v_add_co_u32_e32 v62, vcc, s6, v60
	s_mov_b32 s6, 0xe4000
	s_nop 0
	v_addc_co_u32_e32 v63, vcc, 0, v61, vcc
	v_add_co_u32_e32 v64, vcc, s6, v60
	s_add_u32 s6, s19, s3
	s_nop 0
	v_addc_co_u32_e32 v65, vcc, 0, v61, vcc
	global_load_dwordx4 v[60:63], v[62:63], off nt
	s_nop 0
	global_load_dwordx4 v[64:67], v[64:65], off nt
	s_waitcnt vmcnt(0)
; #define LAS __attribute__((address_space(3)))
; #define LDS_WAIT() asm volatile("s_waitcnt lgkmcnt(0)" ::: "memory")
; __device__ __forceinline__ unsigned cvt_pk_bf16(float lo, float hi) { unsigned r; asm volatile("v_cvt_pk_bf16_f32 %0, %1, %2" : "=v"(r) : "v"(lo), "v"(hi)); return r; }
;     ...
;         for (int e = 0; e < 4; ++e) *(LAS unsigned*)(scr + (4 * r16 + e) * 128 + ((i ^ (r16 & 7)) * 16) + q * 4) = cvt_pk_bf16(v[2 * i][e], v[2 * i + 1][e]);
;     LDS_WAIT(); asm volatile("" ::: "memory");
;     const int c = lane & 7;
; #pragma unroll
;     for (int j = 0; j < 8; ++j) { const int row = (lane >> 3) + 8 * j; const u32x4 o = *(const LAS u32x4*)(scr + row * 128 + ((c ^ ((row >> 2) & 7)) * 16));
;         const int lc = col_off + n0 + row; int dr;
;         if (MODE == 0) dr = lc;
;         else if (MODE == 1) dr = (lc & ~255) + 128 * ((lc >> 5) & 1) + 32 * ((lc >> 6) & 3) + (lc & 31);
;         else if (MODE == 2) dr = 256 * (lc >> 7) + (lc & 127);
;         else dr = 256 * (lc >> 7) + 128 + (lc & 127);
;         *(u32x4*)(WT + (size_t)dr * (ldt ? ldt : K) + k0 + 8 * c) = o; }
; __device__ __forceinline__ void weights_pass(const Args& a, LAS unsigned char* scr, int gw, int NGW, int lane, int pass) {
;     ...
;         if (r < I_OMI) { transpose_item<0>(a.in[I_WOM] + (size_t)l * MW * DM, MW, DM, (bf16_t*)(wl + WL_OM), nullptr, nullptr, 0, scr, r, lane); continue; } r -= I_OMI;
	v_cvt_pk_bf16_f32 v4, v4, v8
	v_add_u32_e32 v8, v69, v71
	ds_write_b32 v8, v4
	v_cvt_pk_bf16_f32 v4, v5, v9
	ds_write_b32 v8, v4 offset:128
	v_cvt_pk_bf16_f32 v4, v6, v10
	ds_write_b32 v8, v4 offset:256
	v_cvt_pk_bf16_f32 v4, v7, v11
	ds_write_b32 v8, v4 offset:384
	v_cvt_pk_bf16_f32 v4, v12, v16
	v_add_u32_e32 v5, v73, v71
	ds_write_b32 v5, v4
	v_cvt_pk_bf16_f32 v4, v13, v17
	ds_write_b32 v5, v4 offset:128
	v_cvt_pk_bf16_f32 v4, v14, v18
	ds_write_b32 v5, v4 offset:256
	v_cvt_pk_bf16_f32 v4, v15, v19
	ds_write_b32 v5, v4 offset:384
	v_cvt_pk_bf16_f32 v4, v20, v24
	v_add_u32_e32 v5, v74, v71
	ds_write_b32 v5, v4
	v_cvt_pk_bf16_f32 v4, v21, v25
	ds_write_b32 v5, v4 offset:128
	v_cvt_pk_bf16_f32 v4, v22, v26
	ds_write_b32 v5, v4 offset:256
	v_cvt_pk_bf16_f32 v4, v23, v27
	ds_write_b32 v5, v4 offset:384
	v_cvt_pk_bf16_f32 v4, v28, v32
	v_add_u32_e32 v5, v75, v71
	ds_write_b32 v5, v4
	v_cvt_pk_bf16_f32 v4, v29, v33
	ds_write_b32 v5, v4 offset:128
	v_cvt_pk_bf16_f32 v4, v30, v34
	ds_write_b32 v5, v4 offset:256
	v_cvt_pk_bf16_f32 v4, v31, v35
	ds_write_b32 v5, v4 offset:384
	v_cvt_pk_bf16_f32 v4, v36, v40
	v_add_u32_e32 v5, v76, v71
	ds_write_b32 v5, v4
	v_cvt_pk_bf16_f32 v4, v37, v41
	ds_write_b32 v5, v4 offset:128
	v_cvt_pk_bf16_f32 v4, v38, v42
	ds_write_b32 v5, v4 offset:256
	v_cvt_pk_bf16_f32 v4, v39, v43
	ds_write_b32 v5, v4 offset:384
	v_cvt_pk_bf16_f32 v4, v44, v48
	v_add_u32_e32 v5, v77, v71
	ds_write_b32 v5, v4
	v_cvt_pk_bf16_f32 v4, v45, v49
	ds_write_b32 v5, v4 offset:128
	v_cvt_pk_bf16_f32 v4, v46, v50
	ds_write_b32 v5, v4 offset:256
	v_cvt_pk_bf16_f32 v4, v47, v51
	ds_write_b32 v5, v4 offset:384
	v_cvt_pk_bf16_f32 v4, v52, v56
	v_add_u32_e32 v5, v78, v71
	ds_write_b32 v5, v4
	v_cvt_pk_bf16_f32 v4, v53, v57
	ds_write_b32 v5, v4 offset:128
	v_cvt_pk_bf16_f32 v4, v54, v58
	ds_write_b32 v5, v4 offset:256
	v_cvt_pk_bf16_f32 v4, v55, v59
	ds_write_b32 v5, v4 offset:384
	v_cvt_pk_bf16_f32 v4, v60, v64
	v_add_u32_e32 v5, v79, v71
	ds_write_b32 v5, v4
	v_cvt_pk_bf16_f32 v4, v61, v65
	ds_write_b32 v5, v4 offset:128
	v_cvt_pk_bf16_f32 v4, v62, v66
	ds_write_b32 v5, v4 offset:256
	v_cvt_pk_bf16_f32 v4, v63, v67
	ds_write_b32 v5, v4 offset:384
	s_addc_u32 s7, s20, 0
	v_lshlrev_b32_e32 v4, 1, v70
	v_mov_b32_e32 v5, v2
	s_waitcnt lgkmcnt(0)
	v_lshl_add_u64 v[4:5], s[6:7], 0, v[4:5]
	s_mov_b64 s[6:7], 0x4a00000
	v_lshl_add_u64 v[12:13], v[4:5], 0, s[6:7]
	v_add_u32_e32 v4, v81, v82
	ds_read_b128 v[4:7], v4
	v_or_b32_e32 v8, s2, v80
	v_lshlrev_b32_e32 v8, 10, v8
	v_mov_b32_e32 v9, v2
	v_lshl_add_u64 v[14:15], v[12:13], 0, v[8:9]
	v_add_u32_e32 v8, v84, v85
	ds_read_b128 v[8:11], v8
	s_waitcnt lgkmcnt(1)
	global_store_dwordx4 v[14:15], v[4:7], off nt
	v_readlane_b32 s46, v250, 56
	v_readlane_b32 s47, v250, 57
	v_or_b32_e32 v4, s2, v83
	v_lshlrev_b32_e32 v4, 10, v4
	v_mov_b32_e32 v5, v2
	v_lshl_add_u64 v[4:5], v[12:13], 0, v[4:5]
	s_waitcnt lgkmcnt(0)
	global_store_dwordx4 v[4:5], v[8:11], off nt
	v_add_u32_e32 v4, v87, v88
	ds_read_b128 v[4:7], v4
	v_or_b32_e32 v8, s2, v86
	v_lshlrev_b32_e32 v8, 10, v8
	v_mov_b32_e32 v9, v2
	v_lshl_add_u64 v[14:15], v[12:13], 0, v[8:9]
	v_add_u32_e32 v8, v90, v91
	ds_read_b128 v[8:11], v8
	s_waitcnt lgkmcnt(1)
	global_store_dwordx4 v[14:15], v[4:7], off nt
	v_readlane_b32 s46, v255, 36
	v_readlane_b32 s37, v250, 47
	v_or_b32_e32 v4, s2, v89
	v_lshlrev_b32_e32 v4, 10, v4
	v_mov_b32_e32 v5, v2
	v_lshl_add_u64 v[4:5], v[12:13], 0, v[4:5]
	s_waitcnt lgkmcnt(0)
	global_store_dwordx4 v[4:5], v[8:11], off nt
	v_add_u32_e32 v4, v93, v82
	ds_read_b128 v[4:7], v4
	v_or_b32_e32 v8, s2, v92
	v_lshlrev_b32_e32 v8, 10, v8
	v_mov_b32_e32 v9, v2
	v_lshl_add_u64 v[14:15], v[12:13], 0, v[8:9]
	v_add_u32_e32 v8, v95, v96
	ds_read_b128 v[8:11], v8
	s_waitcnt lgkmcnt(1)
	global_store_dwordx4 v[14:15], v[4:7], off nt
	v_readlane_b32 s38, v250, 48
	v_readlane_b32 s39, v250, 49
	v_or_b32_e32 v4, s2, v94
	v_lshlrev_b32_e32 v4, 10, v4
	v_mov_b32_e32 v5, v2
	v_lshl_add_u64 v[4:5], v[12:13], 0, v[4:5]
	s_waitcnt lgkmcnt(0)
	global_store_dwordx4 v[4:5], v[8:11], off nt
	v_add_u32_e32 v4, v98, v99
	ds_read_b128 v[4:7], v4
	v_or_b32_e32 v8, s2, v97
	v_lshlrev_b32_e32 v8, 10, v8
	v_mov_b32_e32 v9, v2
	v_lshl_add_u64 v[14:15], v[12:13], 0, v[8:9]
	v_add_u32_e32 v8, v101, v102
	ds_read_b128 v[8:11], v8
	s_waitcnt lgkmcnt(1)
	global_store_dwordx4 v[14:15], v[4:7], off nt
	v_readlane_b32 s40, v250, 50
	v_readlane_b32 s41, v250, 51
	v_or_b32_e32 v4, s2, v100
	v_lshlrev_b32_e32 v4, 10, v4
	v_mov_b32_e32 v5, v2
	v_lshl_add_u64 v[4:5], v[12:13], 0, v[4:5]
	s_waitcnt lgkmcnt(0)
	global_store_dwordx4 v[4:5], v[8:11], off nt
	s_waitcnt lgkmcnt(0)
	v_readlane_b32 s42, v250, 52
	v_readlane_b32 s43, v250, 53
	v_readlane_b32 s44, v250, 54
	v_readlane_b32 s45, v250, 55
	v_readlane_b32 s48, v250, 58
	v_readlane_b32 s49, v250, 59
	v_readlane_b32 s47, v255, 37

; #define LAS __attribute__((address_space(3)))
; #define LDS_WAIT() asm volatile("s_waitcnt lgkmcnt(0)" ::: "memory")
; __device__ __forceinline__ unsigned cvt_pk_bf16(float lo, float hi) { unsigned r; asm volatile("v_cvt_pk_bf16_f32 %0, %1, %2" : "=v"(r) : "v"(lo), "v"(hi)); return r; }
;     ...
;         for (int e = 0; e < 4; ++e) *(LAS unsigned*)(scr + (4 * r16 + e) * 128 + ((i ^ (r16 & 7)) * 16) + q * 4) = cvt_pk_bf16(v[2 * i][e], v[2 * i + 1][e]);
;     LDS_WAIT(); asm volatile("" ::: "memory");
;     const int c = lane & 7;
; #pragma unroll
;     for (int j = 0; j < 8; ++j) { const int row = (lane >> 3) + 8 * j; const u32x4 o = *(const LAS u32x4*)(scr + row * 128 + ((c ^ ((row >> 2) & 7)) * 16));
;         const int lc = col_off + n0 + row; int dr;
;         if (MODE == 0) dr = lc;
;         else if (MODE == 1) dr = (lc & ~255) + 128 * ((lc >> 5) & 1) + 32 * ((lc >> 6) & 3) + (lc & 31);
;         else if (MODE == 2) dr = 256 * (lc >> 7) + (lc & 127);
;         else dr = 256 * (lc >> 7) + 128 + (lc & 127);
;         *(u32x4*)(WT + (size_t)dr * (ldt ? ldt : K) + k0 + 8 * c) = o; }
; __device__ __forceinline__ void weights_pass(const Args& a, LAS unsigned char* scr, int gw, int NGW, int lane, int pass) {
;     ...
;         if (r < I_QM) { transpose_item<1>(a.in[I_WVM] + (size_t)l * DM * MW, DM, MW, (bf16_t*)(ws + WS_WKV) + (size_t)l * 1024 * DM, a.in[I_GMEM] + l * DM, nullptr, 512, scr, r, lane); continue; } r -= I_QM;
.LBB0_1695:
	s_waitcnt vmcnt(0)
	v_cvt_pk_bf16_f32 v60, v60, v64
	v_add_u32_e32 v64, v69, v71
	ds_write_b32 v64, v60
	v_cvt_pk_bf16_f32 v60, v61, v65
	ds_write_b32 v64, v60 offset:128
	v_cvt_pk_bf16_f32 v60, v62, v66
	ds_write_b32 v64, v60 offset:256
	v_cvt_pk_bf16_f32 v60, v63, v67
	ds_write_b32 v64, v60 offset:384
	v_cvt_pk_bf16_f32 v52, v52, v56
	v_add_u32_e32 v56, v73, v71
	ds_write_b32 v56, v52
	v_cvt_pk_bf16_f32 v52, v53, v57
	ds_write_b32 v56, v52 offset:128
	v_cvt_pk_bf16_f32 v52, v54, v58
	ds_write_b32 v56, v52 offset:256
	v_cvt_pk_bf16_f32 v52, v55, v59
	ds_write_b32 v56, v52 offset:384
	v_cvt_pk_bf16_f32 v44, v44, v48
	v_add_u32_e32 v48, v74, v71
	ds_write_b32 v48, v44
	v_cvt_pk_bf16_f32 v44, v45, v49
	ds_write_b32 v48, v44 offset:128
	v_cvt_pk_bf16_f32 v44, v46, v50
	ds_write_b32 v48, v44 offset:256
	v_cvt_pk_bf16_f32 v44, v47, v51
	ds_write_b32 v48, v44 offset:384
	v_cvt_pk_bf16_f32 v36, v36, v40
	v_add_u32_e32 v40, v75, v71
	ds_write_b32 v40, v36
	v_cvt_pk_bf16_f32 v36, v37, v41
	ds_write_b32 v40, v36 offset:128
	v_cvt_pk_bf16_f32 v36, v38, v42
	ds_write_b32 v40, v36 offset:256
	v_cvt_pk_bf16_f32 v36, v39, v43
	ds_write_b32 v40, v36 offset:384
	v_cvt_pk_bf16_f32 v28, v28, v32
	v_add_u32_e32 v32, v76, v71
	ds_write_b32 v32, v28
	v_cvt_pk_bf16_f32 v28, v29, v33
	ds_write_b32 v32, v28 offset:128
	v_cvt_pk_bf16_f32 v28, v30, v34
	ds_write_b32 v32, v28 offset:256
	v_cvt_pk_bf16_f32 v28, v31, v35
	ds_write_b32 v32, v28 offset:384
	v_cvt_pk_bf16_f32 v20, v20, v24
	v_add_u32_e32 v24, v77, v71
	ds_write_b32 v24, v20
	v_cvt_pk_bf16_f32 v20, v21, v25
	ds_write_b32 v24, v20 offset:128
	v_cvt_pk_bf16_f32 v20, v22, v26
	ds_write_b32 v24, v20 offset:256
	v_cvt_pk_bf16_f32 v20, v23, v27
	ds_write_b32 v24, v20 offset:384
	v_cvt_pk_bf16_f32 v12, v12, v16
	v_add_u32_e32 v16, v78, v71
	ds_write_b32 v16, v12
	v_cvt_pk_bf16_f32 v12, v13, v17
	ds_write_b32 v16, v12 offset:128
	v_cvt_pk_bf16_f32 v12, v14, v18
	ds_write_b32 v16, v12 offset:256
	v_cvt_pk_bf16_f32 v12, v15, v19
	ds_write_b32 v16, v12 offset:384
	v_cvt_pk_bf16_f32 v4, v4, v8
	v_add_u32_e32 v8, v79, v71
	v_readlane_b32 s8, v251, 16
	ds_write_b32 v8, v4
	v_cvt_pk_bf16_f32 v4, v5, v9
	s_add_u32 s6, s8, s6
	v_readlane_b32 s8, v251, 17
	ds_write_b32 v8, v4 offset:128
	v_cvt_pk_bf16_f32 v4, v6, v10
	s_addc_u32 s7, s8, s7
	ds_write_b32 v8, v4 offset:256
	v_cvt_pk_bf16_f32 v4, v7, v11
	ds_write_b32 v8, v4 offset:384
	s_or_b32 s8, s3, 0x200
	s_lshl_b32 s2, s2, 1
	s_waitcnt lgkmcnt(0)
	s_add_u32 s2, s6, s2
	s_addc_u32 s3, s7, 0
	v_lshlrev_b32_e32 v4, 1, v70
	v_mov_b32_e32 v5, v2
	v_add_u32_e32 v10, v81, v82
	v_lshl_add_u64 v[16:17], s[2:3], 0, v[4:5]
	ds_read_b128 v[4:7], v10
	s_and_b32 s2, s13, 0x60
	s_and_b32 s3, s8, 0x300
	s_or_b32 s3, s3, s2
	v_or_b32_e32 v8, s3, v80
	v_or_b32_e32 v12, s3, v83
	v_lshlrev_b32_e32 v8, 13, v8
	v_mov_b32_e32 v9, v2
	v_lshlrev_b32_e32 v12, 13, v12
	v_mov_b32_e32 v13, v2
	v_lshl_add_u64 v[18:19], v[16:17], 0, v[8:9]
	v_lshl_add_u64 v[20:21], v[16:17], 0, v[12:13]
	v_add_u32_e32 v12, v87, v88
	ds_read_b128 v[12:15], v12
	s_waitcnt lgkmcnt(1)
	global_store_dwordx4 v[18:19], v[4:7], off nt
	ds_read_b128 v[8:11], v10 offset:4096
	v_readlane_b32 s46, v255, 36
	v_add_u32_e32 v4, v84, v85
	ds_read_b128 v[4:7], v4
	v_readlane_b32 s47, v255, 37
	s_waitcnt lgkmcnt(0)
	global_store_dwordx4 v[20:21], v[4:7], off nt
	s_nop 1
	v_or_b32_e32 v4, s3, v86
	v_lshlrev_b32_e32 v4, 13, v4
	v_mov_b32_e32 v5, v2
	v_lshl_add_u64 v[4:5], v[16:17], 0, v[4:5]
	global_store_dwordx4 v[4:5], v[12:15], off nt
	v_add_u32_e32 v4, v90, v91
	ds_read_b128 v[4:7], v4
	v_or_b32_e32 v12, s3, v89
	v_lshlrev_b32_e32 v12, 13, v12
	v_mov_b32_e32 v13, v2
	v_lshl_add_u64 v[20:21], v[16:17], 0, v[12:13]
	v_add_u32_e32 v12, v95, v96
	s_mov_b32 s3, 0x100000
	ds_read_b128 v[12:15], v12
	s_waitcnt lgkmcnt(1)
	global_store_dwordx4 v[20:21], v[4:7], off nt
	s_nop 1
	v_add_co_u32_e32 v4, vcc, s3, v18
	s_nop 1
	v_addc_co_u32_e32 v5, vcc, 0, v19, vcc
	global_store_dwordx4 v[4:5], v[8:11], off nt
	v_mov_b32_e32 v4, 0x30f
	v_bitop3_b32 v4, s8, v4, v94 bitop3:0xc8
	v_or_b32_e32 v4, s2, v4
	v_lshlrev_b32_e32 v4, 13, v4
	v_mov_b32_e32 v5, v2
	v_lshl_add_u64 v[4:5], v[16:17], 0, v[4:5]
	v_add_co_u32_e32 v4, vcc, s3, v4
	v_mov_b32_e32 v8, 0x317
	s_nop 0
	v_addc_co_u32_e32 v5, vcc, 0, v5, vcc
	s_waitcnt lgkmcnt(0)
	global_store_dwordx4 v[4:5], v[12:15], off nt
	v_add_u32_e32 v4, v98, v99
	v_bitop3_b32 v8, s8, v8, v97 bitop3:0xc8
	ds_read_b128 v[4:7], v4
	v_or_b32_e32 v8, s2, v8
	v_lshlrev_b32_e32 v8, 13, v8
	v_mov_b32_e32 v9, v2
	v_lshl_add_u64 v[8:9], v[16:17], 0, v[8:9]
	v_add_co_u32_e32 v12, vcc, s3, v8
	v_add_u32_e32 v8, v101, v102
	s_nop 0
	v_addc_co_u32_e32 v13, vcc, 0, v9, vcc
	ds_read_b128 v[8:11], v8
	s_waitcnt lgkmcnt(1)
	global_store_dwordx4 v[12:13], v[4:7], off nt
	s_nop 1
	v_mov_b32_e32 v4, 0x31f
	v_bitop3_b32 v4, s8, v4, v100 bitop3:0xc8
	v_or_b32_e32 v4, s2, v4
	v_lshlrev_b32_e32 v4, 13, v4
	v_mov_b32_e32 v5, v2
	v_lshl_add_u64 v[4:5], v[16:17], 0, v[4:5]
	v_add_co_u32_e32 v4, vcc, 0x100000, v4
	s_nop 1
	v_addc_co_u32_e32 v5, vcc, 0, v5, vcc
	s_waitcnt lgkmcnt(0)
	global_store_dwordx4 v[4:5], v[8:11], off nt
	s_waitcnt lgkmcnt(0)

; #define LAS __attribute__((address_space(3)))
; #define LDS_WAIT() asm volatile("s_waitcnt lgkmcnt(0)" ::: "memory")
; __device__ __forceinline__ unsigned cvt_pk_bf16(float lo, float hi) { unsigned r; asm volatile("v_cvt_pk_bf16_f32 %0, %1, %2" : "=v"(r) : "v"(lo), "v"(hi)); return r; }
;     ...
;         for (int e = 0; e < 4; ++e) *(LAS unsigned*)(scr + (4 * r16 + e) * 128 + ((i ^ (r16 & 7)) * 16) + q * 4) = cvt_pk_bf16(v[2 * i][e], v[2 * i + 1][e]);
;     LDS_WAIT(); asm volatile("" ::: "memory");
;     const int c = lane & 7;
; #pragma unroll
;     for (int j = 0; j < 8; ++j) { const int row = (lane >> 3) + 8 * j; const u32x4 o = *(const LAS u32x4*)(scr + row * 128 + ((c ^ ((row >> 2) & 7)) * 16));
;         const int lc = col_off + n0 + row; int dr;
;         if (MODE == 0) dr = lc;
;         else if (MODE == 1) dr = (lc & ~255) + 128 * ((lc >> 5) & 1) + 32 * ((lc >> 6) & 3) + (lc & 31);
;         else if (MODE == 2) dr = 256 * (lc >> 7) + (lc & 127);
;         else dr = 256 * (lc >> 7) + 128 + (lc & 127);
;         *(u32x4*)(WT + (size_t)dr * (ldt ? ldt : K) + k0 + 8 * c) = o; }
; __device__ __forceinline__ void weights_pass(const Args& a, LAS unsigned char* scr, int gw, int NGW, int lane, int pass) {
;     ...
;         if (r < I_QM) { transpose_item<1>(a.in[I_WKM] + (size_t)l * DM * MW, DM, MW, (bf16_t*)(ws + WS_WKV) + (size_t)l * 1024 * DM, a.in[I_GMEM] + l * DM, nullptr, 0, scr, r, lane); continue; } r -= I_QM;
.LBB0_1700:
	s_waitcnt vmcnt(0)
	v_cvt_pk_bf16_f32 v60, v60, v64
	v_add_u32_e32 v64, v69, v71
	ds_write_b32 v64, v60
	v_cvt_pk_bf16_f32 v60, v61, v65
	ds_write_b32 v64, v60 offset:128
	v_cvt_pk_bf16_f32 v60, v62, v66
	ds_write_b32 v64, v60 offset:256
	v_cvt_pk_bf16_f32 v60, v63, v67
	ds_write_b32 v64, v60 offset:384
	v_cvt_pk_bf16_f32 v52, v52, v56
	v_add_u32_e32 v56, v73, v71
	ds_write_b32 v56, v52
	v_cvt_pk_bf16_f32 v52, v53, v57
	ds_write_b32 v56, v52 offset:128
	v_cvt_pk_bf16_f32 v52, v54, v58
	ds_write_b32 v56, v52 offset:256
	v_cvt_pk_bf16_f32 v52, v55, v59
	ds_write_b32 v56, v52 offset:384
	v_cvt_pk_bf16_f32 v44, v44, v48
	v_add_u32_e32 v48, v74, v71
	ds_write_b32 v48, v44
	v_cvt_pk_bf16_f32 v44, v45, v49
	ds_write_b32 v48, v44 offset:128
	v_cvt_pk_bf16_f32 v44, v46, v50
	ds_write_b32 v48, v44 offset:256
	v_cvt_pk_bf16_f32 v44, v47, v51
	ds_write_b32 v48, v44 offset:384
	v_cvt_pk_bf16_f32 v36, v36, v40
	v_add_u32_e32 v40, v75, v71
	ds_write_b32 v40, v36
	v_cvt_pk_bf16_f32 v36, v37, v41
	ds_write_b32 v40, v36 offset:128
	v_cvt_pk_bf16_f32 v36, v38, v42
	ds_write_b32 v40, v36 offset:256
	v_cvt_pk_bf16_f32 v36, v39, v43
	ds_write_b32 v40, v36 offset:384
	v_cvt_pk_bf16_f32 v28, v28, v32
	v_add_u32_e32 v32, v76, v71
	ds_write_b32 v32, v28
	v_cvt_pk_bf16_f32 v28, v29, v33
	ds_write_b32 v32, v28 offset:128
	v_cvt_pk_bf16_f32 v28, v30, v34
	ds_write_b32 v32, v28 offset:256
	v_cvt_pk_bf16_f32 v28, v31, v35
	ds_write_b32 v32, v28 offset:384
	v_cvt_pk_bf16_f32 v20, v20, v24
	v_add_u32_e32 v24, v77, v71
	ds_write_b32 v24, v20
	v_cvt_pk_bf16_f32 v20, v21, v25
	ds_write_b32 v24, v20 offset:128
	v_cvt_pk_bf16_f32 v20, v22, v26
	ds_write_b32 v24, v20 offset:256
	v_cvt_pk_bf16_f32 v20, v23, v27
	ds_write_b32 v24, v20 offset:384
	v_cvt_pk_bf16_f32 v12, v12, v16
	v_add_u32_e32 v16, v78, v71
	ds_write_b32 v16, v12
	v_cvt_pk_bf16_f32 v12, v13, v17
	ds_write_b32 v16, v12 offset:128
	v_cvt_pk_bf16_f32 v12, v14, v18
	ds_write_b32 v16, v12 offset:256
	v_cvt_pk_bf16_f32 v12, v15, v19
	ds_write_b32 v16, v12 offset:384
	v_cvt_pk_bf16_f32 v4, v4, v8
	v_add_u32_e32 v8, v79, v71
	v_readlane_b32 s8, v251, 16
	ds_write_b32 v8, v4
	v_cvt_pk_bf16_f32 v4, v5, v9
	s_add_u32 s6, s8, s6
	v_readlane_b32 s8, v251, 17
	ds_write_b32 v8, v4 offset:128
	v_cvt_pk_bf16_f32 v4, v6, v10
	s_addc_u32 s7, s8, s7
	ds_write_b32 v8, v4 offset:256
	v_cvt_pk_bf16_f32 v4, v7, v11
	ds_write_b32 v8, v4 offset:384
	s_lshl_b32 s3, s3, 1
	s_waitcnt lgkmcnt(0)
	s_add_u32 s6, s6, s3
	s_addc_u32 s7, s7, 0
	v_lshlrev_b32_e32 v4, 1, v70
	v_mov_b32_e32 v5, v2
	v_add_u32_e32 v10, v81, v82
	v_lshl_add_u64 v[16:17], s[6:7], 0, v[4:5]
	ds_read_b128 v[4:7], v10
	s_and_b32 s3, s13, 0x60
	s_and_b32 s6, s2, 0x100
	s_or_b32 s6, s6, s3
	v_or_b32_e32 v8, s6, v80
	v_or_b32_e32 v12, s6, v83
	v_lshlrev_b32_e32 v8, 13, v8
	v_mov_b32_e32 v9, v2
	v_lshlrev_b32_e32 v12, 13, v12
	v_mov_b32_e32 v13, v2
	v_lshl_add_u64 v[18:19], v[16:17], 0, v[8:9]
	v_lshl_add_u64 v[20:21], v[16:17], 0, v[12:13]
	v_add_u32_e32 v12, v87, v88
	ds_read_b128 v[12:15], v12
	s_waitcnt lgkmcnt(1)
	global_store_dwordx4 v[18:19], v[4:7], off nt
	ds_read_b128 v[8:11], v10 offset:4096
	v_readlane_b32 s46, v255, 36
	v_add_u32_e32 v4, v84, v85
	ds_read_b128 v[4:7], v4
	v_readlane_b32 s47, v255, 37
	s_waitcnt lgkmcnt(0)
	global_store_dwordx4 v[20:21], v[4:7], off nt
	s_nop 1
	v_or_b32_e32 v4, s6, v86
	v_lshlrev_b32_e32 v4, 13, v4
	v_mov_b32_e32 v5, v2
	v_lshl_add_u64 v[4:5], v[16:17], 0, v[4:5]
	global_store_dwordx4 v[4:5], v[12:15], off nt
	v_add_u32_e32 v4, v90, v91
	ds_read_b128 v[4:7], v4
	v_or_b32_e32 v12, s6, v89
	v_lshlrev_b32_e32 v12, 13, v12
	v_mov_b32_e32 v13, v2
	v_lshl_add_u64 v[20:21], v[16:17], 0, v[12:13]
	v_add_u32_e32 v12, v95, v96
	s_mov_b32 s6, 0x100000
	ds_read_b128 v[12:15], v12
	s_waitcnt lgkmcnt(1)
	global_store_dwordx4 v[20:21], v[4:7], off nt
	s_nop 1
	v_add_co_u32_e32 v4, vcc, s6, v18
	v_add_u32_e32 v18, s2, v80
	s_nop 0
	v_addc_co_u32_e32 v5, vcc, 0, v19, vcc
	global_store_dwordx4 v[4:5], v[8:11], off nt
	v_add_u32_e32 v4, 40, v18
	v_and_b32_e32 v4, 0x10f, v4
	v_or_b32_e32 v4, s3, v4
	v_lshlrev_b32_e32 v4, 13, v4
	v_mov_b32_e32 v5, v2
	v_lshl_add_u64 v[4:5], v[16:17], 0, v[4:5]
	v_add_co_u32_e32 v4, vcc, s6, v4
	v_add_u32_e32 v8, 48, v18
	s_nop 0
	v_addc_co_u32_e32 v5, vcc, 0, v5, vcc
	s_waitcnt lgkmcnt(0)
	global_store_dwordx4 v[4:5], v[12:15], off nt
	v_add_u32_e32 v4, v98, v99
	v_and_b32_e32 v8, 0x117, v8
	ds_read_b128 v[4:7], v4
	v_or_b32_e32 v8, s3, v8
	v_lshlrev_b32_e32 v8, 13, v8
	v_mov_b32_e32 v9, v2
	v_lshl_add_u64 v[8:9], v[16:17], 0, v[8:9]
	v_add_co_u32_e32 v12, vcc, s6, v8
	v_add_u32_e32 v8, v101, v102
	s_nop 0
	v_addc_co_u32_e32 v13, vcc, 0, v9, vcc
	ds_read_b128 v[8:11], v8
	s_waitcnt lgkmcnt(1)
	global_store_dwordx4 v[12:13], v[4:7], off nt
	s_nop 1
	v_add_u32_e32 v4, 56, v18
	v_and_b32_e32 v4, 0x11f, v4
	v_or_b32_e32 v4, s3, v4
	v_lshlrev_b32_e32 v4, 13, v4
	v_mov_b32_e32 v5, v2
	v_lshl_add_u64 v[4:5], v[16:17], 0, v[4:5]
	v_add_co_u32_e32 v4, vcc, 0x100000, v4
	s_nop 1
	v_addc_co_u32_e32 v5, vcc, 0, v5, vcc
	s_waitcnt lgkmcnt(0)
	global_store_dwordx4 v[4:5], v[8:11], off nt
	s_waitcnt lgkmcnt(0)

; #define LAS __attribute__((address_space(3)))
; #define LDS_WAIT() asm volatile("s_waitcnt lgkmcnt(0)" ::: "memory")
; __device__ __forceinline__ unsigned cvt_pk_bf16(float lo, float hi) { unsigned r; asm volatile("v_cvt_pk_bf16_f32 %0, %1, %2" : "=v"(r) : "v"(lo), "v"(hi)); return r; }
;     ...
;         for (int e = 0; e < 4; ++e) *(LAS unsigned*)(scr + (4 * r16 + e) * 128 + ((i ^ (r16 & 7)) * 16) + q * 4) = cvt_pk_bf16(v[2 * i][e], v[2 * i + 1][e]);
;     LDS_WAIT(); asm volatile("" ::: "memory");
;     const int c = lane & 7;
; #pragma unroll
;     for (int j = 0; j < 8; ++j) { const int row = (lane >> 3) + 8 * j; const u32x4 o = *(const LAS u32x4*)(scr + row * 128 + ((c ^ ((row >> 2) & 7)) * 16));
;         const int lc = col_off + n0 + row; int dr;
;         if (MODE == 0) dr = lc;
;         else if (MODE == 1) dr = (lc & ~255) + 128 * ((lc >> 5) & 1) + 32 * ((lc >> 6) & 3) + (lc & 31);
;         else if (MODE == 2) dr = 256 * (lc >> 7) + (lc & 127);
;         else dr = 256 * (lc >> 7) + 128 + (lc & 127);
;         *(u32x4*)(WT + (size_t)dr * (ldt ? ldt : K) + k0 + 8 * c) = o; }
; __device__ __forceinline__ void weights_pass(const Args& a, LAS unsigned char* scr, int gw, int NGW, int lane, int pass) {
;     ...
;         if (r < I_QM) { transpose_item<0>(a.in[I_WQM] + (size_t)l * DM * MW, DM, MW, (bf16_t*)(wl + WL_Q), a.in[I_GCROSS] + l * DM, nullptr, 0, scr, r, lane); continue; } r -= I_QM;
.LBB0_1705:
	s_waitcnt vmcnt(0)
	v_cvt_pk_bf16_f32 v60, v60, v64
	v_add_u32_e32 v64, v69, v71
	ds_write_b32 v64, v60
	v_cvt_pk_bf16_f32 v60, v61, v65
	ds_write_b32 v64, v60 offset:128
	v_cvt_pk_bf16_f32 v60, v62, v66
	ds_write_b32 v64, v60 offset:256
	v_cvt_pk_bf16_f32 v60, v63, v67
	ds_write_b32 v64, v60 offset:384
	v_cvt_pk_bf16_f32 v52, v52, v56
	v_add_u32_e32 v56, v73, v71
	ds_write_b32 v56, v52
	v_cvt_pk_bf16_f32 v52, v53, v57
	ds_write_b32 v56, v52 offset:128
	v_cvt_pk_bf16_f32 v52, v54, v58
	ds_write_b32 v56, v52 offset:256
	v_cvt_pk_bf16_f32 v52, v55, v59
	ds_write_b32 v56, v52 offset:384
	v_cvt_pk_bf16_f32 v44, v44, v48
	v_add_u32_e32 v48, v74, v71
	ds_write_b32 v48, v44
	v_cvt_pk_bf16_f32 v44, v45, v49
	ds_write_b32 v48, v44 offset:128
	v_cvt_pk_bf16_f32 v44, v46, v50
	ds_write_b32 v48, v44 offset:256
	v_cvt_pk_bf16_f32 v44, v47, v51
	ds_write_b32 v48, v44 offset:384
	v_cvt_pk_bf16_f32 v36, v36, v40
	v_add_u32_e32 v40, v75, v71
	ds_write_b32 v40, v36
	v_cvt_pk_bf16_f32 v36, v37, v41
	ds_write_b32 v40, v36 offset:128
	v_cvt_pk_bf16_f32 v36, v38, v42
	ds_write_b32 v40, v36 offset:256
	v_cvt_pk_bf16_f32 v36, v39, v43
	ds_write_b32 v40, v36 offset:384
	v_cvt_pk_bf16_f32 v28, v28, v32
	v_add_u32_e32 v32, v76, v71
	ds_write_b32 v32, v28
	v_cvt_pk_bf16_f32 v28, v29, v33
	ds_write_b32 v32, v28 offset:128
	v_cvt_pk_bf16_f32 v28, v30, v34
	ds_write_b32 v32, v28 offset:256
	v_cvt_pk_bf16_f32 v28, v31, v35
	ds_write_b32 v32, v28 offset:384
	v_cvt_pk_bf16_f32 v20, v20, v24
	v_add_u32_e32 v24, v77, v71
	ds_write_b32 v24, v20
	v_cvt_pk_bf16_f32 v20, v21, v25
	ds_write_b32 v24, v20 offset:128
	v_cvt_pk_bf16_f32 v20, v22, v26
	ds_write_b32 v24, v20 offset:256
	v_cvt_pk_bf16_f32 v20, v23, v27
	ds_write_b32 v24, v20 offset:384
	v_cvt_pk_bf16_f32 v12, v12, v16
	v_add_u32_e32 v16, v78, v71
	ds_write_b32 v16, v12
	v_cvt_pk_bf16_f32 v12, v13, v17
	ds_write_b32 v16, v12 offset:128
	v_cvt_pk_bf16_f32 v12, v14, v18
	ds_write_b32 v16, v12 offset:256
	v_cvt_pk_bf16_f32 v12, v15, v19
	ds_write_b32 v16, v12 offset:384
	v_cvt_pk_bf16_f32 v4, v4, v8
	v_add_u32_e32 v8, v79, v71
	ds_write_b32 v8, v4
	v_cvt_pk_bf16_f32 v4, v5, v9
	s_and_b32 s3, 0xffff, s3
	ds_write_b32 v8, v4 offset:128
	v_cvt_pk_bf16_f32 v4, v6, v10
	s_lshl_b32 s2, s2, 1
	ds_write_b32 v8, v4 offset:256
	v_cvt_pk_bf16_f32 v4, v7, v11
	s_add_u32 s6, s19, s2
	ds_write_b32 v8, v4 offset:384
	s_addc_u32 s7, s20, 0
	v_lshlrev_b32_e32 v4, 1, v70
	v_mov_b32_e32 v5, v2
	s_waitcnt lgkmcnt(0)
	v_lshl_add_u64 v[4:5], s[6:7], 0, v[4:5]
	s_mov_b64 s[6:7], 0x4600000
	v_lshl_add_u64 v[12:13], v[4:5], 0, s[6:7]
	v_add_u32_e32 v4, v81, v82
	ds_read_b128 v[4:7], v4
	v_or_b32_e32 v8, s3, v80
	v_lshlrev_b32_e32 v8, 13, v8
	v_mov_b32_e32 v9, v2
	v_lshl_add_u64 v[14:15], v[12:13], 0, v[8:9]
	v_add_u32_e32 v8, v84, v85
	ds_read_b128 v[8:11], v8
	s_waitcnt lgkmcnt(1)
	global_store_dwordx4 v[14:15], v[4:7], off nt
	v_readlane_b32 s46, v255, 36
	v_readlane_b32 s47, v255, 37
	v_or_b32_e32 v4, s3, v83
	v_lshlrev_b32_e32 v4, 13, v4
	v_mov_b32_e32 v5, v2
	v_lshl_add_u64 v[4:5], v[12:13], 0, v[4:5]
	s_waitcnt lgkmcnt(0)
	global_store_dwordx4 v[4:5], v[8:11], off nt
	v_add_u32_e32 v4, v87, v88
	ds_read_b128 v[4:7], v4
	v_or_b32_e32 v8, s3, v86
	v_lshlrev_b32_e32 v8, 13, v8
	v_mov_b32_e32 v9, v2
	v_lshl_add_u64 v[14:15], v[12:13], 0, v[8:9]
	v_add_u32_e32 v8, v90, v91
	ds_read_b128 v[8:11], v8
	s_waitcnt lgkmcnt(1)
	global_store_dwordx4 v[14:15], v[4:7], off nt
	s_nop 1
	v_or_b32_e32 v4, s3, v89
	v_lshlrev_b32_e32 v4, 13, v4
	v_mov_b32_e32 v5, v2
	v_lshl_add_u64 v[4:5], v[12:13], 0, v[4:5]
	s_waitcnt lgkmcnt(0)
	global_store_dwordx4 v[4:5], v[8:11], off nt
	v_add_u32_e32 v4, v93, v82
	ds_read_b128 v[4:7], v4
	v_or_b32_e32 v8, s3, v92
	v_lshlrev_b32_e32 v8, 13, v8
	v_mov_b32_e32 v9, v2
	v_lshl_add_u64 v[14:15], v[12:13], 0, v[8:9]
	v_add_u32_e32 v8, v95, v96
	ds_read_b128 v[8:11], v8
	s_waitcnt lgkmcnt(1)
	global_store_dwordx4 v[14:15], v[4:7], off nt
	s_nop 1
	v_or_b32_e32 v4, s3, v94
	v_lshlrev_b32_e32 v4, 13, v4
	v_mov_b32_e32 v5, v2
	v_lshl_add_u64 v[4:5], v[12:13], 0, v[4:5]
	s_waitcnt lgkmcnt(0)
	global_store_dwordx4 v[4:5], v[8:11], off nt
	v_add_u32_e32 v4, v98, v99
	ds_read_b128 v[4:7], v4
	v_or_b32_e32 v8, s3, v97
	v_lshlrev_b32_e32 v8, 13, v8
	v_mov_b32_e32 v9, v2
	v_lshl_add_u64 v[14:15], v[12:13], 0, v[8:9]
	v_add_u32_e32 v8, v101, v102
	ds_read_b128 v[8:11], v8
	s_waitcnt lgkmcnt(1)
	global_store_dwordx4 v[14:15], v[4:7], off nt
	s_nop 1
	v_or_b32_e32 v4, s3, v100
	v_lshlrev_b32_e32 v4, 13, v4
	v_mov_b32_e32 v5, v2
	v_lshl_add_u64 v[4:5], v[12:13], 0, v[4:5]
	s_waitcnt lgkmcnt(0)
	global_store_dwordx4 v[4:5], v[8:11], off nt
	s_waitcnt lgkmcnt(0)

;     const int nblk = N / 64, kb = item / nblk, nb = item % nblk, k0 = 64 * kb, n0 = 64 * nb;
;     const int r16 = lane & 15, q = lane >> 4;
;     const float* src = W + (size_t)(k0 + 2 * q) * N + n0 + 4 * r16;
;     f32x4 v[16];
; #pragma unroll
;     for (int j = 0; j < 16; ++j) v[j] = *(const f32x4*)(src + (size_t)(8 * (j >> 1) + (j & 1)) * N);
; __device__ __forceinline__ void weights_pass(const Args& a, LAS unsigned char* scr, int gw, int NGW, int lane, int pass) {
;     ...
;         if (r < I_OUT / 2) { transpose_item<0>(a.in[I_WOUT] + (size_t)l * DM * DM + (size_t)2048 * DM, 2048, DM, (bf16_t*)(ws + WS_WLOW) + (size_t)l * DM * 2048, nullptr, nullptr, 0, scr, r, lane); continue; } r -= I_OUT / 2;
.LBB0_1707:
	s_andn2_b64 vcc, exec, s[6:7]
	s_cbranch_vccnz .LBB0_1709
	s_lshl_b64 s[2:3], s[0:1], 26
	s_add_u32 s8, s74, s2
	s_addc_u32 s9, s75, s3
	s_lshl_b64 s[6:7], s[0:1], 24
	v_readlane_b32 s2, v252, 53
	s_add_u32 s3, s2, s6
	v_readlane_b32 s2, v252, 54
	s_addc_u32 s6, s2, s7
	s_and_b32 s7, s23, 0xffc0
	s_lshl_b32 s2, s21, 6
	v_lshlrev_b32_e32 v4, 2, v3
	s_and_b32 s2, s2, 0xfc0
	v_lshl_or_b32 v4, s7, 14, v4
	v_mov_b32_e32 v5, v2
	v_lshl_add_u64 v[4:5], s[8:9], 0, v[4:5]
	s_lshl_b32 s14, s2, 2
	v_lshl_add_u64 v[4:5], v[4:5], 0, s[14:15]
	v_lshlrev_b32_e32 v6, 2, v68
	v_mov_b32_e32 v7, v2
	v_lshl_add_u64 v[60:61], v[4:5], 0, v[6:7]
	s_brev_b32 s8, 64
	v_add_co_u32_e32 v4, vcc, s8, v60
	s_mov_b32 s8, 0x2004000
	s_nop 0
	v_addc_co_u32_e32 v5, vcc, 0, v61, vcc
	v_add_co_u32_e32 v8, vcc, s8, v60
	s_mov_b32 s8, 0x2020000
	s_nop 0
	v_addc_co_u32_e32 v9, vcc, 0, v61, vcc
	global_load_dwordx4 v[4:7], v[4:5], off nt
	s_nop 0
	global_load_dwordx4 v[8:11], v[8:9], off nt
	v_add_co_u32_e32 v12, vcc, s8, v60
	s_mov_b32 s8, 0x2024000
	s_nop 0
	v_addc_co_u32_e32 v13, vcc, 0, v61, vcc
	v_add_co_u32_e32 v16, vcc, s8, v60
	s_mov_b32 s8, 0x2040000
	s_nop 0
	v_addc_co_u32_e32 v17, vcc, 0, v61, vcc
	global_load_dwordx4 v[12:15], v[12:13], off nt
	s_nop 0
	global_load_dwordx4 v[16:19], v[16:17], off nt
	v_add_co_u32_e32 v20, vcc, s8, v60
	s_mov_b32 s8, 0x2044000
	s_nop 0
	v_addc_co_u32_e32 v21, vcc, 0, v61, vcc
	v_add_co_u32_e32 v24, vcc, s8, v60
	s_mov_b32 s8, 0x2060000
	s_nop 0
	v_addc_co_u32_e32 v25, vcc, 0, v61, vcc
	global_load_dwordx4 v[20:23], v[20:21], off nt
	s_nop 0
	global_load_dwordx4 v[24:27], v[24:25], off nt
	v_add_co_u32_e32 v28, vcc, s8, v60
	s_mov_b32 s8, 0x2064000
	s_nop 0
	v_addc_co_u32_e32 v29, vcc, 0, v61, vcc
	v_add_co_u32_e32 v32, vcc, s8, v60
	s_mov_b32 s8, 0x2080000
	s_nop 0
	v_addc_co_u32_e32 v33, vcc, 0, v61, vcc
	global_load_dwordx4 v[28:31], v[28:29], off nt
	s_nop 0
	global_load_dwordx4 v[32:35], v[32:33], off nt
	v_add_co_u32_e32 v36, vcc, s8, v60
	s_mov_b32 s8, 0x2084000
	s_nop 0
	v_addc_co_u32_e32 v37, vcc, 0, v61, vcc
	v_add_co_u32_e32 v40, vcc, s8, v60
	s_mov_b32 s8, 0x20a0000
	s_nop 0
	v_addc_co_u32_e32 v41, vcc, 0, v61, vcc
	global_load_dwordx4 v[36:39], v[36:37], off nt
	s_nop 0
	global_load_dwordx4 v[40:43], v[40:41], off nt
	v_add_co_u32_e32 v44, vcc, s8, v60
	s_mov_b32 s8, 0x20a4000
	s_nop 0
	v_addc_co_u32_e32 v45, vcc, 0, v61, vcc
	v_add_co_u32_e32 v48, vcc, s8, v60
	s_mov_b32 s8, 0x20c0000
	s_nop 0
	v_addc_co_u32_e32 v49, vcc, 0, v61, vcc
	global_load_dwordx4 v[44:47], v[44:45], off nt
	s_nop 0
	global_load_dwordx4 v[48:51], v[48:49], off nt
	v_add_co_u32_e32 v52, vcc, s8, v60
	s_mov_b32 s8, 0x20c4000
	s_nop 0
	v_addc_co_u32_e32 v53, vcc, 0, v61, vcc
	v_add_co_u32_e32 v56, vcc, s8, v60
	s_mov_b32 s8, 0x20e0000
	s_nop 0
	v_addc_co_u32_e32 v57, vcc, 0, v61, vcc
	global_load_dwordx4 v[52:55], v[52:53], off nt
	s_nop 0
	global_load_dwordx4 v[56:59], v[56:57], off nt
	v_add_co_u32_e32 v62, vcc, s8, v60
	s_mov_b32 s8, 0x20e4000
	s_nop 0
	v_addc_co_u32_e32 v63, vcc, 0, v61, vcc
	v_add_co_u32_e32 v64, vcc, s8, v60
	s_lshl_b32 s7, s7, 1
	s_nop 0
	v_addc_co_u32_e32 v65, vcc, 0, v61, vcc
	global_load_dwordx4 v[60:63], v[62:63], off nt
	s_nop 0
	global_load_dwordx4 v[64:67], v[64:65], off nt
	s_waitcnt vmcnt(0)
; #define LAS __attribute__((address_space(3)))
; #define LDS_WAIT() asm volatile("s_waitcnt lgkmcnt(0)" ::: "memory")
; __device__ __forceinline__ unsigned cvt_pk_bf16(float lo, float hi) { unsigned r; asm volatile("v_cvt_pk_bf16_f32 %0, %1, %2" : "=v"(r) : "v"(lo), "v"(hi)); return r; }
;     ...
;         for (int e = 0; e < 4; ++e) *(LAS unsigned*)(scr + (4 * r16 + e) * 128 + ((i ^ (r16 & 7)) * 16) + q * 4) = cvt_pk_bf16(v[2 * i][e], v[2 * i + 1][e]);
;     LDS_WAIT(); asm volatile("" ::: "memory");
;     const int c = lane & 7;
; #pragma unroll
;     for (int j = 0; j < 8; ++j) { const int row = (lane >> 3) + 8 * j; const u32x4 o = *(const LAS u32x4*)(scr + row * 128 + ((c ^ ((row >> 2) & 7)) * 16));
;         const int lc = col_off + n0 + row; int dr;
;         if (MODE == 0) dr = lc;
;         else if (MODE == 1) dr = (lc & ~255) + 128 * ((lc >> 5) & 1) + 32 * ((lc >> 6) & 3) + (lc & 31);
;         else if (MODE == 2) dr = 256 * (lc >> 7) + (lc & 127);
;         else dr = 256 * (lc >> 7) + 128 + (lc & 127);
;         *(u32x4*)(WT + (size_t)dr * (ldt ? ldt : K) + k0 + 8 * c) = o; }
; __device__ __forceinline__ void weights_pass(const Args& a, LAS unsigned char* scr, int gw, int NGW, int lane, int pass) {
;     ...
;         if (r < I_OUT / 2) { transpose_item<0>(a.in[I_WOUT] + (size_t)l * DM * DM + (size_t)2048 * DM, 2048, DM, (bf16_t*)(ws + WS_WLOW) + (size_t)l * DM * 2048, nullptr, nullptr, 0, scr, r, lane); continue; } r -= I_OUT / 2;
	v_cvt_pk_bf16_f32 v4, v4, v8
	v_add_u32_e32 v8, v69, v71
	ds_write_b32 v8, v4
	v_cvt_pk_bf16_f32 v4, v5, v9
	ds_write_b32 v8, v4 offset:128
	v_cvt_pk_bf16_f32 v4, v6, v10
	ds_write_b32 v8, v4 offset:256
	v_cvt_pk_bf16_f32 v4, v7, v11
	ds_write_b32 v8, v4 offset:384
	v_cvt_pk_bf16_f32 v4, v12, v16
	v_add_u32_e32 v5, v73, v71
	ds_write_b32 v5, v4
	v_cvt_pk_bf16_f32 v4, v13, v17
	ds_write_b32 v5, v4 offset:128
	v_cvt_pk_bf16_f32 v4, v14, v18
	ds_write_b32 v5, v4 offset:256
	v_cvt_pk_bf16_f32 v4, v15, v19
	ds_write_b32 v5, v4 offset:384
	v_cvt_pk_bf16_f32 v4, v20, v24
	v_add_u32_e32 v5, v74, v71
	ds_write_b32 v5, v4
	v_cvt_pk_bf16_f32 v4, v21, v25
	ds_write_b32 v5, v4 offset:128
	v_cvt_pk_bf16_f32 v4, v22, v26
	ds_write_b32 v5, v4 offset:256
	v_cvt_pk_bf16_f32 v4, v23, v27
	ds_write_b32 v5, v4 offset:384
	v_cvt_pk_bf16_f32 v4, v28, v32
	v_add_u32_e32 v5, v75, v71
	ds_write_b32 v5, v4
	v_cvt_pk_bf16_f32 v4, v29, v33
	ds_write_b32 v5, v4 offset:128
	v_cvt_pk_bf16_f32 v4, v30, v34
	ds_write_b32 v5, v4 offset:256
	v_cvt_pk_bf16_f32 v4, v31, v35
	ds_write_b32 v5, v4 offset:384
	v_cvt_pk_bf16_f32 v4, v36, v40
	v_add_u32_e32 v5, v76, v71
	ds_write_b32 v5, v4
	v_cvt_pk_bf16_f32 v4, v37, v41
	ds_write_b32 v5, v4 offset:128
	v_cvt_pk_bf16_f32 v4, v38, v42
	ds_write_b32 v5, v4 offset:256
	v_cvt_pk_bf16_f32 v4, v39, v43
	ds_write_b32 v5, v4 offset:384
	v_cvt_pk_bf16_f32 v4, v44, v48
	v_add_u32_e32 v5, v77, v71
	ds_write_b32 v5, v4
	v_cvt_pk_bf16_f32 v4, v45, v49
	ds_write_b32 v5, v4 offset:128
	v_cvt_pk_bf16_f32 v4, v46, v50
	ds_write_b32 v5, v4 offset:256
	v_cvt_pk_bf16_f32 v4, v47, v51
	ds_write_b32 v5, v4 offset:384
	v_cvt_pk_bf16_f32 v4, v52, v56
	v_add_u32_e32 v5, v78, v71
	ds_write_b32 v5, v4
	v_cvt_pk_bf16_f32 v4, v53, v57
	ds_write_b32 v5, v4 offset:128
	v_cvt_pk_bf16_f32 v4, v54, v58
	ds_write_b32 v5, v4 offset:256
	v_cvt_pk_bf16_f32 v4, v55, v59
	ds_write_b32 v5, v4 offset:384
	v_cvt_pk_bf16_f32 v4, v60, v64
	v_add_u32_e32 v5, v79, v71
	ds_write_b32 v5, v4
	v_cvt_pk_bf16_f32 v4, v61, v65
	ds_write_b32 v5, v4 offset:128
	v_cvt_pk_bf16_f32 v4, v62, v66
	ds_write_b32 v5, v4 offset:256
	v_cvt_pk_bf16_f32 v4, v63, v67
	ds_write_b32 v5, v4 offset:384
	s_add_u32 s8, s3, s7
	s_waitcnt lgkmcnt(0)
	s_addc_u32 s9, s6, 0
	v_lshlrev_b32_e32 v4, 1, v70
	v_mov_b32_e32 v5, v2
	v_lshl_add_u64 v[12:13], s[8:9], 0, v[4:5]
	v_add_u32_e32 v4, v81, v82
	ds_read_b128 v[4:7], v4
	v_or_b32_e32 v8, s2, v80
	v_lshlrev_b32_e32 v8, 12, v8
	v_mov_b32_e32 v9, v2
	v_lshl_add_u64 v[14:15], v[12:13], 0, v[8:9]
	v_add_u32_e32 v8, v84, v85
	ds_read_b128 v[8:11], v8
	s_waitcnt lgkmcnt(1)
	global_store_dwordx4 v[14:15], v[4:7], off nt
	s_nop 1
	v_or_b32_e32 v4, s2, v83
	v_lshlrev_b32_e32 v4, 12, v4
	v_mov_b32_e32 v5, v2
	v_lshl_add_u64 v[4:5], v[12:13], 0, v[4:5]
	s_waitcnt lgkmcnt(0)
	global_store_dwordx4 v[4:5], v[8:11], off nt
	v_add_u32_e32 v4, v87, v88
	ds_read_b128 v[4:7], v4
	v_or_b32_e32 v8, s2, v86
	v_lshlrev_b32_e32 v8, 12, v8
	v_mov_b32_e32 v9, v2
	v_lshl_add_u64 v[14:15], v[12:13], 0, v[8:9]
	v_add_u32_e32 v8, v90, v91
	ds_read_b128 v[8:11], v8
	s_waitcnt lgkmcnt(1)
	global_store_dwordx4 v[14:15], v[4:7], off nt
	s_nop 1
	v_or_b32_e32 v4, s2, v89
	v_lshlrev_b32_e32 v4, 12, v4
	v_mov_b32_e32 v5, v2
	v_lshl_add_u64 v[4:5], v[12:13], 0, v[4:5]
	s_waitcnt lgkmcnt(0)
	global_store_dwordx4 v[4:5], v[8:11], off nt
	v_add_u32_e32 v4, v93, v82
	ds_read_b128 v[4:7], v4
	v_or_b32_e32 v8, s2, v92
	v_lshlrev_b32_e32 v8, 12, v8
	v_mov_b32_e32 v9, v2
	v_lshl_add_u64 v[14:15], v[12:13], 0, v[8:9]
	v_add_u32_e32 v8, v95, v96
	ds_read_b128 v[8:11], v8
	s_waitcnt lgkmcnt(1)
	global_store_dwordx4 v[14:15], v[4:7], off nt
	s_nop 1
	v_or_b32_e32 v4, s2, v94
	v_lshlrev_b32_e32 v4, 12, v4
	v_mov_b32_e32 v5, v2
	v_lshl_add_u64 v[4:5], v[12:13], 0, v[4:5]
	s_waitcnt lgkmcnt(0)
	global_store_dwordx4 v[4:5], v[8:11], off nt
	v_add_u32_e32 v4, v98, v99
	ds_read_b128 v[4:7], v4
	v_or_b32_e32 v8, s2, v97
	v_lshlrev_b32_e32 v8, 12, v8
	v_mov_b32_e32 v9, v2
	v_lshl_add_u64 v[14:15], v[12:13], 0, v[8:9]
	v_add_u32_e32 v8, v101, v102
	ds_read_b128 v[8:11], v8
	s_waitcnt lgkmcnt(1)
	global_store_dwordx4 v[14:15], v[4:7], off nt
	s_nop 1
	v_or_b32_e32 v4, s2, v100
	v_lshlrev_b32_e32 v4, 12, v4
	v_mov_b32_e32 v5, v2
	v_lshl_add_u64 v[4:5], v[12:13], 0, v[4:5]
	s_waitcnt lgkmcnt(0)
	global_store_dwordx4 v[4:5], v[8:11], off nt
	s_waitcnt lgkmcnt(0)

;     const int nblk = N / 64, kb = item / nblk, nb = item % nblk, k0 = 64 * kb, n0 = 64 * nb;
;     const int r16 = lane & 15, q = lane >> 4;
;     const float* src = W + (size_t)(k0 + 2 * q) * N + n0 + 4 * r16;
;     f32x4 v[16];
; #pragma unroll
;     for (int j = 0; j < 16; ++j) v[j] = *(const f32x4*)(src + (size_t)(8 * (j >> 1) + (j & 1)) * N);
; __device__ __forceinline__ void weights_pass(const Args& a, LAS unsigned char* scr, int gw, int NGW, int lane, int pass) {
;     ...
;         if (r < I_OUT / 2) { transpose_item<0>(a.in[I_WOUT] + (size_t)l * DM * DM, 2048, DM, (bf16_t*)(wl + WL_OUT), nullptr, nullptr, 0, scr, r, lane, DM); continue; } r -= I_OUT / 2;
.LBB0_1710:
	s_andn2_b64 vcc, exec, s[6:7]
	s_cbranch_vccnz .LBB0_1712
	s_lshl_b64 s[2:3], s[0:1], 26
	s_add_u32 s6, s74, s2
	s_addc_u32 s7, s75, s3
	s_add_i32 s1, s21, 0xee00
	s_and_b32 s2, s1, 0xffc0
	s_lshl_b32 s1, s21, 6
	v_lshlrev_b32_e32 v4, 2, v3
	s_and_b32 s1, s1, 0xfc0
	v_lshl_or_b32 v4, s2, 14, v4
	v_mov_b32_e32 v5, v2
	v_lshl_add_u64 v[4:5], s[6:7], 0, v[4:5]
	s_lshl_b32 s14, s1, 2
	v_lshl_add_u64 v[4:5], v[4:5], 0, s[14:15]
	v_lshlrev_b32_e32 v6, 2, v68
	v_mov_b32_e32 v7, v2
	v_lshl_add_u64 v[60:61], v[4:5], 0, v[6:7]
	s_movk_i32 s3, 0x4000
	v_add_co_u32_e32 v8, vcc, s3, v60
	s_mov_b32 s3, 0x24000
	s_nop 0
	v_addc_co_u32_e32 v9, vcc, 0, v61, vcc
	global_load_dwordx4 v[4:7], v[60:61], off nt
	s_nop 0
	global_load_dwordx4 v[8:11], v[8:9], off nt
	v_add_co_u32_e32 v12, vcc, s22, v60
	s_lshl_b32 s2, s2, 1
	s_nop 0
	v_addc_co_u32_e32 v13, vcc, 0, v61, vcc
	v_add_co_u32_e32 v16, vcc, s3, v60
	s_mov_b32 s3, 0x40000
	s_nop 0
	v_addc_co_u32_e32 v17, vcc, 0, v61, vcc
	global_load_dwordx4 v[12:15], v[12:13], off nt
	s_nop 0
	global_load_dwordx4 v[16:19], v[16:17], off nt
	v_add_co_u32_e32 v20, vcc, s3, v60
	s_mov_b32 s3, 0x44000
	s_nop 0
	v_addc_co_u32_e32 v21, vcc, 0, v61, vcc
	v_add_co_u32_e32 v24, vcc, s3, v60
	s_mov_b32 s3, 0x60000
	s_nop 0
	v_addc_co_u32_e32 v25, vcc, 0, v61, vcc
	global_load_dwordx4 v[20:23], v[20:21], off nt
	s_nop 0
	global_load_dwordx4 v[24:27], v[24:25], off nt
	v_add_co_u32_e32 v28, vcc, s3, v60
	s_mov_b32 s3, 0x64000
	s_nop 0
	v_addc_co_u32_e32 v29, vcc, 0, v61, vcc
	v_add_co_u32_e32 v32, vcc, s3, v60
	s_mov_b32 s3, 0x80000
	s_nop 0
	v_addc_co_u32_e32 v33, vcc, 0, v61, vcc
	global_load_dwordx4 v[28:31], v[28:29], off nt
	s_nop 0
	global_load_dwordx4 v[32:35], v[32:33], off nt
	v_add_co_u32_e32 v36, vcc, s3, v60
	s_mov_b32 s3, 0x84000
	s_nop 0
	v_addc_co_u32_e32 v37, vcc, 0, v61, vcc
	v_add_co_u32_e32 v40, vcc, s3, v60
	s_mov_b32 s3, 0xa0000
	s_nop 0
	v_addc_co_u32_e32 v41, vcc, 0, v61, vcc
	global_load_dwordx4 v[36:39], v[36:37], off nt
	s_nop 0
	global_load_dwordx4 v[40:43], v[40:41], off nt
	v_add_co_u32_e32 v44, vcc, s3, v60
	s_mov_b32 s3, 0xa4000
	s_nop 0
	v_addc_co_u32_e32 v45, vcc, 0, v61, vcc
	v_add_co_u32_e32 v48, vcc, s3, v60
	s_mov_b32 s3, 0xc0000
	s_nop 0
	v_addc_co_u32_e32 v49, vcc, 0, v61, vcc
	global_load_dwordx4 v[44:47], v[44:45], off nt
	s_nop 0
	global_load_dwordx4 v[48:51], v[48:49], off nt
	v_add_co_u32_e32 v52, vcc, s3, v60
	s_mov_b32 s3, 0xc4000
	s_nop 0
	v_addc_co_u32_e32 v53, vcc, 0, v61, vcc
	v_add_co_u32_e32 v56, vcc, s3, v60
	s_mov_b32 s3, 0xe0000
	s_nop 0
	v_addc_co_u32_e32 v57, vcc, 0, v61, vcc
	global_load_dwordx4 v[52:55], v[52:53], off nt
	s_nop 0
	global_load_dwordx4 v[56:59], v[56:57], off nt
	v_add_co_u32_e32 v62, vcc, s3, v60
	s_mov_b32 s3, 0xe4000
	s_nop 0
	v_addc_co_u32_e32 v63, vcc, 0, v61, vcc
	v_add_co_u32_e32 v64, vcc, s3, v60
	s_add_u32 s2, s19, s2
	s_nop 0
	v_addc_co_u32_e32 v65, vcc, 0, v61, vcc
	global_load_dwordx4 v[60:63], v[62:63], off nt
	s_nop 0
	global_load_dwordx4 v[64:67], v[64:65], off nt
	s_waitcnt vmcnt(0)
; #define LAS __attribute__((address_space(3)))
; #define LDS_WAIT() asm volatile("s_waitcnt lgkmcnt(0)" ::: "memory")
; __device__ __forceinline__ unsigned cvt_pk_bf16(float lo, float hi) { unsigned r; asm volatile("v_cvt_pk_bf16_f32 %0, %1, %2" : "=v"(r) : "v"(lo), "v"(hi)); return r; }
;     ...
;         for (int e = 0; e < 4; ++e) *(LAS unsigned*)(scr + (4 * r16 + e) * 128 + ((i ^ (r16 & 7)) * 16) + q * 4) = cvt_pk_bf16(v[2 * i][e], v[2 * i + 1][e]);
;     LDS_WAIT(); asm volatile("" ::: "memory");
;     const int c = lane & 7;
; #pragma unroll
;     for (int j = 0; j < 8; ++j) { const int row = (lane >> 3) + 8 * j; const u32x4 o = *(const LAS u32x4*)(scr + row * 128 + ((c ^ ((row >> 2) & 7)) * 16));
;         const int lc = col_off + n0 + row; int dr;
;         if (MODE == 0) dr = lc;
;         else if (MODE == 1) dr = (lc & ~255) + 128 * ((lc >> 5) & 1) + 32 * ((lc >> 6) & 3) + (lc & 31);
;         else if (MODE == 2) dr = 256 * (lc >> 7) + (lc & 127);
;         else dr = 256 * (lc >> 7) + 128 + (lc & 127);
;         *(u32x4*)(WT + (size_t)dr * (ldt ? ldt : K) + k0 + 8 * c) = o; }
; __device__ __forceinline__ void weights_pass(const Args& a, LAS unsigned char* scr, int gw, int NGW, int lane, int pass) {
;     ...
;         if (r < I_OUT / 2) { transpose_item<0>(a.in[I_WOUT] + (size_t)l * DM * DM, 2048, DM, (bf16_t*)(wl + WL_OUT), nullptr, nullptr, 0, scr, r, lane, DM); continue; } r -= I_OUT / 2;
	v_cvt_pk_bf16_f32 v4, v4, v8
	v_add_u32_e32 v8, v69, v71
	ds_write_b32 v8, v4
	v_cvt_pk_bf16_f32 v4, v5, v9
	ds_write_b32 v8, v4 offset:128
	v_cvt_pk_bf16_f32 v4, v6, v10
	ds_write_b32 v8, v4 offset:256
	v_cvt_pk_bf16_f32 v4, v7, v11
	ds_write_b32 v8, v4 offset:384
	v_cvt_pk_bf16_f32 v4, v12, v16
	v_add_u32_e32 v5, v73, v71
	ds_write_b32 v5, v4
	v_cvt_pk_bf16_f32 v4, v13, v17
	ds_write_b32 v5, v4 offset:128
	v_cvt_pk_bf16_f32 v4, v14, v18
	ds_write_b32 v5, v4 offset:256
	v_cvt_pk_bf16_f32 v4, v15, v19
	ds_write_b32 v5, v4 offset:384
	v_cvt_pk_bf16_f32 v4, v20, v24
	v_add_u32_e32 v5, v74, v71
	ds_write_b32 v5, v4
	v_cvt_pk_bf16_f32 v4, v21, v25
	ds_write_b32 v5, v4 offset:128
	v_cvt_pk_bf16_f32 v4, v22, v26
	ds_write_b32 v5, v4 offset:256
	v_cvt_pk_bf16_f32 v4, v23, v27
	ds_write_b32 v5, v4 offset:384
	v_cvt_pk_bf16_f32 v4, v28, v32
	v_add_u32_e32 v5, v75, v71
	ds_write_b32 v5, v4
	v_cvt_pk_bf16_f32 v4, v29, v33
	ds_write_b32 v5, v4 offset:128
	v_cvt_pk_bf16_f32 v4, v30, v34
	ds_write_b32 v5, v4 offset:256
	v_cvt_pk_bf16_f32 v4, v31, v35
	ds_write_b32 v5, v4 offset:384
	v_cvt_pk_bf16_f32 v4, v36, v40
	v_add_u32_e32 v5, v76, v71
	ds_write_b32 v5, v4
	v_cvt_pk_bf16_f32 v4, v37, v41
	ds_write_b32 v5, v4 offset:128
	v_cvt_pk_bf16_f32 v4, v38, v42
	ds_write_b32 v5, v4 offset:256
	v_cvt_pk_bf16_f32 v4, v39, v43
	ds_write_b32 v5, v4 offset:384
	v_cvt_pk_bf16_f32 v4, v44, v48
	v_add_u32_e32 v5, v77, v71
	ds_write_b32 v5, v4
	v_cvt_pk_bf16_f32 v4, v45, v49
	ds_write_b32 v5, v4 offset:128
	v_cvt_pk_bf16_f32 v4, v46, v50
	ds_write_b32 v5, v4 offset:256
	v_cvt_pk_bf16_f32 v4, v47, v51
	ds_write_b32 v5, v4 offset:384
	v_cvt_pk_bf16_f32 v4, v52, v56
	v_add_u32_e32 v5, v78, v71
	ds_write_b32 v5, v4
	v_cvt_pk_bf16_f32 v4, v53, v57
	ds_write_b32 v5, v4 offset:128
	v_cvt_pk_bf16_f32 v4, v54, v58
	ds_write_b32 v5, v4 offset:256
	v_cvt_pk_bf16_f32 v4, v55, v59
	ds_write_b32 v5, v4 offset:384
	v_cvt_pk_bf16_f32 v4, v60, v64
	v_add_u32_e32 v5, v79, v71
	ds_write_b32 v5, v4
	v_cvt_pk_bf16_f32 v4, v61, v65
	ds_write_b32 v5, v4 offset:128
	v_cvt_pk_bf16_f32 v4, v62, v66
	ds_write_b32 v5, v4 offset:256
	v_cvt_pk_bf16_f32 v4, v63, v67
	ds_write_b32 v5, v4 offset:384
	s_addc_u32 s3, s20, 0
	v_lshlrev_b32_e32 v4, 1, v70
	v_mov_b32_e32 v5, v2
	s_waitcnt lgkmcnt(0)
	v_lshl_add_u64 v[4:5], s[2:3], 0, v[4:5]
	s_mov_b64 s[2:3], 0x2600000
	v_lshl_add_u64 v[12:13], v[4:5], 0, s[2:3]
	v_add_u32_e32 v4, v81, v82
	ds_read_b128 v[4:7], v4
	v_or_b32_e32 v8, s1, v80
	v_lshlrev_b32_e32 v8, 13, v8
	v_mov_b32_e32 v9, v2
	v_lshl_add_u64 v[14:15], v[12:13], 0, v[8:9]
	v_add_u32_e32 v8, v84, v85
	ds_read_b128 v[8:11], v8
	s_waitcnt lgkmcnt(1)
	global_store_dwordx4 v[14:15], v[4:7], off nt
	s_nop 1
	v_or_b32_e32 v4, s1, v83
	v_lshlrev_b32_e32 v4, 13, v4
	v_mov_b32_e32 v5, v2
	v_lshl_add_u64 v[4:5], v[12:13], 0, v[4:5]
	s_waitcnt lgkmcnt(0)
	global_store_dwordx4 v[4:5], v[8:11], off nt
	v_add_u32_e32 v4, v87, v88
	ds_read_b128 v[4:7], v4
	v_or_b32_e32 v8, s1, v86
	v_lshlrev_b32_e32 v8, 13, v8
	v_mov_b32_e32 v9, v2
	v_lshl_add_u64 v[14:15], v[12:13], 0, v[8:9]
	v_add_u32_e32 v8, v90, v91
	ds_read_b128 v[8:11], v8
	s_waitcnt lgkmcnt(1)
	global_store_dwordx4 v[14:15], v[4:7], off nt
	s_nop 1
	v_or_b32_e32 v4, s1, v89
	v_lshlrev_b32_e32 v4, 13, v4
	v_mov_b32_e32 v5, v2
	v_lshl_add_u64 v[4:5], v[12:13], 0, v[4:5]
	s_waitcnt lgkmcnt(0)
	global_store_dwordx4 v[4:5], v[8:11], off nt
	v_add_u32_e32 v4, v93, v82
	ds_read_b128 v[4:7], v4
	v_or_b32_e32 v8, s1, v92
	v_lshlrev_b32_e32 v8, 13, v8
	v_mov_b32_e32 v9, v2
	v_lshl_add_u64 v[14:15], v[12:13], 0, v[8:9]
	v_add_u32_e32 v8, v95, v96
	ds_read_b128 v[8:11], v8
	s_waitcnt lgkmcnt(1)
	global_store_dwordx4 v[14:15], v[4:7], off nt
	s_nop 1
	v_or_b32_e32 v4, s1, v94
	v_lshlrev_b32_e32 v4, 13, v4
	v_mov_b32_e32 v5, v2
	v_lshl_add_u64 v[4:5], v[12:13], 0, v[4:5]
	s_waitcnt lgkmcnt(0)
	global_store_dwordx4 v[4:5], v[8:11], off nt
	v_add_u32_e32 v4, v98, v99
	ds_read_b128 v[4:7], v4
	v_or_b32_e32 v8, s1, v97
	v_lshlrev_b32_e32 v8, 13, v8
	v_mov_b32_e32 v9, v2
	v_lshl_add_u64 v[14:15], v[12:13], 0, v[8:9]
	v_add_u32_e32 v8, v101, v102
	ds_read_b128 v[8:11], v8
	s_waitcnt lgkmcnt(1)
	global_store_dwordx4 v[14:15], v[4:7], off nt
	s_nop 1
	v_or_b32_e32 v4, s1, v100
	v_lshlrev_b32_e32 v4, 13, v4
	v_mov_b32_e32 v5, v2
	v_lshl_add_u64 v[4:5], v[12:13], 0, v[4:5]
	s_waitcnt lgkmcnt(0)
	global_store_dwordx4 v[4:5], v[8:11], off nt
	s_waitcnt lgkmcnt(0)
